# attention QKT reads software-pipelined + finishSM interleaved; GEMM MFMAs reordered so the two k-steps of each accumulator issue back to back
# speedup vs baseline: 1.0049x; 1.0049x over previous
.LBB0_127:
	ds_read_b128 v[176:179], v167
	ds_read_b128 v[180:183], v167 offset:1024
	ds_read_b128 v[186:189], v167 offset:2048
	ds_read_b128 v[190:193], v167 offset:3072
	s_add_u32 s40, s38, 0xfff00080
	s_addc_u32 s41, s39, -1
	s_cmp_eq_u32 s54, 60
	s_cselect_b32 s43, s6, s41
	s_cselect_b32 s42, s7, s40
	s_cselect_b32 s41, s9, s29
	s_cselect_b32 s40, s11, s27
	v_lshl_add_u64 v[156:157], s[38:39], 0, v[138:139]
	s_add_i32 m0, s44, 0xc000
	ds_read_b128 v[194:197], v168
	ds_read_b128 v[198:201], v168 offset:1024
	ds_read_b128 v[202:205], v168 offset:2048
	ds_read_b128 v[206:209], v168 offset:3072
	ds_read_b128 v[210:213], v168 offset:4096
	ds_read_b128 v[214:217], v168 offset:5120
	ds_read_b128 v[218:221], v168 offset:6144
	ds_read_b128 v[222:225], v168 offset:7168
	global_load_lds_dwordx4 v[156:157], off
	v_lshl_add_u64 v[156:157], s[38:39], 0, v[140:141]
	s_add_i32 m0, s44, 0xe000
	s_nop 0
	global_load_lds_dwordx4 v[156:157], off
	s_waitcnt lgkmcnt(8)
	s_barrier
	s_waitcnt lgkmcnt(0)
	s_setprio 1
	s_waitcnt lgkmcnt(0)
	v_mfma_f32_16x16x32_bf16 v[124:127], v[176:179], v[194:197], v[124:127]
	v_mfma_f32_16x16x32_bf16 v[124:127], v[180:183], v[198:201], v[124:127]
	v_mfma_f32_16x16x32_bf16 v[120:123], v[186:189], v[194:197], v[120:123]
	v_mfma_f32_16x16x32_bf16 v[120:123], v[190:193], v[198:201], v[120:123]
	v_mfma_f32_16x16x32_bf16 v[108:111], v[176:179], v[202:205], v[108:111]
	v_mfma_f32_16x16x32_bf16 v[108:111], v[180:183], v[206:209], v[108:111]
	v_mfma_f32_16x16x32_bf16 v[104:107], v[186:189], v[202:205], v[104:107]
	v_mfma_f32_16x16x32_bf16 v[104:107], v[190:193], v[206:209], v[104:107]
	v_mfma_f32_16x16x32_bf16 v[92:95], v[176:179], v[210:213], v[92:95]
	v_mfma_f32_16x16x32_bf16 v[92:95], v[180:183], v[214:217], v[92:95]
	v_mfma_f32_16x16x32_bf16 v[88:91], v[186:189], v[210:213], v[88:91]
	v_mfma_f32_16x16x32_bf16 v[88:91], v[190:193], v[214:217], v[88:91]
	v_mfma_f32_16x16x32_bf16 v[76:79], v[176:179], v[218:221], v[76:79]
	v_mfma_f32_16x16x32_bf16 v[76:79], v[180:183], v[222:225], v[76:79]
	v_mfma_f32_16x16x32_bf16 v[72:75], v[186:189], v[218:221], v[72:75]
	v_mfma_f32_16x16x32_bf16 v[72:75], v[190:193], v[222:225], v[72:75]
	s_setprio 0
	s_barrier
	s_add_i32 s55, s72, s5
	v_lshl_add_u64 v[156:157], s[40:41], 0, v[130:131]
	s_mov_b32 m0, s55
	ds_read_b128 v[226:229], v169
	ds_read_b128 v[230:233], v169 offset:1024
	ds_read_b128 v[234:237], v169 offset:2048
	ds_read_b128 v[238:241], v169 offset:3072
	global_load_lds_dwordx4 v[156:157], off
	v_lshl_add_u64 v[162:163], s[40:41], 0, v[134:135]
	s_add_i32 m0, s55, 0x2000
	s_nop 0
	global_load_lds_dwordx4 v[162:163], off
	s_barrier
	s_waitcnt lgkmcnt(0)
	s_setprio 1
	s_waitcnt lgkmcnt(0)
	v_mfma_f32_16x16x32_bf16 v[116:119], v[226:229], v[194:197], v[116:119]
	v_mfma_f32_16x16x32_bf16 v[116:119], v[230:233], v[198:201], v[116:119]
	v_mfma_f32_16x16x32_bf16 v[112:115], v[234:237], v[194:197], v[112:115]
	v_mfma_f32_16x16x32_bf16 v[112:115], v[238:241], v[198:201], v[112:115]
	v_mfma_f32_16x16x32_bf16 v[100:103], v[226:229], v[202:205], v[100:103]
	v_mfma_f32_16x16x32_bf16 v[100:103], v[230:233], v[206:209], v[100:103]
	v_mfma_f32_16x16x32_bf16 v[96:99], v[234:237], v[202:205], v[96:99]
	v_mfma_f32_16x16x32_bf16 v[96:99], v[238:241], v[206:209], v[96:99]
	v_mfma_f32_16x16x32_bf16 v[84:87], v[226:229], v[210:213], v[84:87]
	v_mfma_f32_16x16x32_bf16 v[84:87], v[230:233], v[214:217], v[84:87]
	v_mfma_f32_16x16x32_bf16 v[80:83], v[234:237], v[210:213], v[80:83]
	v_mfma_f32_16x16x32_bf16 v[80:83], v[238:241], v[214:217], v[80:83]
	v_mfma_f32_16x16x32_bf16 v[68:71], v[226:229], v[218:221], v[68:71]
	v_mfma_f32_16x16x32_bf16 v[68:71], v[230:233], v[222:225], v[68:71]
	v_mfma_f32_16x16x32_bf16 v[64:67], v[234:237], v[218:221], v[64:67]
	v_mfma_f32_16x16x32_bf16 v[64:67], v[238:241], v[222:225], v[64:67]
	s_setprio 0
	s_mov_b32 m0, s44
	v_lshl_add_u64 v[170:171], s[42:43], 0, v[128:129]
	s_barrier
	ds_read_b128 v[194:197], v168 offset:16384
	ds_read_b128 v[198:201], v168 offset:17408
	ds_read_b128 v[202:205], v168 offset:18432
	ds_read_b128 v[206:209], v168 offset:19456
	ds_read_b128 v[210:213], v168 offset:20480
	ds_read_b128 v[214:217], v168 offset:21504
	ds_read_b128 v[218:221], v168 offset:22528
	ds_read_b128 v[222:225], v168 offset:23552
	global_load_lds_dwordx4 v[170:171], off
	v_lshl_add_u64 v[242:243], s[42:43], 0, v[132:133]
	s_mov_b32 m0, s45
	s_nop 0
	global_load_lds_dwordx4 v[242:243], off
	s_barrier
	s_waitcnt lgkmcnt(0)
	s_setprio 1
	s_waitcnt lgkmcnt(0)
	v_mfma_f32_16x16x32_bf16 v[60:63], v[176:179], v[194:197], v[60:63]
	v_mfma_f32_16x16x32_bf16 v[60:63], v[180:183], v[198:201], v[60:63]
	v_mfma_f32_16x16x32_bf16 v[56:59], v[186:189], v[194:197], v[56:59]
	v_mfma_f32_16x16x32_bf16 v[56:59], v[190:193], v[198:201], v[56:59]
	v_mfma_f32_16x16x32_bf16 v[44:47], v[176:179], v[202:205], v[44:47]
	v_mfma_f32_16x16x32_bf16 v[44:47], v[180:183], v[206:209], v[44:47]
	v_mfma_f32_16x16x32_bf16 v[40:43], v[186:189], v[202:205], v[40:43]
	v_mfma_f32_16x16x32_bf16 v[40:43], v[190:193], v[206:209], v[40:43]
	v_mfma_f32_16x16x32_bf16 v[28:31], v[176:179], v[210:213], v[28:31]
	v_mfma_f32_16x16x32_bf16 v[28:31], v[180:183], v[214:217], v[28:31]
	v_mfma_f32_16x16x32_bf16 v[24:27], v[186:189], v[210:213], v[24:27]
	v_mfma_f32_16x16x32_bf16 v[24:27], v[190:193], v[214:217], v[24:27]
	v_mfma_f32_16x16x32_bf16 v[12:15], v[176:179], v[218:221], v[12:15]
	v_mfma_f32_16x16x32_bf16 v[12:15], v[180:183], v[222:225], v[12:15]
	v_mfma_f32_16x16x32_bf16 v[8:11], v[186:189], v[218:221], v[8:11]
	v_mfma_f32_16x16x32_bf16 v[8:11], v[190:193], v[222:225], v[8:11]
	s_setprio 0
	s_barrier
	s_add_u32 s62, s40, 0x100000
	s_addc_u32 s63, s41, 0
	s_add_i32 s55, s73, s5
	v_lshl_add_u64 v[176:177], s[62:63], 0, v[130:131]
	s_mov_b32 m0, s55
	s_nop 0
	global_load_lds_dwordx4 v[176:177], off
	v_lshl_add_u64 v[176:177], s[62:63], 0, v[134:135]
	s_add_i32 m0, s55, 0x2000
	s_nop 0
	global_load_lds_dwordx4 v[176:177], off
	s_waitcnt vmcnt(6)
	s_barrier
	s_setprio 1
	v_mfma_f32_16x16x32_bf16 v[52:55], v[226:229], v[194:197], v[52:55]
	v_mfma_f32_16x16x32_bf16 v[52:55], v[230:233], v[198:201], v[52:55]
	v_mfma_f32_16x16x32_bf16 v[48:51], v[234:237], v[194:197], v[48:51]
	v_mfma_f32_16x16x32_bf16 v[48:51], v[238:241], v[198:201], v[48:51]
	v_mfma_f32_16x16x32_bf16 v[36:39], v[226:229], v[202:205], v[36:39]
	v_mfma_f32_16x16x32_bf16 v[36:39], v[230:233], v[206:209], v[36:39]
	v_mfma_f32_16x16x32_bf16 v[32:35], v[234:237], v[202:205], v[32:35]
	v_mfma_f32_16x16x32_bf16 v[32:35], v[238:241], v[206:209], v[32:35]
	v_mfma_f32_16x16x32_bf16 v[20:23], v[226:229], v[210:213], v[20:23]
	v_mfma_f32_16x16x32_bf16 v[20:23], v[230:233], v[214:217], v[20:23]
	v_mfma_f32_16x16x32_bf16 v[16:19], v[234:237], v[210:213], v[16:19]
	v_mfma_f32_16x16x32_bf16 v[16:19], v[238:241], v[214:217], v[16:19]
	v_mfma_f32_16x16x32_bf16 v[4:7], v[226:229], v[218:221], v[4:7]
	v_mfma_f32_16x16x32_bf16 v[4:7], v[230:233], v[222:225], v[4:7]
	v_mfma_f32_16x16x32_bf16 v[0:3], v[234:237], v[218:221], v[0:3]
	v_mfma_f32_16x16x32_bf16 v[0:3], v[238:241], v[222:225], v[0:3]
	s_setprio 0
	s_add_i32 s55, 0, 0x18000
	v_add_u32_e32 v137, s55, v165
	s_barrier
	ds_read_b128 v[176:179], v137
	ds_read_b128 v[180:183], v137 offset:1024
	ds_read_b128 v[186:189], v137 offset:2048
	ds_read_b128 v[190:193], v137 offset:3072
	s_add_u32 s42, s42, 0x100000
	s_addc_u32 s43, s43, 0
	s_mov_b32 m0, s46
	v_lshl_add_u64 v[226:227], s[42:43], 0, v[128:129]
	ds_read_b128 v[194:197], v168 offset:32768
	ds_read_b128 v[198:201], v168 offset:33792
	ds_read_b128 v[202:205], v168 offset:34816
	ds_read_b128 v[206:209], v168 offset:35840
	ds_read_b128 v[210:213], v168 offset:36864
	ds_read_b128 v[214:217], v168 offset:37888
	ds_read_b128 v[218:221], v168 offset:38912
	ds_read_b128 v[222:225], v168 offset:39936
	global_load_lds_dwordx4 v[226:227], off
	v_lshl_add_u64 v[226:227], s[42:43], 0, v[132:133]
	s_mov_b32 m0, s47
	s_nop 0
	global_load_lds_dwordx4 v[226:227], off
	s_waitcnt lgkmcnt(8)
	s_barrier
	s_waitcnt lgkmcnt(0)
	s_setprio 1
	s_waitcnt lgkmcnt(0)
	v_mfma_f32_16x16x32_bf16 v[124:127], v[176:179], v[194:197], v[124:127]
	v_mfma_f32_16x16x32_bf16 v[124:127], v[180:183], v[198:201], v[124:127]
	v_mfma_f32_16x16x32_bf16 v[120:123], v[186:189], v[194:197], v[120:123]
	v_mfma_f32_16x16x32_bf16 v[120:123], v[190:193], v[198:201], v[120:123]
	v_mfma_f32_16x16x32_bf16 v[108:111], v[176:179], v[202:205], v[108:111]
	v_mfma_f32_16x16x32_bf16 v[108:111], v[180:183], v[206:209], v[108:111]
	v_mfma_f32_16x16x32_bf16 v[104:107], v[186:189], v[202:205], v[104:107]
	v_mfma_f32_16x16x32_bf16 v[104:107], v[190:193], v[206:209], v[104:107]
	v_mfma_f32_16x16x32_bf16 v[92:95], v[176:179], v[210:213], v[92:95]
	v_mfma_f32_16x16x32_bf16 v[92:95], v[180:183], v[214:217], v[92:95]
	v_mfma_f32_16x16x32_bf16 v[88:91], v[186:189], v[210:213], v[88:91]
	v_mfma_f32_16x16x32_bf16 v[88:91], v[190:193], v[214:217], v[88:91]
	v_mfma_f32_16x16x32_bf16 v[76:79], v[176:179], v[218:221], v[76:79]
	v_mfma_f32_16x16x32_bf16 v[76:79], v[180:183], v[222:225], v[76:79]
	v_mfma_f32_16x16x32_bf16 v[72:75], v[186:189], v[218:221], v[72:75]
	v_mfma_f32_16x16x32_bf16 v[72:75], v[190:193], v[222:225], v[72:75]
	s_setprio 0
	s_barrier
	s_add_i32 s42, 0, 0x1c000
	s_add_i32 s43, s55, s5
	v_add_u32_e32 v137, s42, v165
	v_lshl_add_u64 v[156:157], v[156:157], 0, s[24:25]
	s_mov_b32 m0, s43
	ds_read_b128 v[226:229], v137
	ds_read_b128 v[230:233], v137 offset:1024
	ds_read_b128 v[234:237], v137 offset:2048
	ds_read_b128 v[238:241], v137 offset:3072
	global_load_lds_dwordx4 v[156:157], off
	v_lshl_add_u64 v[156:157], v[162:163], 0, s[24:25]
	s_add_i32 m0, s43, 0x2000
	s_nop 0
	global_load_lds_dwordx4 v[156:157], off
	s_barrier
	s_waitcnt lgkmcnt(0)
	s_setprio 1
	s_waitcnt lgkmcnt(0)
	v_mfma_f32_16x16x32_bf16 v[116:119], v[226:229], v[194:197], v[116:119]
	v_mfma_f32_16x16x32_bf16 v[116:119], v[230:233], v[198:201], v[116:119]
	v_mfma_f32_16x16x32_bf16 v[112:115], v[234:237], v[194:197], v[112:115]
	v_mfma_f32_16x16x32_bf16 v[112:115], v[238:241], v[198:201], v[112:115]
	v_mfma_f32_16x16x32_bf16 v[100:103], v[226:229], v[202:205], v[100:103]
	v_mfma_f32_16x16x32_bf16 v[100:103], v[230:233], v[206:209], v[100:103]
	v_mfma_f32_16x16x32_bf16 v[96:99], v[234:237], v[202:205], v[96:99]
	v_mfma_f32_16x16x32_bf16 v[96:99], v[238:241], v[206:209], v[96:99]
	v_mfma_f32_16x16x32_bf16 v[84:87], v[226:229], v[210:213], v[84:87]
	v_mfma_f32_16x16x32_bf16 v[84:87], v[230:233], v[214:217], v[84:87]
	v_mfma_f32_16x16x32_bf16 v[80:83], v[234:237], v[210:213], v[80:83]
	v_mfma_f32_16x16x32_bf16 v[80:83], v[238:241], v[214:217], v[80:83]
	v_mfma_f32_16x16x32_bf16 v[68:71], v[226:229], v[218:221], v[68:71]
	v_mfma_f32_16x16x32_bf16 v[68:71], v[230:233], v[222:225], v[68:71]
	v_mfma_f32_16x16x32_bf16 v[64:67], v[234:237], v[218:221], v[64:67]
	v_mfma_f32_16x16x32_bf16 v[64:67], v[238:241], v[222:225], v[64:67]
	s_setprio 0
	s_mov_b32 m0, s49
	v_lshl_add_u64 v[156:157], v[170:171], 0, s[24:25]
	s_barrier
	ds_read_b128 v[194:197], v168 offset:49152
	ds_read_b128 v[198:201], v168 offset:50176
	ds_read_b128 v[202:205], v168 offset:51200
	ds_read_b128 v[206:209], v168 offset:52224
	ds_read_b128 v[210:213], v168 offset:53248
	ds_read_b128 v[214:217], v168 offset:54272
	ds_read_b128 v[218:221], v168 offset:55296
	ds_read_b128 v[222:225], v168 offset:56320
	global_load_lds_dwordx4 v[156:157], off
	v_lshl_add_u64 v[156:157], v[242:243], 0, s[24:25]
	s_mov_b32 m0, s50
	s_nop 0
	global_load_lds_dwordx4 v[156:157], off
	s_barrier
	s_waitcnt lgkmcnt(0)
	s_setprio 1
	s_waitcnt lgkmcnt(0)
	v_mfma_f32_16x16x32_bf16 v[60:63], v[176:179], v[194:197], v[60:63]
	v_mfma_f32_16x16x32_bf16 v[60:63], v[180:183], v[198:201], v[60:63]
	v_mfma_f32_16x16x32_bf16 v[56:59], v[186:189], v[194:197], v[56:59]
	v_mfma_f32_16x16x32_bf16 v[56:59], v[190:193], v[198:201], v[56:59]
	v_mfma_f32_16x16x32_bf16 v[44:47], v[176:179], v[202:205], v[44:47]
	v_mfma_f32_16x16x32_bf16 v[44:47], v[180:183], v[206:209], v[44:47]
	v_mfma_f32_16x16x32_bf16 v[40:43], v[186:189], v[202:205], v[40:43]
	v_mfma_f32_16x16x32_bf16 v[40:43], v[190:193], v[206:209], v[40:43]
	v_mfma_f32_16x16x32_bf16 v[28:31], v[176:179], v[210:213], v[28:31]
	v_mfma_f32_16x16x32_bf16 v[28:31], v[180:183], v[214:217], v[28:31]
	v_mfma_f32_16x16x32_bf16 v[24:27], v[186:189], v[210:213], v[24:27]
	v_mfma_f32_16x16x32_bf16 v[24:27], v[190:193], v[214:217], v[24:27]
	v_mfma_f32_16x16x32_bf16 v[12:15], v[176:179], v[218:221], v[12:15]
	v_mfma_f32_16x16x32_bf16 v[12:15], v[180:183], v[222:225], v[12:15]
	v_mfma_f32_16x16x32_bf16 v[8:11], v[186:189], v[218:221], v[8:11]
	v_mfma_f32_16x16x32_bf16 v[8:11], v[190:193], v[222:225], v[8:11]
	s_setprio 0
	s_barrier
	s_add_u32 s40, s40, 0x100080
	s_addc_u32 s41, s41, 0
	s_add_i32 s42, s42, s5
	v_lshl_add_u64 v[156:157], s[40:41], 0, v[130:131]
	s_mov_b32 m0, s42
	s_nop 0
	global_load_lds_dwordx4 v[156:157], off
	v_lshl_add_u64 v[156:157], s[40:41], 0, v[134:135]
	s_add_i32 m0, s42, 0x2000
	s_nop 0
	global_load_lds_dwordx4 v[156:157], off
	s_waitcnt vmcnt(6)
	s_barrier
	s_setprio 1
	v_mfma_f32_16x16x32_bf16 v[52:55], v[226:229], v[194:197], v[52:55]
	v_mfma_f32_16x16x32_bf16 v[52:55], v[230:233], v[198:201], v[52:55]
	v_mfma_f32_16x16x32_bf16 v[48:51], v[234:237], v[194:197], v[48:51]
	v_mfma_f32_16x16x32_bf16 v[48:51], v[238:241], v[198:201], v[48:51]
	v_mfma_f32_16x16x32_bf16 v[36:39], v[226:229], v[202:205], v[36:39]
	v_mfma_f32_16x16x32_bf16 v[36:39], v[230:233], v[206:209], v[36:39]
	v_mfma_f32_16x16x32_bf16 v[32:35], v[234:237], v[202:205], v[32:35]
	v_mfma_f32_16x16x32_bf16 v[32:35], v[238:241], v[206:209], v[32:35]
	v_mfma_f32_16x16x32_bf16 v[20:23], v[226:229], v[210:213], v[20:23]
	v_mfma_f32_16x16x32_bf16 v[20:23], v[230:233], v[214:217], v[20:23]
	v_mfma_f32_16x16x32_bf16 v[16:19], v[234:237], v[210:213], v[16:19]
	v_mfma_f32_16x16x32_bf16 v[16:19], v[238:241], v[214:217], v[16:19]
	v_mfma_f32_16x16x32_bf16 v[4:7], v[226:229], v[218:221], v[4:7]
	v_mfma_f32_16x16x32_bf16 v[4:7], v[230:233], v[222:225], v[4:7]
	v_mfma_f32_16x16x32_bf16 v[0:3], v[234:237], v[218:221], v[0:3]
	v_mfma_f32_16x16x32_bf16 v[0:3], v[238:241], v[222:225], v[0:3]
	s_setprio 0
	s_add_i32 s54, s54, 2
	s_add_u32 s38, s38, 0x100
	s_addc_u32 s39, s39, 0
	s_add_u32 s27, s27, 0x100
	s_addc_u32 s29, s29, 0
	s_cmp_gt_u32 s54, 61
	s_barrier
	s_cbranch_scc0 .LBB0_127
	v_lshl_or_b32 v156, s8, 8, v166
	s_waitcnt vmcnt(0)
	v_pk_mul_f32 v[126:127], v[160:161], v[126:127] op_sel_hi:[0,1]
	v_pk_mul_f32 v[124:125], v[160:161], v[124:125] op_sel_hi:[0,1]
	v_pk_mul_f32 v[122:123], v[160:161], v[122:123] op_sel_hi:[0,1]
	v_pk_mul_f32 v[162:163], v[160:161], v[120:121] op_sel_hi:[0,1]
	v_cmp_lt_i32_e64 s[8:9], s74, v156
	s_and_saveexec_b64 s[38:39], s[8:9]
	s_cbranch_execz .LBB0_130
	v_mul_f32_e32 v147, 0xbfb8aa3b, v126
	v_mul_f32_e32 v121, 0xbfb8aa3b, v162
	v_exp_f32_e32 v147, v147
	v_mul_f32_e32 v149, 0xbfb8aa3b, v122
	v_mul_f32_e32 v137, 0xbfb8aa3b, v125
	v_exp_f32_e32 v121, v121
	v_exp_f32_e32 v149, v149
	v_exp_f32_e32 v137, v137
	v_add_f32_e32 v147, 1.0, v147
	v_add_f32_e32 v121, 1.0, v121
	v_rcp_f32_e32 v176, v147
	v_add_f32_e32 v147, 1.0, v149
	v_mul_f32_e32 v149, 0xbfb8aa3b, v127
	v_mul_f32_e32 v120, 0xbfb8aa3b, v124
	v_rcp_f32_e32 v170, v121
	v_add_f32_e32 v121, 1.0, v137
	v_mul_f32_e32 v137, 0xbfb8aa3b, v163
	v_exp_f32_e32 v149, v149
	v_mul_f32_e32 v151, 0xbfb8aa3b, v123
	v_exp_f32_e32 v120, v120
	v_exp_f32_e32 v137, v137
	v_exp_f32_e32 v151, v151
	v_rcp_f32_e32 v178, v147
	v_add_f32_e32 v147, 1.0, v149
	v_add_f32_e32 v120, 1.0, v120
	v_add_f32_e32 v137, 1.0, v137
	v_rcp_f32_e32 v177, v147
	v_add_f32_e32 v147, 1.0, v151
	v_rcp_f32_e32 v120, v120
	v_rcp_f32_e32 v121, v121
	v_rcp_f32_e32 v179, v147
	v_rcp_f32_e32 v171, v137
	v_pk_mul_f32 v[126:127], v[126:127], v[176:177]
	v_pk_mul_f32 v[124:125], v[124:125], v[120:121]
	v_pk_mul_f32 v[122:123], v[122:123], v[178:179]
	v_pk_mul_f32 v[162:163], v[162:163], v[170:171]

.LBB0_301:
	ds_read_b128 v[160:163], v151
	ds_read_b128 v[164:167], v151 offset:1024
	ds_read_b128 v[168:171], v151 offset:2048
	ds_read_b128 v[176:179], v151 offset:3072
	s_add_u32 s44, s42, 0x100
	s_addc_u32 s45, s43, 0
	s_cmp_eq_u32 s83, 12
	s_cselect_b32 s49, s39, s45
	s_cselect_b32 s48, s38, s44
	s_cselect_b32 s47, s37, s82
	s_cselect_b32 s46, s62, s63
	v_lshl_add_u64 v[214:215], s[42:43], 0, v[142:143]
	s_add_i32 m0, s50, 0xc000
	ds_read_b128 v[180:183], v153
	ds_read_b128 v[186:189], v153 offset:1024
	ds_read_b128 v[190:193], v153 offset:2048
	ds_read_b128 v[194:197], v153 offset:3072
	ds_read_b128 v[198:201], v153 offset:4096
	ds_read_b128 v[202:205], v153 offset:5120
	ds_read_b128 v[206:209], v153 offset:6144
	ds_read_b128 v[210:213], v153 offset:7168
	global_load_lds_dwordx4 v[214:215], off
	v_lshl_add_u64 v[214:215], s[42:43], 0, v[144:145]
	s_add_i32 m0, s50, 0xe000
	s_nop 0
	global_load_lds_dwordx4 v[214:215], off
	s_waitcnt lgkmcnt(8)
	s_barrier
	s_waitcnt lgkmcnt(0)
	s_setprio 1
	s_waitcnt lgkmcnt(0)
	v_mfma_f32_16x16x32_bf16 v[124:127], v[160:163], v[180:183], v[124:127]
	v_mfma_f32_16x16x32_bf16 v[124:127], v[164:167], v[186:189], v[124:127]
	v_mfma_f32_16x16x32_bf16 v[120:123], v[168:171], v[180:183], v[120:123]
	v_mfma_f32_16x16x32_bf16 v[120:123], v[176:179], v[186:189], v[120:123]
	v_mfma_f32_16x16x32_bf16 v[112:115], v[160:163], v[190:193], v[112:115]
	v_mfma_f32_16x16x32_bf16 v[112:115], v[164:167], v[194:197], v[112:115]
	v_mfma_f32_16x16x32_bf16 v[104:107], v[168:171], v[190:193], v[104:107]
	v_mfma_f32_16x16x32_bf16 v[104:107], v[176:179], v[194:197], v[104:107]
	v_mfma_f32_16x16x32_bf16 v[96:99], v[160:163], v[198:201], v[96:99]
	v_mfma_f32_16x16x32_bf16 v[96:99], v[164:167], v[202:205], v[96:99]
	v_mfma_f32_16x16x32_bf16 v[88:91], v[168:171], v[198:201], v[88:91]
	v_mfma_f32_16x16x32_bf16 v[88:91], v[176:179], v[202:205], v[88:91]
	v_mfma_f32_16x16x32_bf16 v[80:83], v[160:163], v[206:209], v[80:83]
	v_mfma_f32_16x16x32_bf16 v[80:83], v[164:167], v[210:213], v[80:83]
	v_mfma_f32_16x16x32_bf16 v[72:75], v[168:171], v[206:209], v[72:75]
	v_mfma_f32_16x16x32_bf16 v[72:75], v[176:179], v[210:213], v[72:75]
	s_setprio 0
	s_barrier
	s_add_i32 s42, s76, s5
	v_lshl_add_u64 v[230:231], s[46:47], 0, v[132:133]
	s_mov_b32 m0, s42
	ds_read_b128 v[214:217], v155
	ds_read_b128 v[218:221], v155 offset:1024
	ds_read_b128 v[222:225], v155 offset:2048
	ds_read_b128 v[226:229], v155 offset:3072
	global_load_lds_dwordx4 v[230:231], off
	v_lshl_add_u64 v[232:233], s[46:47], 0, v[128:129]
	s_add_i32 m0, s42, 0x2000
	s_nop 0
	global_load_lds_dwordx4 v[232:233], off
	s_barrier
	s_waitcnt lgkmcnt(0)
	s_setprio 1
	s_waitcnt lgkmcnt(0)
	v_mfma_f32_16x16x32_bf16 v[116:119], v[214:217], v[180:183], v[116:119]
	v_mfma_f32_16x16x32_bf16 v[116:119], v[218:221], v[186:189], v[116:119]
	v_mfma_f32_16x16x32_bf16 v[108:111], v[222:225], v[180:183], v[108:111]
	v_mfma_f32_16x16x32_bf16 v[108:111], v[226:229], v[186:189], v[108:111]
	v_mfma_f32_16x16x32_bf16 v[100:103], v[214:217], v[190:193], v[100:103]
	v_mfma_f32_16x16x32_bf16 v[100:103], v[218:221], v[194:197], v[100:103]
	v_mfma_f32_16x16x32_bf16 v[92:95], v[222:225], v[190:193], v[92:95]
	v_mfma_f32_16x16x32_bf16 v[92:95], v[226:229], v[194:197], v[92:95]
	v_mfma_f32_16x16x32_bf16 v[84:87], v[214:217], v[198:201], v[84:87]
	v_mfma_f32_16x16x32_bf16 v[84:87], v[218:221], v[202:205], v[84:87]
	v_mfma_f32_16x16x32_bf16 v[76:79], v[222:225], v[198:201], v[76:79]
	v_mfma_f32_16x16x32_bf16 v[76:79], v[226:229], v[202:205], v[76:79]
	v_mfma_f32_16x16x32_bf16 v[68:71], v[214:217], v[206:209], v[68:71]
	v_mfma_f32_16x16x32_bf16 v[68:71], v[218:221], v[210:213], v[68:71]
	v_mfma_f32_16x16x32_bf16 v[64:67], v[222:225], v[206:209], v[64:67]
	v_mfma_f32_16x16x32_bf16 v[64:67], v[226:229], v[210:213], v[64:67]
	s_setprio 0
	s_mov_b32 m0, s50
	v_lshl_add_u64 v[234:235], s[48:49], 0, v[134:135]
	s_barrier
	ds_read_b128 v[180:183], v153 offset:16384
	ds_read_b128 v[186:189], v153 offset:17408
	ds_read_b128 v[190:193], v153 offset:18432
	ds_read_b128 v[194:197], v153 offset:19456
	ds_read_b128 v[198:201], v153 offset:20480
	ds_read_b128 v[202:205], v153 offset:21504
	ds_read_b128 v[206:209], v153 offset:22528
	ds_read_b128 v[210:213], v153 offset:23552
	global_load_lds_dwordx4 v[234:235], off
	v_lshl_add_u64 v[236:237], s[48:49], 0, v[130:131]
	s_mov_b32 m0, s51
	s_nop 0
	global_load_lds_dwordx4 v[236:237], off
	s_barrier
	s_waitcnt lgkmcnt(0)
	s_setprio 1
	s_waitcnt lgkmcnt(0)
	v_mfma_f32_16x16x32_bf16 v[60:63], v[160:163], v[180:183], v[60:63]
	v_mfma_f32_16x16x32_bf16 v[60:63], v[164:167], v[186:189], v[60:63]
	v_mfma_f32_16x16x32_bf16 v[56:59], v[168:171], v[180:183], v[56:59]
	v_mfma_f32_16x16x32_bf16 v[56:59], v[176:179], v[186:189], v[56:59]
	v_mfma_f32_16x16x32_bf16 v[48:51], v[160:163], v[190:193], v[48:51]
	v_mfma_f32_16x16x32_bf16 v[48:51], v[164:167], v[194:197], v[48:51]
	v_mfma_f32_16x16x32_bf16 v[40:43], v[168:171], v[190:193], v[40:43]
	v_mfma_f32_16x16x32_bf16 v[40:43], v[176:179], v[194:197], v[40:43]
	v_mfma_f32_16x16x32_bf16 v[32:35], v[160:163], v[198:201], v[32:35]
	v_mfma_f32_16x16x32_bf16 v[32:35], v[164:167], v[202:205], v[32:35]
	v_mfma_f32_16x16x32_bf16 v[24:27], v[168:171], v[198:201], v[24:27]
	v_mfma_f32_16x16x32_bf16 v[24:27], v[176:179], v[202:205], v[24:27]
	v_mfma_f32_16x16x32_bf16 v[16:19], v[160:163], v[206:209], v[16:19]
	v_mfma_f32_16x16x32_bf16 v[16:19], v[164:167], v[210:213], v[16:19]
	v_mfma_f32_16x16x32_bf16 v[8:11], v[168:171], v[206:209], v[8:11]
	v_mfma_f32_16x16x32_bf16 v[8:11], v[176:179], v[210:213], v[8:11]
	s_setprio 0
	s_barrier
	s_add_u32 s42, s46, 0x40000
	s_addc_u32 s43, s47, 0
	s_add_i32 s84, s77, s5
	v_lshl_add_u64 v[160:161], s[42:43], 0, v[132:133]
	s_mov_b32 m0, s84
	s_nop 0
	global_load_lds_dwordx4 v[160:161], off
	v_lshl_add_u64 v[160:161], s[42:43], 0, v[128:129]
	s_add_i32 m0, s84, 0x2000
	s_nop 0
	global_load_lds_dwordx4 v[160:161], off
	s_waitcnt vmcnt(6)
	s_barrier
	s_setprio 1
	v_mfma_f32_16x16x32_bf16 v[52:55], v[214:217], v[180:183], v[52:55]
	v_mfma_f32_16x16x32_bf16 v[52:55], v[218:221], v[186:189], v[52:55]
	v_mfma_f32_16x16x32_bf16 v[44:47], v[222:225], v[180:183], v[44:47]
	v_mfma_f32_16x16x32_bf16 v[44:47], v[226:229], v[186:189], v[44:47]
	v_mfma_f32_16x16x32_bf16 v[36:39], v[214:217], v[190:193], v[36:39]
	v_mfma_f32_16x16x32_bf16 v[36:39], v[218:221], v[194:197], v[36:39]
	v_mfma_f32_16x16x32_bf16 v[28:31], v[222:225], v[190:193], v[28:31]
	v_mfma_f32_16x16x32_bf16 v[28:31], v[226:229], v[194:197], v[28:31]
	v_mfma_f32_16x16x32_bf16 v[20:23], v[214:217], v[198:201], v[20:23]
	v_mfma_f32_16x16x32_bf16 v[20:23], v[218:221], v[202:205], v[20:23]
	v_mfma_f32_16x16x32_bf16 v[12:15], v[222:225], v[198:201], v[12:15]
	v_mfma_f32_16x16x32_bf16 v[12:15], v[226:229], v[202:205], v[12:15]
	v_mfma_f32_16x16x32_bf16 v[4:7], v[214:217], v[206:209], v[4:7]
	v_mfma_f32_16x16x32_bf16 v[4:7], v[218:221], v[210:213], v[4:7]
	v_mfma_f32_16x16x32_bf16 v[0:3], v[222:225], v[206:209], v[0:3]
	v_mfma_f32_16x16x32_bf16 v[0:3], v[226:229], v[210:213], v[0:3]
	s_setprio 0
	s_add_i32 s84, 0, 0x18000
	v_add_u32_e32 v157, s84, v139
	s_barrier
	ds_read_b128 v[160:163], v157
	ds_read_b128 v[164:167], v157 offset:1024
	ds_read_b128 v[168:171], v157 offset:2048
	ds_read_b128 v[176:179], v157 offset:3072
	s_add_u32 s42, s48, 0x170000
	s_addc_u32 s43, s49, 0
	s_mov_b32 m0, s52
	v_lshl_add_u64 v[214:215], s[42:43], 0, v[134:135]
	ds_read_b128 v[180:183], v153 offset:32768
	ds_read_b128 v[186:189], v153 offset:33792
	ds_read_b128 v[190:193], v153 offset:34816
	ds_read_b128 v[194:197], v153 offset:35840
	ds_read_b128 v[198:201], v153 offset:36864
	ds_read_b128 v[202:205], v153 offset:37888
	ds_read_b128 v[206:209], v153 offset:38912
	ds_read_b128 v[210:213], v153 offset:39936
	global_load_lds_dwordx4 v[214:215], off
	v_lshl_add_u64 v[214:215], s[42:43], 0, v[130:131]
	s_mov_b32 m0, s53
	s_nop 0
	global_load_lds_dwordx4 v[214:215], off
	s_waitcnt lgkmcnt(8)
	s_barrier
	s_waitcnt lgkmcnt(0)
	s_setprio 1
	s_waitcnt lgkmcnt(0)
	v_mfma_f32_16x16x32_bf16 v[124:127], v[160:163], v[180:183], v[124:127]
	v_mfma_f32_16x16x32_bf16 v[124:127], v[164:167], v[186:189], v[124:127]
	v_mfma_f32_16x16x32_bf16 v[120:123], v[168:171], v[180:183], v[120:123]
	v_mfma_f32_16x16x32_bf16 v[120:123], v[176:179], v[186:189], v[120:123]
	v_mfma_f32_16x16x32_bf16 v[112:115], v[160:163], v[190:193], v[112:115]
	v_mfma_f32_16x16x32_bf16 v[112:115], v[164:167], v[194:197], v[112:115]
	v_mfma_f32_16x16x32_bf16 v[104:107], v[168:171], v[190:193], v[104:107]
	v_mfma_f32_16x16x32_bf16 v[104:107], v[176:179], v[194:197], v[104:107]
	v_mfma_f32_16x16x32_bf16 v[96:99], v[160:163], v[198:201], v[96:99]
	v_mfma_f32_16x16x32_bf16 v[96:99], v[164:167], v[202:205], v[96:99]
	v_mfma_f32_16x16x32_bf16 v[88:91], v[168:171], v[198:201], v[88:91]
	v_mfma_f32_16x16x32_bf16 v[88:91], v[176:179], v[202:205], v[88:91]
	v_mfma_f32_16x16x32_bf16 v[80:83], v[160:163], v[206:209], v[80:83]
	v_mfma_f32_16x16x32_bf16 v[80:83], v[164:167], v[210:213], v[80:83]
	v_mfma_f32_16x16x32_bf16 v[72:75], v[168:171], v[206:209], v[72:75]
	v_mfma_f32_16x16x32_bf16 v[72:75], v[176:179], v[210:213], v[72:75]
	s_setprio 0
	s_barrier
	s_add_i32 s48, 0, 0x1c000
	s_add_i32 s42, s84, s5
	v_add_u32_e32 v157, s48, v139
	v_lshl_add_u64 v[230:231], v[230:231], 0, s[10:11]
	s_mov_b32 m0, s42
	ds_read_b128 v[214:217], v157
	ds_read_b128 v[218:221], v157 offset:1024
	ds_read_b128 v[222:225], v157 offset:2048
	ds_read_b128 v[226:229], v157 offset:3072
	global_load_lds_dwordx4 v[230:231], off
	v_lshl_add_u64 v[230:231], v[232:233], 0, s[10:11]
	s_add_i32 m0, s42, 0x2000
	s_nop 0
	global_load_lds_dwordx4 v[230:231], off
	s_barrier
	s_waitcnt lgkmcnt(0)
	s_setprio 1
	s_waitcnt lgkmcnt(0)
	v_mfma_f32_16x16x32_bf16 v[116:119], v[214:217], v[180:183], v[116:119]
	v_mfma_f32_16x16x32_bf16 v[116:119], v[218:221], v[186:189], v[116:119]
	v_mfma_f32_16x16x32_bf16 v[108:111], v[222:225], v[180:183], v[108:111]
	v_mfma_f32_16x16x32_bf16 v[108:111], v[226:229], v[186:189], v[108:111]
	v_mfma_f32_16x16x32_bf16 v[100:103], v[214:217], v[190:193], v[100:103]
	v_mfma_f32_16x16x32_bf16 v[100:103], v[218:221], v[194:197], v[100:103]
	v_mfma_f32_16x16x32_bf16 v[92:95], v[222:225], v[190:193], v[92:95]
	v_mfma_f32_16x16x32_bf16 v[92:95], v[226:229], v[194:197], v[92:95]
	v_mfma_f32_16x16x32_bf16 v[84:87], v[214:217], v[198:201], v[84:87]
	v_mfma_f32_16x16x32_bf16 v[84:87], v[218:221], v[202:205], v[84:87]
	v_mfma_f32_16x16x32_bf16 v[76:79], v[222:225], v[198:201], v[76:79]
	v_mfma_f32_16x16x32_bf16 v[76:79], v[226:229], v[202:205], v[76:79]
	v_mfma_f32_16x16x32_bf16 v[68:71], v[214:217], v[206:209], v[68:71]
	v_mfma_f32_16x16x32_bf16 v[68:71], v[218:221], v[210:213], v[68:71]
	v_mfma_f32_16x16x32_bf16 v[64:67], v[222:225], v[206:209], v[64:67]
	v_mfma_f32_16x16x32_bf16 v[64:67], v[226:229], v[210:213], v[64:67]
	s_setprio 0
	s_mov_b32 m0, s55
	v_lshl_add_u64 v[230:231], v[234:235], 0, s[10:11]
	s_barrier
	ds_read_b128 v[180:183], v153 offset:49152
	ds_read_b128 v[186:189], v153 offset:50176
	ds_read_b128 v[190:193], v153 offset:51200
	ds_read_b128 v[194:197], v153 offset:52224
	ds_read_b128 v[198:201], v153 offset:53248
	ds_read_b128 v[202:205], v153 offset:54272
	ds_read_b128 v[206:209], v153 offset:55296
	ds_read_b128 v[210:213], v153 offset:56320
	global_load_lds_dwordx4 v[230:231], off
	v_lshl_add_u64 v[230:231], v[236:237], 0, s[10:11]
	s_mov_b32 m0, s61
	s_nop 0
	global_load_lds_dwordx4 v[230:231], off
	s_barrier
	s_waitcnt lgkmcnt(0)
	s_setprio 1
	s_waitcnt lgkmcnt(0)
	v_mfma_f32_16x16x32_bf16 v[60:63], v[160:163], v[180:183], v[60:63]
	v_mfma_f32_16x16x32_bf16 v[60:63], v[164:167], v[186:189], v[60:63]
	v_mfma_f32_16x16x32_bf16 v[56:59], v[168:171], v[180:183], v[56:59]
	v_mfma_f32_16x16x32_bf16 v[56:59], v[176:179], v[186:189], v[56:59]
	v_mfma_f32_16x16x32_bf16 v[48:51], v[160:163], v[190:193], v[48:51]
	v_mfma_f32_16x16x32_bf16 v[48:51], v[164:167], v[194:197], v[48:51]
	v_mfma_f32_16x16x32_bf16 v[40:43], v[168:171], v[190:193], v[40:43]
	v_mfma_f32_16x16x32_bf16 v[40:43], v[176:179], v[194:197], v[40:43]
	v_mfma_f32_16x16x32_bf16 v[32:35], v[160:163], v[198:201], v[32:35]
	v_mfma_f32_16x16x32_bf16 v[32:35], v[164:167], v[202:205], v[32:35]
	v_mfma_f32_16x16x32_bf16 v[24:27], v[168:171], v[198:201], v[24:27]
	v_mfma_f32_16x16x32_bf16 v[24:27], v[176:179], v[202:205], v[24:27]
	v_mfma_f32_16x16x32_bf16 v[16:19], v[160:163], v[206:209], v[16:19]
	v_mfma_f32_16x16x32_bf16 v[16:19], v[164:167], v[210:213], v[16:19]
	v_mfma_f32_16x16x32_bf16 v[8:11], v[168:171], v[206:209], v[8:11]
	v_mfma_f32_16x16x32_bf16 v[8:11], v[176:179], v[210:213], v[8:11]
	s_setprio 0
	s_barrier
	s_add_u32 s42, s46, 0x40080
	s_addc_u32 s43, s47, 0
	s_add_i32 s46, s48, s5
	v_lshl_add_u64 v[160:161], s[42:43], 0, v[132:133]
	s_mov_b32 m0, s46
	s_nop 0
	global_load_lds_dwordx4 v[160:161], off
	v_lshl_add_u64 v[160:161], s[42:43], 0, v[128:129]
	s_add_i32 m0, s46, 0x2000
	s_nop 0
	global_load_lds_dwordx4 v[160:161], off
	s_waitcnt vmcnt(6)
	s_barrier
	s_setprio 1
	v_mfma_f32_16x16x32_bf16 v[52:55], v[214:217], v[180:183], v[52:55]
	v_mfma_f32_16x16x32_bf16 v[52:55], v[218:221], v[186:189], v[52:55]
	v_mfma_f32_16x16x32_bf16 v[44:47], v[222:225], v[180:183], v[44:47]
	v_mfma_f32_16x16x32_bf16 v[44:47], v[226:229], v[186:189], v[44:47]
	v_mfma_f32_16x16x32_bf16 v[36:39], v[214:217], v[190:193], v[36:39]
	v_mfma_f32_16x16x32_bf16 v[36:39], v[218:221], v[194:197], v[36:39]
	v_mfma_f32_16x16x32_bf16 v[28:31], v[222:225], v[190:193], v[28:31]
	v_mfma_f32_16x16x32_bf16 v[28:31], v[226:229], v[194:197], v[28:31]
	v_mfma_f32_16x16x32_bf16 v[20:23], v[214:217], v[198:201], v[20:23]
	v_mfma_f32_16x16x32_bf16 v[20:23], v[218:221], v[202:205], v[20:23]
	v_mfma_f32_16x16x32_bf16 v[12:15], v[222:225], v[198:201], v[12:15]
	v_mfma_f32_16x16x32_bf16 v[12:15], v[226:229], v[202:205], v[12:15]
	v_mfma_f32_16x16x32_bf16 v[4:7], v[214:217], v[206:209], v[4:7]
	v_mfma_f32_16x16x32_bf16 v[4:7], v[218:221], v[210:213], v[4:7]
	v_mfma_f32_16x16x32_bf16 v[0:3], v[222:225], v[206:209], v[0:3]
	v_mfma_f32_16x16x32_bf16 v[0:3], v[226:229], v[210:213], v[0:3]
	s_setprio 0
	s_add_i32 s83, s83, 2
	s_add_u32 s63, s63, 0x100
	s_addc_u32 s82, s82, 0
	s_cmp_gt_u32 s83, 13
	s_mov_b64 s[42:43], s[44:45]
	s_barrier
	s_cbranch_scc0 .LBB0_301
	v_lshl_or_b32 v162, s81, 8, v141
	v_lshl_add_u32 v157, s80, 8, v137
	v_ashrrev_i32_e32 v163, 31, v162
	v_mov_b64_e32 v[160:161], s[12:13]
	v_mad_i64_i32 v[164:165], s[42:43], v157, s78, v[160:161]
	v_lshlrev_b64 v[162:163], 1, v[162:163]
	v_lshl_add_u64 v[164:165], v[164:165], 0, v[162:163]
	s_waitcnt vmcnt(0)
	v_pk_mul_f32 v[126:127], v[158:159], v[126:127] op_sel_hi:[0,1]
	v_pk_mul_f32 v[124:125], v[158:159], v[124:125] op_sel_hi:[0,1]
	v_pk_mul_f32 v[166:167], v[158:159], v[122:123] op_sel_hi:[0,1]
	v_pk_mul_f32 v[122:123], v[158:159], v[120:121] op_sel_hi:[0,1]
	v_cvt_pk_bf16_f32 v120, v124, v125
	v_cvt_pk_bf16_f32 v121, v126, v127
	v_cvt_pk_bf16_f32 v122, v122, v123
	v_cvt_pk_bf16_f32 v123, v166, v167
	global_store_dwordx4 v[164:165], v[120:123], off
	v_pk_mul_f32 v[116:117], v[158:159], v[116:117] op_sel_hi:[0,1]
	v_pk_mul_f32 v[118:119], v[158:159], v[118:119] op_sel_hi:[0,1]
	v_pk_mul_f32 v[120:121], v[158:159], v[110:111] op_sel_hi:[0,1]
	v_pk_mul_f32 v[110:111], v[158:159], v[108:109] op_sel_hi:[0,1]
	v_cvt_pk_bf16_f32 v108, v116, v117
	v_cvt_pk_bf16_f32 v109, v118, v119
	v_cvt_pk_bf16_f32 v110, v110, v111
	v_cvt_pk_bf16_f32 v111, v120, v121
	global_store_dwordx4 v[164:165], v[108:111], off offset:256
	v_pk_mul_f32 v[112:113], v[156:157], v[112:113] op_sel_hi:[0,1]
	v_pk_mul_f32 v[100:101], v[156:157], v[100:101] op_sel_hi:[0,1]
	v_or_b32_e32 v108, 16, v157
	v_mad_i64_i32 v[108:109], s[42:43], v108, s78, v[160:161]
	v_lshl_add_u64 v[108:109], v[108:109], 0, v[162:163]
	v_pk_mul_f32 v[110:111], v[156:157], v[114:115] op_sel_hi:[0,1]
	v_pk_mul_f32 v[114:115], v[156:157], v[106:107] op_sel_hi:[0,1]
	v_pk_mul_f32 v[106:107], v[156:157], v[104:105] op_sel_hi:[0,1]
	v_cvt_pk_bf16_f32 v104, v112, v113
	v_cvt_pk_bf16_f32 v105, v110, v111
	v_cvt_pk_bf16_f32 v106, v106, v107
	v_cvt_pk_bf16_f32 v107, v114, v115
	global_store_dwordx4 v[108:109], v[104:107], off
	v_pk_mul_f32 v[102:103], v[156:157], v[102:103] op_sel_hi:[0,1]
	v_pk_mul_f32 v[96:97], v[154:155], v[96:97] op_sel_hi:[0,1]
	v_pk_mul_f32 v[104:105], v[156:157], v[94:95] op_sel_hi:[0,1]
	v_pk_mul_f32 v[94:95], v[156:157], v[92:93] op_sel_hi:[0,1]
	v_cvt_pk_bf16_f32 v92, v100, v101
	v_cvt_pk_bf16_f32 v93, v102, v103
	v_cvt_pk_bf16_f32 v94, v94, v95
	v_cvt_pk_bf16_f32 v95, v104, v105
	global_store_dwordx4 v[108:109], v[92:95], off offset:256
	v_pk_mul_f32 v[84:85], v[154:155], v[84:85] op_sel_hi:[0,1]
	v_pk_mul_f32 v[86:87], v[154:155], v[86:87] op_sel_hi:[0,1]
	v_or_b32_e32 v92, 32, v157
	v_mad_i64_i32 v[92:93], s[42:43], v92, s78, v[160:161]
	v_lshl_add_u64 v[92:93], v[92:93], 0, v[162:163]
	v_pk_mul_f32 v[94:95], v[154:155], v[98:99] op_sel_hi:[0,1]
	v_pk_mul_f32 v[98:99], v[154:155], v[90:91] op_sel_hi:[0,1]
	v_pk_mul_f32 v[90:91], v[154:155], v[88:89] op_sel_hi:[0,1]
	v_cvt_pk_bf16_f32 v88, v96, v97
	v_cvt_pk_bf16_f32 v89, v94, v95
	v_cvt_pk_bf16_f32 v90, v90, v91
	v_cvt_pk_bf16_f32 v91, v98, v99
	global_store_dwordx4 v[92:93], v[88:91], off
	v_pk_mul_f32 v[80:81], v[152:153], v[80:81] op_sel_hi:[0,1]
	v_pk_mul_f32 v[68:69], v[152:153], v[68:69] op_sel_hi:[0,1]
	v_pk_mul_f32 v[88:89], v[154:155], v[78:79] op_sel_hi:[0,1]
	v_pk_mul_f32 v[78:79], v[154:155], v[76:77] op_sel_hi:[0,1]
	v_cvt_pk_bf16_f32 v76, v84, v85
	v_cvt_pk_bf16_f32 v77, v86, v87
	v_cvt_pk_bf16_f32 v78, v78, v79
	v_cvt_pk_bf16_f32 v79, v88, v89
	global_store_dwordx4 v[92:93], v[76:79], off offset:256
	v_pk_mul_f32 v[70:71], v[152:153], v[70:71] op_sel_hi:[0,1]
	v_pk_mul_f32 v[62:63], v[150:151], v[62:63] op_sel_hi:[0,1]
	v_or_b32_e32 v76, 48, v157
	v_mad_i64_i32 v[76:77], s[42:43], v76, s78, v[160:161]
	v_lshl_add_u64 v[76:77], v[76:77], 0, v[162:163]
	v_pk_mul_f32 v[78:79], v[152:153], v[82:83] op_sel_hi:[0,1]
	v_pk_mul_f32 v[82:83], v[152:153], v[74:75] op_sel_hi:[0,1]
	v_pk_mul_f32 v[74:75], v[152:153], v[72:73] op_sel_hi:[0,1]
	v_cvt_pk_bf16_f32 v72, v80, v81
	v_cvt_pk_bf16_f32 v73, v78, v79
	v_cvt_pk_bf16_f32 v74, v74, v75
	v_cvt_pk_bf16_f32 v75, v82, v83
	global_store_dwordx4 v[76:77], v[72:75], off
	v_pk_mul_f32 v[60:61], v[150:151], v[60:61] op_sel_hi:[0,1]
	v_pk_mul_f32 v[52:53], v[150:151], v[52:53] op_sel_hi:[0,1]
	v_pk_mul_f32 v[72:73], v[152:153], v[66:67] op_sel_hi:[0,1]
	v_pk_mul_f32 v[66:67], v[152:153], v[64:65] op_sel_hi:[0,1]
	v_cvt_pk_bf16_f32 v64, v68, v69
	v_cvt_pk_bf16_f32 v65, v70, v71
	v_cvt_pk_bf16_f32 v66, v66, v67
	v_cvt_pk_bf16_f32 v67, v72, v73
	global_store_dwordx4 v[76:77], v[64:67], off offset:256
	v_pk_mul_f32 v[54:55], v[150:151], v[54:55] op_sel_hi:[0,1]
	v_pk_mul_f32 v[48:49], v[140:141], v[48:49] op_sel_hi:[0,1]
	v_add_u32_e32 v64, 0x80, v157
	v_mad_i64_i32 v[64:65], s[42:43], v64, s78, v[160:161]
	v_lshl_add_u64 v[64:65], v[64:65], 0, v[162:163]
	v_pk_mul_f32 v[66:67], v[150:151], v[58:59] op_sel_hi:[0,1]
	v_pk_mul_f32 v[58:59], v[150:151], v[56:57] op_sel_hi:[0,1]
	v_cvt_pk_bf16_f32 v56, v60, v61
	v_cvt_pk_bf16_f32 v57, v62, v63
	v_cvt_pk_bf16_f32 v58, v58, v59
	v_cvt_pk_bf16_f32 v59, v66, v67
	global_store_dwordx4 v[64:65], v[56:59], off
	v_pk_mul_f32 v[36:37], v[140:141], v[36:37] op_sel_hi:[0,1]
	v_pk_mul_f32 v[38:39], v[140:141], v[38:39] op_sel_hi:[0,1]
	v_pk_mul_f32 v[56:57], v[150:151], v[46:47] op_sel_hi:[0,1]
	v_pk_mul_f32 v[46:47], v[150:151], v[44:45] op_sel_hi:[0,1]
	v_cvt_pk_bf16_f32 v44, v52, v53
	v_cvt_pk_bf16_f32 v45, v54, v55
	v_cvt_pk_bf16_f32 v46, v46, v47
	v_cvt_pk_bf16_f32 v47, v56, v57
	global_store_dwordx4 v[64:65], v[44:47], off offset:256
	v_pk_mul_f32 v[32:33], v[138:139], v[32:33] op_sel_hi:[0,1]
	v_pk_mul_f32 v[20:21], v[138:139], v[20:21] op_sel_hi:[0,1]
	v_add_u32_e32 v44, 0x90, v157
	v_mad_i64_i32 v[44:45], s[42:43], v44, s78, v[160:161]
	v_lshl_add_u64 v[44:45], v[44:45], 0, v[162:163]
	v_pk_mul_f32 v[46:47], v[140:141], v[50:51] op_sel_hi:[0,1]
	v_pk_mul_f32 v[50:51], v[140:141], v[42:43] op_sel_hi:[0,1]
	v_pk_mul_f32 v[42:43], v[140:141], v[40:41] op_sel_hi:[0,1]
	v_cvt_pk_bf16_f32 v40, v48, v49
	v_cvt_pk_bf16_f32 v41, v46, v47
	v_cvt_pk_bf16_f32 v42, v42, v43
	v_cvt_pk_bf16_f32 v43, v50, v51
	global_store_dwordx4 v[44:45], v[40:43], off
	v_pk_mul_f32 v[22:23], v[138:139], v[22:23] op_sel_hi:[0,1]
	v_pk_mul_f32 v[16:17], v[136:137], v[16:17] op_sel_hi:[0,1]
	v_pk_mul_f32 v[40:41], v[140:141], v[30:31] op_sel_hi:[0,1]
	v_pk_mul_f32 v[30:31], v[140:141], v[28:29] op_sel_hi:[0,1]
	v_cvt_pk_bf16_f32 v28, v36, v37
	v_cvt_pk_bf16_f32 v29, v38, v39
	v_cvt_pk_bf16_f32 v30, v30, v31
	v_cvt_pk_bf16_f32 v31, v40, v41
	global_store_dwordx4 v[44:45], v[28:31], off offset:256
	s_and_b64 vcc, s[8:9], exec
	v_pk_mul_f32 v[6:7], v[136:137], v[6:7] op_sel_hi:[0,1]
	v_add_u32_e32 v28, 0xa0, v157
	v_mad_i64_i32 v[28:29], s[42:43], v28, s78, v[160:161]
	v_lshl_add_u64 v[28:29], v[28:29], 0, v[162:163]
	v_pk_mul_f32 v[30:31], v[138:139], v[34:35] op_sel_hi:[0,1]
	v_pk_mul_f32 v[34:35], v[138:139], v[26:27] op_sel_hi:[0,1]
	v_pk_mul_f32 v[26:27], v[138:139], v[24:25] op_sel_hi:[0,1]
	v_cvt_pk_bf16_f32 v24, v32, v33
	v_cvt_pk_bf16_f32 v25, v30, v31
	v_cvt_pk_bf16_f32 v26, v26, v27
	v_cvt_pk_bf16_f32 v27, v34, v35
	global_store_dwordx4 v[28:29], v[24:27], off
	v_pk_mul_f32 v[4:5], v[136:137], v[4:5] op_sel_hi:[0,1]
	s_nop 0
	v_pk_mul_f32 v[24:25], v[138:139], v[14:15] op_sel_hi:[0,1]
	v_pk_mul_f32 v[14:15], v[138:139], v[12:13] op_sel_hi:[0,1]
	v_cvt_pk_bf16_f32 v12, v20, v21
	v_cvt_pk_bf16_f32 v13, v22, v23
	v_cvt_pk_bf16_f32 v14, v14, v15
	v_cvt_pk_bf16_f32 v15, v24, v25
	global_store_dwordx4 v[28:29], v[12:15], off offset:256
	s_nop 1
	v_add_u32_e32 v12, 0xb0, v157
	v_mad_i64_i32 v[12:13], s[42:43], v12, s78, v[160:161]
	v_lshl_add_u64 v[12:13], v[12:13], 0, v[162:163]
	v_pk_mul_f32 v[14:15], v[136:137], v[18:19] op_sel_hi:[0,1]
	v_pk_mul_f32 v[18:19], v[136:137], v[10:11] op_sel_hi:[0,1]
	v_pk_mul_f32 v[10:11], v[136:137], v[8:9] op_sel_hi:[0,1]
	v_cvt_pk_bf16_f32 v8, v16, v17
	v_cvt_pk_bf16_f32 v9, v14, v15
	v_cvt_pk_bf16_f32 v10, v10, v11
	v_cvt_pk_bf16_f32 v11, v18, v19
	global_store_dwordx4 v[12:13], v[8:11], off
	s_mov_b64 s[42:43], -1
	s_nop 0
	v_pk_mul_f32 v[8:9], v[136:137], v[2:3] op_sel_hi:[0,1]
	v_pk_mul_f32 v[2:3], v[136:137], v[0:1] op_sel_hi:[0,1]
	v_cvt_pk_bf16_f32 v0, v4, v5
	v_cvt_pk_bf16_f32 v1, v6, v7
	v_cvt_pk_bf16_f32 v2, v2, v3
	v_cvt_pk_bf16_f32 v3, v8, v9
	global_store_dwordx4 v[12:13], v[0:3], off offset:256
	s_cbranch_vccz .LBB0_295
	s_nop 0
	v_lshl_add_u32 v0, s79, 8, v137
	v_ashrrev_i32_e32 v1, 31, v0
	v_lshl_add_u64 v[0:1], v[0:1], 2, s[72:73]
	global_load_dword v158, v[0:1], off
	global_load_dword v156, v[0:1], off offset:64
	global_load_dword v154, v[0:1], off offset:128
	global_load_dword v152, v[0:1], off offset:192
	global_load_dword v150, v[0:1], off offset:512
	global_load_dword v140, v[0:1], off offset:576
	global_load_dword v138, v[0:1], off offset:640
	global_load_dword v136, v[0:1], off offset:704
	s_mov_b64 s[42:43], 0
	s_branch .LBB0_295

.LBB0_325:
	ds_read_b128 v[160:163], v151
	ds_read_b128 v[164:167], v151 offset:1024
	ds_read_b128 v[168:171], v151 offset:2048
	ds_read_b128 v[176:179], v151 offset:3072
	s_add_u32 s48, s46, 0x100
	s_addc_u32 s49, s47, 0
	s_cmp_eq_u32 s91, 4
	s_cselect_b32 s53, s43, s49
	s_cselect_b32 s52, s42, s48
	s_cselect_b32 s51, s41, s90
	s_cselect_b32 s50, s62, s63
	v_lshl_add_u64 v[214:215], s[46:47], 0, v[142:143]
	s_add_i32 m0, s55, 0xc000
	ds_read_b128 v[180:183], v153
	ds_read_b128 v[186:189], v153 offset:1024
	ds_read_b128 v[190:193], v153 offset:2048
	ds_read_b128 v[194:197], v153 offset:3072
	ds_read_b128 v[198:201], v153 offset:4096
	ds_read_b128 v[202:205], v153 offset:5120
	ds_read_b128 v[206:209], v153 offset:6144
	ds_read_b128 v[210:213], v153 offset:7168
	global_load_lds_dwordx4 v[214:215], off
	v_lshl_add_u64 v[214:215], s[46:47], 0, v[144:145]
	s_add_i32 m0, s55, 0xe000
	s_nop 0
	global_load_lds_dwordx4 v[214:215], off
	s_waitcnt lgkmcnt(8)
	s_barrier
	s_waitcnt lgkmcnt(0)
	s_setprio 1
	s_waitcnt lgkmcnt(0)
	v_mfma_f32_16x16x32_bf16 v[124:127], v[160:163], v[180:183], v[124:127]
	v_mfma_f32_16x16x32_bf16 v[124:127], v[164:167], v[186:189], v[124:127]
	v_mfma_f32_16x16x32_bf16 v[120:123], v[168:171], v[180:183], v[120:123]
	v_mfma_f32_16x16x32_bf16 v[120:123], v[176:179], v[186:189], v[120:123]
	v_mfma_f32_16x16x32_bf16 v[108:111], v[160:163], v[190:193], v[108:111]
	v_mfma_f32_16x16x32_bf16 v[108:111], v[164:167], v[194:197], v[108:111]
	v_mfma_f32_16x16x32_bf16 v[104:107], v[168:171], v[190:193], v[104:107]
	v_mfma_f32_16x16x32_bf16 v[104:107], v[176:179], v[194:197], v[104:107]
	v_mfma_f32_16x16x32_bf16 v[92:95], v[160:163], v[198:201], v[92:95]
	v_mfma_f32_16x16x32_bf16 v[92:95], v[164:167], v[202:205], v[92:95]
	v_mfma_f32_16x16x32_bf16 v[88:91], v[168:171], v[198:201], v[88:91]
	v_mfma_f32_16x16x32_bf16 v[88:91], v[176:179], v[202:205], v[88:91]
	v_mfma_f32_16x16x32_bf16 v[76:79], v[160:163], v[206:209], v[76:79]
	v_mfma_f32_16x16x32_bf16 v[76:79], v[164:167], v[210:213], v[76:79]
	v_mfma_f32_16x16x32_bf16 v[72:75], v[168:171], v[206:209], v[72:75]
	v_mfma_f32_16x16x32_bf16 v[72:75], v[176:179], v[210:213], v[72:75]
	s_setprio 0
	s_barrier
	s_add_i32 s46, s81, s54
	v_lshl_add_u64 v[230:231], s[50:51], 0, v[130:131]
	s_mov_b32 m0, s46
	ds_read_b128 v[214:217], v155
	ds_read_b128 v[218:221], v155 offset:1024
	ds_read_b128 v[222:225], v155 offset:2048
	ds_read_b128 v[226:229], v155 offset:3072
	global_load_lds_dwordx4 v[230:231], off
	v_lshl_add_u64 v[232:233], s[50:51], 0, v[134:135]
	s_add_i32 m0, s46, 0x2000
	s_nop 0
	global_load_lds_dwordx4 v[232:233], off
	s_barrier
	s_waitcnt lgkmcnt(0)
	s_setprio 1
	s_waitcnt lgkmcnt(0)
	v_mfma_f32_16x16x32_bf16 v[116:119], v[214:217], v[180:183], v[116:119]
	v_mfma_f32_16x16x32_bf16 v[116:119], v[218:221], v[186:189], v[116:119]
	v_mfma_f32_16x16x32_bf16 v[112:115], v[222:225], v[180:183], v[112:115]
	v_mfma_f32_16x16x32_bf16 v[112:115], v[226:229], v[186:189], v[112:115]
	v_mfma_f32_16x16x32_bf16 v[100:103], v[214:217], v[190:193], v[100:103]
	v_mfma_f32_16x16x32_bf16 v[100:103], v[218:221], v[194:197], v[100:103]
	v_mfma_f32_16x16x32_bf16 v[96:99], v[222:225], v[190:193], v[96:99]
	v_mfma_f32_16x16x32_bf16 v[96:99], v[226:229], v[194:197], v[96:99]
	v_mfma_f32_16x16x32_bf16 v[84:87], v[214:217], v[198:201], v[84:87]
	v_mfma_f32_16x16x32_bf16 v[84:87], v[218:221], v[202:205], v[84:87]
	v_mfma_f32_16x16x32_bf16 v[80:83], v[222:225], v[198:201], v[80:83]
	v_mfma_f32_16x16x32_bf16 v[80:83], v[226:229], v[202:205], v[80:83]
	v_mfma_f32_16x16x32_bf16 v[68:71], v[214:217], v[206:209], v[68:71]
	v_mfma_f32_16x16x32_bf16 v[68:71], v[218:221], v[210:213], v[68:71]
	v_mfma_f32_16x16x32_bf16 v[64:67], v[222:225], v[206:209], v[64:67]
	v_mfma_f32_16x16x32_bf16 v[64:67], v[226:229], v[210:213], v[64:67]
	s_setprio 0
	s_mov_b32 m0, s55
	v_lshl_add_u64 v[234:235], s[52:53], 0, v[128:129]
	s_barrier
	ds_read_b128 v[180:183], v153 offset:16384
	ds_read_b128 v[186:189], v153 offset:17408
	ds_read_b128 v[190:193], v153 offset:18432
	ds_read_b128 v[194:197], v153 offset:19456
	ds_read_b128 v[198:201], v153 offset:20480
	ds_read_b128 v[202:205], v153 offset:21504
	ds_read_b128 v[206:209], v153 offset:22528
	ds_read_b128 v[210:213], v153 offset:23552
	global_load_lds_dwordx4 v[234:235], off
	v_lshl_add_u64 v[236:237], s[52:53], 0, v[132:133]
	s_mov_b32 m0, s61
	s_nop 0
	global_load_lds_dwordx4 v[236:237], off
	s_barrier
	s_waitcnt lgkmcnt(0)
	s_setprio 1
	s_waitcnt lgkmcnt(0)
	v_mfma_f32_16x16x32_bf16 v[60:63], v[160:163], v[180:183], v[60:63]
	v_mfma_f32_16x16x32_bf16 v[60:63], v[164:167], v[186:189], v[60:63]
	v_mfma_f32_16x16x32_bf16 v[56:59], v[168:171], v[180:183], v[56:59]
	v_mfma_f32_16x16x32_bf16 v[56:59], v[176:179], v[186:189], v[56:59]
	v_mfma_f32_16x16x32_bf16 v[48:51], v[160:163], v[190:193], v[48:51]
	v_mfma_f32_16x16x32_bf16 v[48:51], v[164:167], v[194:197], v[48:51]
	v_mfma_f32_16x16x32_bf16 v[40:43], v[168:171], v[190:193], v[40:43]
	v_mfma_f32_16x16x32_bf16 v[40:43], v[176:179], v[194:197], v[40:43]
	v_mfma_f32_16x16x32_bf16 v[32:35], v[160:163], v[198:201], v[32:35]
	v_mfma_f32_16x16x32_bf16 v[32:35], v[164:167], v[202:205], v[32:35]
	v_mfma_f32_16x16x32_bf16 v[24:27], v[168:171], v[198:201], v[24:27]
	v_mfma_f32_16x16x32_bf16 v[24:27], v[176:179], v[202:205], v[24:27]
	v_mfma_f32_16x16x32_bf16 v[16:19], v[160:163], v[206:209], v[16:19]
	v_mfma_f32_16x16x32_bf16 v[16:19], v[164:167], v[210:213], v[16:19]
	v_mfma_f32_16x16x32_bf16 v[8:11], v[168:171], v[206:209], v[8:11]
	v_mfma_f32_16x16x32_bf16 v[8:11], v[176:179], v[210:213], v[8:11]
	s_setprio 0
	s_barrier
	s_add_u32 s46, s50, 0x20000
	s_addc_u32 s47, s51, 0
	s_add_i32 s92, s82, s54
	v_lshl_add_u64 v[160:161], s[46:47], 0, v[130:131]
	s_mov_b32 m0, s92
	s_nop 0
	global_load_lds_dwordx4 v[160:161], off
	v_lshl_add_u64 v[160:161], s[46:47], 0, v[134:135]
	s_add_i32 m0, s92, 0x2000
	s_nop 0
	global_load_lds_dwordx4 v[160:161], off
	s_waitcnt vmcnt(6)
	s_barrier
	s_setprio 1
	v_mfma_f32_16x16x32_bf16 v[52:55], v[214:217], v[180:183], v[52:55]
	v_mfma_f32_16x16x32_bf16 v[52:55], v[218:221], v[186:189], v[52:55]
	v_mfma_f32_16x16x32_bf16 v[44:47], v[222:225], v[180:183], v[44:47]
	v_mfma_f32_16x16x32_bf16 v[44:47], v[226:229], v[186:189], v[44:47]
	v_mfma_f32_16x16x32_bf16 v[36:39], v[214:217], v[190:193], v[36:39]
	v_mfma_f32_16x16x32_bf16 v[36:39], v[218:221], v[194:197], v[36:39]
	v_mfma_f32_16x16x32_bf16 v[28:31], v[222:225], v[190:193], v[28:31]
	v_mfma_f32_16x16x32_bf16 v[28:31], v[226:229], v[194:197], v[28:31]
	v_mfma_f32_16x16x32_bf16 v[20:23], v[214:217], v[198:201], v[20:23]
	v_mfma_f32_16x16x32_bf16 v[20:23], v[218:221], v[202:205], v[20:23]
	v_mfma_f32_16x16x32_bf16 v[12:15], v[222:225], v[198:201], v[12:15]
	v_mfma_f32_16x16x32_bf16 v[12:15], v[226:229], v[202:205], v[12:15]
	v_mfma_f32_16x16x32_bf16 v[4:7], v[214:217], v[206:209], v[4:7]
	v_mfma_f32_16x16x32_bf16 v[4:7], v[218:221], v[210:213], v[4:7]
	v_mfma_f32_16x16x32_bf16 v[0:3], v[222:225], v[206:209], v[0:3]
	v_mfma_f32_16x16x32_bf16 v[0:3], v[226:229], v[210:213], v[0:3]
	s_setprio 0
	s_add_i32 s92, 0, 0x18000
	v_add_u32_e32 v157, s92, v139
	s_barrier
	ds_read_b128 v[160:163], v157
	ds_read_b128 v[164:167], v157 offset:1024
	ds_read_b128 v[168:171], v157 offset:2048
	ds_read_b128 v[176:179], v157 offset:3072
	s_add_u32 s46, s52, 0x170000
	s_addc_u32 s47, s53, 0
	s_mov_b32 m0, s74
	v_lshl_add_u64 v[214:215], s[46:47], 0, v[128:129]
	ds_read_b128 v[180:183], v153 offset:32768
	ds_read_b128 v[186:189], v153 offset:33792
	ds_read_b128 v[190:193], v153 offset:34816
	ds_read_b128 v[194:197], v153 offset:35840
	ds_read_b128 v[198:201], v153 offset:36864
	ds_read_b128 v[202:205], v153 offset:37888
	ds_read_b128 v[206:209], v153 offset:38912
	ds_read_b128 v[210:213], v153 offset:39936
	global_load_lds_dwordx4 v[214:215], off
	v_lshl_add_u64 v[214:215], s[46:47], 0, v[132:133]
	s_mov_b32 m0, s75
	s_nop 0
	global_load_lds_dwordx4 v[214:215], off
	s_waitcnt lgkmcnt(8)
	s_barrier
	s_waitcnt lgkmcnt(0)
	s_setprio 1
	s_waitcnt lgkmcnt(0)
	v_mfma_f32_16x16x32_bf16 v[124:127], v[160:163], v[180:183], v[124:127]
	v_mfma_f32_16x16x32_bf16 v[124:127], v[164:167], v[186:189], v[124:127]
	v_mfma_f32_16x16x32_bf16 v[120:123], v[168:171], v[180:183], v[120:123]
	v_mfma_f32_16x16x32_bf16 v[120:123], v[176:179], v[186:189], v[120:123]
	v_mfma_f32_16x16x32_bf16 v[108:111], v[160:163], v[190:193], v[108:111]
	v_mfma_f32_16x16x32_bf16 v[108:111], v[164:167], v[194:197], v[108:111]
	v_mfma_f32_16x16x32_bf16 v[104:107], v[168:171], v[190:193], v[104:107]
	v_mfma_f32_16x16x32_bf16 v[104:107], v[176:179], v[194:197], v[104:107]
	v_mfma_f32_16x16x32_bf16 v[92:95], v[160:163], v[198:201], v[92:95]
	v_mfma_f32_16x16x32_bf16 v[92:95], v[164:167], v[202:205], v[92:95]
	v_mfma_f32_16x16x32_bf16 v[88:91], v[168:171], v[198:201], v[88:91]
	v_mfma_f32_16x16x32_bf16 v[88:91], v[176:179], v[202:205], v[88:91]
	v_mfma_f32_16x16x32_bf16 v[76:79], v[160:163], v[206:209], v[76:79]
	v_mfma_f32_16x16x32_bf16 v[76:79], v[164:167], v[210:213], v[76:79]
	v_mfma_f32_16x16x32_bf16 v[72:75], v[168:171], v[206:209], v[72:75]
	v_mfma_f32_16x16x32_bf16 v[72:75], v[176:179], v[210:213], v[72:75]
	s_setprio 0
	s_barrier
	s_add_i32 s52, 0, 0x1c000
	s_add_i32 s46, s92, s54
	v_add_u32_e32 v157, s52, v139
	v_lshl_add_u64 v[230:231], v[230:231], 0, s[10:11]
	s_mov_b32 m0, s46
	ds_read_b128 v[214:217], v157
	ds_read_b128 v[218:221], v157 offset:1024
	ds_read_b128 v[222:225], v157 offset:2048
	ds_read_b128 v[226:229], v157 offset:3072
	global_load_lds_dwordx4 v[230:231], off
	v_lshl_add_u64 v[230:231], v[232:233], 0, s[10:11]
	s_add_i32 m0, s46, 0x2000
	s_nop 0
	global_load_lds_dwordx4 v[230:231], off
	s_barrier
	s_waitcnt lgkmcnt(0)
	s_setprio 1
	s_waitcnt lgkmcnt(0)
	v_mfma_f32_16x16x32_bf16 v[116:119], v[214:217], v[180:183], v[116:119]
	v_mfma_f32_16x16x32_bf16 v[116:119], v[218:221], v[186:189], v[116:119]
	v_mfma_f32_16x16x32_bf16 v[112:115], v[222:225], v[180:183], v[112:115]
	v_mfma_f32_16x16x32_bf16 v[112:115], v[226:229], v[186:189], v[112:115]
	v_mfma_f32_16x16x32_bf16 v[100:103], v[214:217], v[190:193], v[100:103]
	v_mfma_f32_16x16x32_bf16 v[100:103], v[218:221], v[194:197], v[100:103]
	v_mfma_f32_16x16x32_bf16 v[96:99], v[222:225], v[190:193], v[96:99]
	v_mfma_f32_16x16x32_bf16 v[96:99], v[226:229], v[194:197], v[96:99]
	v_mfma_f32_16x16x32_bf16 v[84:87], v[214:217], v[198:201], v[84:87]
	v_mfma_f32_16x16x32_bf16 v[84:87], v[218:221], v[202:205], v[84:87]
	v_mfma_f32_16x16x32_bf16 v[80:83], v[222:225], v[198:201], v[80:83]
	v_mfma_f32_16x16x32_bf16 v[80:83], v[226:229], v[202:205], v[80:83]
	v_mfma_f32_16x16x32_bf16 v[68:71], v[214:217], v[206:209], v[68:71]
	v_mfma_f32_16x16x32_bf16 v[68:71], v[218:221], v[210:213], v[68:71]
	v_mfma_f32_16x16x32_bf16 v[64:67], v[222:225], v[206:209], v[64:67]
	v_mfma_f32_16x16x32_bf16 v[64:67], v[226:229], v[210:213], v[64:67]
	s_setprio 0
	s_mov_b32 m0, s77
	v_lshl_add_u64 v[230:231], v[234:235], 0, s[10:11]
	s_barrier
	ds_read_b128 v[180:183], v153 offset:49152
	ds_read_b128 v[186:189], v153 offset:50176
	ds_read_b128 v[190:193], v153 offset:51200
	ds_read_b128 v[194:197], v153 offset:52224
	ds_read_b128 v[198:201], v153 offset:53248
	ds_read_b128 v[202:205], v153 offset:54272
	ds_read_b128 v[206:209], v153 offset:55296
	ds_read_b128 v[210:213], v153 offset:56320
	global_load_lds_dwordx4 v[230:231], off
	v_lshl_add_u64 v[230:231], v[236:237], 0, s[10:11]
	s_mov_b32 m0, s78
	s_nop 0
	global_load_lds_dwordx4 v[230:231], off
	s_barrier
	s_waitcnt lgkmcnt(0)
	s_setprio 1
	s_waitcnt lgkmcnt(0)
	v_mfma_f32_16x16x32_bf16 v[60:63], v[160:163], v[180:183], v[60:63]
	v_mfma_f32_16x16x32_bf16 v[60:63], v[164:167], v[186:189], v[60:63]
	v_mfma_f32_16x16x32_bf16 v[56:59], v[168:171], v[180:183], v[56:59]
	v_mfma_f32_16x16x32_bf16 v[56:59], v[176:179], v[186:189], v[56:59]
	v_mfma_f32_16x16x32_bf16 v[48:51], v[160:163], v[190:193], v[48:51]
	v_mfma_f32_16x16x32_bf16 v[48:51], v[164:167], v[194:197], v[48:51]
	v_mfma_f32_16x16x32_bf16 v[40:43], v[168:171], v[190:193], v[40:43]
	v_mfma_f32_16x16x32_bf16 v[40:43], v[176:179], v[194:197], v[40:43]
	v_mfma_f32_16x16x32_bf16 v[32:35], v[160:163], v[198:201], v[32:35]
	v_mfma_f32_16x16x32_bf16 v[32:35], v[164:167], v[202:205], v[32:35]
	v_mfma_f32_16x16x32_bf16 v[24:27], v[168:171], v[198:201], v[24:27]
	v_mfma_f32_16x16x32_bf16 v[24:27], v[176:179], v[202:205], v[24:27]
	v_mfma_f32_16x16x32_bf16 v[16:19], v[160:163], v[206:209], v[16:19]
	v_mfma_f32_16x16x32_bf16 v[16:19], v[164:167], v[210:213], v[16:19]
	v_mfma_f32_16x16x32_bf16 v[8:11], v[168:171], v[206:209], v[8:11]
	v_mfma_f32_16x16x32_bf16 v[8:11], v[176:179], v[210:213], v[8:11]
	s_setprio 0
	s_barrier
	s_add_u32 s46, s50, 0x20080
	s_addc_u32 s47, s51, 0
	s_add_i32 s50, s52, s54
	v_lshl_add_u64 v[160:161], s[46:47], 0, v[130:131]
	s_mov_b32 m0, s50
	s_nop 0
	global_load_lds_dwordx4 v[160:161], off
	v_lshl_add_u64 v[160:161], s[46:47], 0, v[134:135]
	s_add_i32 m0, s50, 0x2000
	s_nop 0
	global_load_lds_dwordx4 v[160:161], off
	s_waitcnt vmcnt(6)
	s_barrier
	s_setprio 1
	v_mfma_f32_16x16x32_bf16 v[52:55], v[214:217], v[180:183], v[52:55]
	v_mfma_f32_16x16x32_bf16 v[52:55], v[218:221], v[186:189], v[52:55]
	v_mfma_f32_16x16x32_bf16 v[44:47], v[222:225], v[180:183], v[44:47]
	v_mfma_f32_16x16x32_bf16 v[44:47], v[226:229], v[186:189], v[44:47]
	v_mfma_f32_16x16x32_bf16 v[36:39], v[214:217], v[190:193], v[36:39]
	v_mfma_f32_16x16x32_bf16 v[36:39], v[218:221], v[194:197], v[36:39]
	v_mfma_f32_16x16x32_bf16 v[28:31], v[222:225], v[190:193], v[28:31]
	v_mfma_f32_16x16x32_bf16 v[28:31], v[226:229], v[194:197], v[28:31]
	v_mfma_f32_16x16x32_bf16 v[20:23], v[214:217], v[198:201], v[20:23]
	v_mfma_f32_16x16x32_bf16 v[20:23], v[218:221], v[202:205], v[20:23]
	v_mfma_f32_16x16x32_bf16 v[12:15], v[222:225], v[198:201], v[12:15]
	v_mfma_f32_16x16x32_bf16 v[12:15], v[226:229], v[202:205], v[12:15]
	v_mfma_f32_16x16x32_bf16 v[4:7], v[214:217], v[206:209], v[4:7]
	v_mfma_f32_16x16x32_bf16 v[4:7], v[218:221], v[210:213], v[4:7]
	v_mfma_f32_16x16x32_bf16 v[0:3], v[222:225], v[206:209], v[0:3]
	v_mfma_f32_16x16x32_bf16 v[0:3], v[226:229], v[210:213], v[0:3]
	s_setprio 0
	s_add_i32 s91, s91, 2
	s_add_u32 s63, s63, 0x100
	s_addc_u32 s90, s90, 0
	s_cmp_gt_u32 s91, 5
	s_mov_b64 s[46:47], s[48:49]
	s_barrier
	s_cbranch_scc0 .LBB0_325
	v_lshl_add_u32 v162, s88, 8, v137
	v_lshl_or_b32 v160, s89, 8, v141
	v_ashrrev_i32_e32 v163, 31, v162
	v_ashrrev_i32_e32 v161, 31, v160
	v_lshlrev_b64 v[164:165], 14, v[162:163]
	v_lshl_add_u64 v[164:165], s[56:57], 0, v[164:165]
	v_lshlrev_b64 v[166:167], 1, v[160:161]
	v_lshl_add_u64 v[160:161], v[164:165], 0, v[166:167]
	s_waitcnt vmcnt(0)
	v_pk_mul_f32 v[126:127], v[158:159], v[126:127] op_sel_hi:[0,1]
	v_pk_mul_f32 v[124:125], v[158:159], v[124:125] op_sel_hi:[0,1]
	v_pk_mul_f32 v[164:165], v[158:159], v[122:123] op_sel_hi:[0,1]
	v_pk_mul_f32 v[122:123], v[158:159], v[120:121] op_sel_hi:[0,1]
	v_cvt_pk_bf16_f32 v120, v124, v125
	v_cvt_pk_bf16_f32 v121, v126, v127
	v_cvt_pk_bf16_f32 v122, v122, v123
	v_cvt_pk_bf16_f32 v123, v164, v165
	global_store_dwordx4 v[160:161], v[120:123], off
	v_pk_mul_f32 v[116:117], v[158:159], v[116:117] op_sel_hi:[0,1]
	v_pk_mul_f32 v[118:119], v[158:159], v[118:119] op_sel_hi:[0,1]
	v_pk_mul_f32 v[120:121], v[158:159], v[114:115] op_sel_hi:[0,1]
	v_pk_mul_f32 v[114:115], v[158:159], v[112:113] op_sel_hi:[0,1]
	v_cvt_pk_bf16_f32 v112, v116, v117
	v_cvt_pk_bf16_f32 v113, v118, v119
	v_cvt_pk_bf16_f32 v114, v114, v115
	v_cvt_pk_bf16_f32 v115, v120, v121
	global_store_dwordx4 v[160:161], v[112:115], off offset:256
	v_pk_mul_f32 v[110:111], v[156:157], v[110:111] op_sel_hi:[0,1]
	v_pk_mul_f32 v[108:109], v[156:157], v[108:109] op_sel_hi:[0,1]
	v_or_b32_e32 v112, 16, v162
	v_ashrrev_i32_e32 v113, 31, v112
	v_lshlrev_b64 v[112:113], 14, v[112:113]
	v_lshl_add_u64 v[112:113], s[56:57], 0, v[112:113]
	v_lshl_add_u64 v[112:113], v[112:113], 0, v[166:167]
	v_pk_mul_f32 v[114:115], v[156:157], v[106:107] op_sel_hi:[0,1]
	v_pk_mul_f32 v[106:107], v[156:157], v[104:105] op_sel_hi:[0,1]
	v_cvt_pk_bf16_f32 v104, v108, v109
	v_cvt_pk_bf16_f32 v105, v110, v111
	v_cvt_pk_bf16_f32 v106, v106, v107
	v_cvt_pk_bf16_f32 v107, v114, v115
	global_store_dwordx4 v[112:113], v[104:107], off
	v_pk_mul_f32 v[100:101], v[156:157], v[100:101] op_sel_hi:[0,1]
	v_pk_mul_f32 v[102:103], v[156:157], v[102:103] op_sel_hi:[0,1]
	v_pk_mul_f32 v[104:105], v[156:157], v[98:99] op_sel_hi:[0,1]
	v_pk_mul_f32 v[98:99], v[156:157], v[96:97] op_sel_hi:[0,1]
	v_cvt_pk_bf16_f32 v96, v100, v101
	v_cvt_pk_bf16_f32 v97, v102, v103
	v_cvt_pk_bf16_f32 v98, v98, v99
	v_cvt_pk_bf16_f32 v99, v104, v105
	global_store_dwordx4 v[112:113], v[96:99], off offset:256
	v_pk_mul_f32 v[94:95], v[154:155], v[94:95] op_sel_hi:[0,1]
	v_pk_mul_f32 v[92:93], v[154:155], v[92:93] op_sel_hi:[0,1]
	v_or_b32_e32 v96, 32, v162
	v_ashrrev_i32_e32 v97, 31, v96
	v_lshlrev_b64 v[96:97], 14, v[96:97]
	v_lshl_add_u64 v[96:97], s[56:57], 0, v[96:97]
	v_lshl_add_u64 v[96:97], v[96:97], 0, v[166:167]
	v_pk_mul_f32 v[98:99], v[154:155], v[90:91] op_sel_hi:[0,1]
	v_pk_mul_f32 v[90:91], v[154:155], v[88:89] op_sel_hi:[0,1]
	v_cvt_pk_bf16_f32 v88, v92, v93
	v_cvt_pk_bf16_f32 v89, v94, v95
	v_cvt_pk_bf16_f32 v90, v90, v91
	v_cvt_pk_bf16_f32 v91, v98, v99
	global_store_dwordx4 v[96:97], v[88:91], off
	v_pk_mul_f32 v[84:85], v[154:155], v[84:85] op_sel_hi:[0,1]
	v_pk_mul_f32 v[86:87], v[154:155], v[86:87] op_sel_hi:[0,1]
	v_pk_mul_f32 v[88:89], v[154:155], v[82:83] op_sel_hi:[0,1]
	v_pk_mul_f32 v[82:83], v[154:155], v[80:81] op_sel_hi:[0,1]
	v_cvt_pk_bf16_f32 v80, v84, v85
	v_cvt_pk_bf16_f32 v81, v86, v87
	v_cvt_pk_bf16_f32 v82, v82, v83
	v_cvt_pk_bf16_f32 v83, v88, v89
	global_store_dwordx4 v[96:97], v[80:83], off offset:256
	v_pk_mul_f32 v[78:79], v[152:153], v[78:79] op_sel_hi:[0,1]
	v_pk_mul_f32 v[76:77], v[152:153], v[76:77] op_sel_hi:[0,1]
	v_or_b32_e32 v80, 48, v162
	v_ashrrev_i32_e32 v81, 31, v80
	v_lshlrev_b64 v[80:81], 14, v[80:81]
	v_lshl_add_u64 v[80:81], s[56:57], 0, v[80:81]
	v_lshl_add_u64 v[80:81], v[80:81], 0, v[166:167]
	v_pk_mul_f32 v[82:83], v[152:153], v[74:75] op_sel_hi:[0,1]
	v_pk_mul_f32 v[74:75], v[152:153], v[72:73] op_sel_hi:[0,1]
	v_cvt_pk_bf16_f32 v72, v76, v77
	v_cvt_pk_bf16_f32 v73, v78, v79
	v_cvt_pk_bf16_f32 v74, v74, v75
	v_cvt_pk_bf16_f32 v75, v82, v83
	global_store_dwordx4 v[80:81], v[72:75], off
	v_pk_mul_f32 v[70:71], v[152:153], v[70:71] op_sel_hi:[0,1]
	v_pk_mul_f32 v[68:69], v[152:153], v[68:69] op_sel_hi:[0,1]
	v_pk_mul_f32 v[72:73], v[152:153], v[66:67] op_sel_hi:[0,1]
	v_pk_mul_f32 v[66:67], v[152:153], v[64:65] op_sel_hi:[0,1]
	v_cvt_pk_bf16_f32 v64, v68, v69
	v_cvt_pk_bf16_f32 v65, v70, v71
	v_cvt_pk_bf16_f32 v66, v66, v67
	v_cvt_pk_bf16_f32 v67, v72, v73
	v_pk_mul_f32 v[60:61], v[150:151], v[60:61] op_sel_hi:[0,1]
	global_store_dwordx4 v[80:81], v[64:67], off offset:256
	v_pk_mul_f32 v[62:63], v[150:151], v[62:63] op_sel_hi:[0,1]
	s_mov_b64 s[46:47], 0x200000
	v_pk_mul_f32 v[66:67], v[150:151], v[58:59] op_sel_hi:[0,1]
	v_pk_mul_f32 v[58:59], v[150:151], v[56:57] op_sel_hi:[0,1]
	v_cvt_pk_bf16_f32 v56, v60, v61
	v_add_co_u32_e32 v60, vcc, s83, v160
	v_cvt_pk_bf16_f32 v57, v62, v63
	v_cvt_pk_bf16_f32 v58, v58, v59
	v_cvt_pk_bf16_f32 v59, v66, v67
	v_lshl_add_u64 v[64:65], v[160:161], 0, s[46:47]
	s_nop 0
	v_addc_co_u32_e32 v61, vcc, 0, v161, vcc
	global_store_dwordx4 v[60:61], v[56:59], off
	v_pk_mul_f32 v[54:55], v[150:151], v[54:55] op_sel_hi:[0,1]
	v_pk_mul_f32 v[52:53], v[150:151], v[52:53] op_sel_hi:[0,1]
	v_pk_mul_f32 v[56:57], v[150:151], v[46:47] op_sel_hi:[0,1]
	v_pk_mul_f32 v[46:47], v[150:151], v[44:45] op_sel_hi:[0,1]
	v_cvt_pk_bf16_f32 v44, v52, v53
	v_cvt_pk_bf16_f32 v45, v54, v55
	v_cvt_pk_bf16_f32 v46, v46, v47
	v_cvt_pk_bf16_f32 v47, v56, v57
	global_store_dwordx4 v[64:65], v[44:47], off offset:256
	v_pk_mul_f32 v[48:49], v[140:141], v[48:49] op_sel_hi:[0,1]
	v_pk_mul_f32 v[38:39], v[140:141], v[38:39] op_sel_hi:[0,1]
	v_pk_mul_f32 v[46:47], v[140:141], v[50:51] op_sel_hi:[0,1]
	v_pk_mul_f32 v[50:51], v[140:141], v[42:43] op_sel_hi:[0,1]
	v_pk_mul_f32 v[42:43], v[140:141], v[40:41] op_sel_hi:[0,1]
	v_cvt_pk_bf16_f32 v40, v48, v49
	v_cvt_pk_bf16_f32 v41, v46, v47
	v_add_co_u32_e32 v46, vcc, s84, v160
	v_cvt_pk_bf16_f32 v42, v42, v43
	v_cvt_pk_bf16_f32 v43, v50, v51
	v_lshl_add_u64 v[44:45], v[160:161], 0, s[30:31]
	s_nop 0
	v_addc_co_u32_e32 v47, vcc, 0, v161, vcc
	global_store_dwordx4 v[46:47], v[40:43], off
	v_pk_mul_f32 v[36:37], v[140:141], v[36:37] op_sel_hi:[0,1]
	v_pk_mul_f32 v[32:33], v[138:139], v[32:33] op_sel_hi:[0,1]
	v_pk_mul_f32 v[40:41], v[140:141], v[30:31] op_sel_hi:[0,1]
	v_pk_mul_f32 v[30:31], v[140:141], v[28:29] op_sel_hi:[0,1]
	v_cvt_pk_bf16_f32 v28, v36, v37
	v_cvt_pk_bf16_f32 v29, v38, v39
	v_cvt_pk_bf16_f32 v30, v30, v31
	v_cvt_pk_bf16_f32 v31, v40, v41
	global_store_dwordx4 v[44:45], v[28:31], off offset:256
	v_pk_mul_f32 v[22:23], v[138:139], v[22:23] op_sel_hi:[0,1]
	v_pk_mul_f32 v[20:21], v[138:139], v[20:21] op_sel_hi:[0,1]
	v_pk_mul_f32 v[30:31], v[138:139], v[34:35] op_sel_hi:[0,1]
	v_pk_mul_f32 v[34:35], v[138:139], v[26:27] op_sel_hi:[0,1]
	v_pk_mul_f32 v[26:27], v[138:139], v[24:25] op_sel_hi:[0,1]
	v_cvt_pk_bf16_f32 v24, v32, v33
	v_cvt_pk_bf16_f32 v25, v30, v31
	v_add_co_u32_e32 v30, vcc, s85, v160
	v_cvt_pk_bf16_f32 v26, v26, v27
	v_cvt_pk_bf16_f32 v27, v34, v35
	v_lshl_add_u64 v[28:29], v[160:161], 0, s[36:37]
	s_nop 0
	v_addc_co_u32_e32 v31, vcc, 0, v161, vcc
	global_store_dwordx4 v[30:31], v[24:27], off
	v_pk_mul_f32 v[16:17], v[136:137], v[16:17] op_sel_hi:[0,1]
	s_mov_b64 s[46:47], -1
	v_pk_mul_f32 v[24:25], v[138:139], v[14:15] op_sel_hi:[0,1]
	v_pk_mul_f32 v[14:15], v[138:139], v[12:13] op_sel_hi:[0,1]
	v_cvt_pk_bf16_f32 v12, v20, v21
	v_cvt_pk_bf16_f32 v13, v22, v23
	v_cvt_pk_bf16_f32 v14, v14, v15
	v_cvt_pk_bf16_f32 v15, v24, v25
	global_store_dwordx4 v[28:29], v[12:15], off offset:256
	v_pk_mul_f32 v[6:7], v[136:137], v[6:7] op_sel_hi:[0,1]
	v_pk_mul_f32 v[4:5], v[136:137], v[4:5] op_sel_hi:[0,1]
	v_pk_mul_f32 v[14:15], v[136:137], v[18:19] op_sel_hi:[0,1]
	v_pk_mul_f32 v[18:19], v[136:137], v[10:11] op_sel_hi:[0,1]
	v_pk_mul_f32 v[10:11], v[136:137], v[8:9] op_sel_hi:[0,1]
	v_cvt_pk_bf16_f32 v8, v16, v17
	v_cvt_pk_bf16_f32 v9, v14, v15
	v_add_co_u32_e32 v14, vcc, s86, v160
	v_lshl_add_u64 v[12:13], v[160:161], 0, s[38:39]
	s_nop 0
	v_addc_co_u32_e32 v15, vcc, 0, v161, vcc
	v_cvt_pk_bf16_f32 v10, v10, v11
	v_cvt_pk_bf16_f32 v11, v18, v19
	global_store_dwordx4 v[14:15], v[8:11], off
	s_and_b64 vcc, s[8:9], exec
	s_nop 0
	v_pk_mul_f32 v[8:9], v[136:137], v[2:3] op_sel_hi:[0,1]
	v_pk_mul_f32 v[2:3], v[136:137], v[0:1] op_sel_hi:[0,1]
	v_cvt_pk_bf16_f32 v0, v4, v5
	v_cvt_pk_bf16_f32 v1, v6, v7
	v_cvt_pk_bf16_f32 v2, v2, v3
	v_cvt_pk_bf16_f32 v3, v8, v9
	global_store_dwordx4 v[12:13], v[0:3], off offset:256
	s_cbranch_vccz .LBB0_315
	s_nop 0
	v_lshl_add_u32 v0, s87, 8, v137
	v_ashrrev_i32_e32 v1, 31, v0
	v_lshl_add_u64 v[0:1], v[0:1], 2, s[34:35]
	global_load_dword v158, v[0:1], off
	global_load_dword v156, v[0:1], off offset:64
	global_load_dword v154, v[0:1], off offset:128
	global_load_dword v152, v[0:1], off offset:192
	global_load_dword v150, v[0:1], off offset:512
	global_load_dword v140, v[0:1], off offset:576
	global_load_dword v138, v[0:1], off offset:640
	global_load_dword v136, v[0:1], off offset:704
	s_mov_b64 s[46:47], 0
	s_branch .LBB0_315

.LBB0_394:
	s_sub_i32 s10, s54, 63
	s_cmp_le_i32 s10, s5
	s_cselect_b64 s[76:77], -1, 0
	s_cmp_gt_i32 s10, s5
	s_cbranch_scc1 .LBB0_396
	ds_read_b128 v[236:239], v196 offset:57344
	ds_read_b128 v[240:243], v207 offset:12288
	ds_read_b128 v[246:249], v197 offset:57344
	ds_read_b128 v[250:253], v205 offset:12288
	ds_read_b128 v[6:9], v195
	ds_read_b128 v[10:13], v195 offset:1024
	ds_read_b128 v[2:5], v195 offset:2048
	v_cvt_pk_bf16_f32 v18, v224, v226
	v_cvt_pk_bf16_f32 v19, v222, v225
	v_cvt_pk_bf16_f32 v20, v220, v223
	v_cvt_pk_bf16_f32 v21, v219, v221
	v_cvt_pk_bf16_f32 v22, v216, v218
	v_cvt_pk_bf16_f32 v23, v214, v217
	v_cvt_pk_bf16_f32 v24, v212, v215
	v_cvt_pk_bf16_f32 v25, v211, v213
	v_add_f32_e32 v0, 0, v224
	v_add_f32_e32 v0, v226, v0
	v_add_f32_e32 v0, v222, v0
	v_add_f32_e32 v0, v225, v0
	v_add_f32_e32 v0, v220, v0
	v_add_f32_e32 v0, v223, v0
	v_add_f32_e32 v0, v219, v0
	v_add_f32_e32 v0, v221, v0
	s_waitcnt lgkmcnt(6)
	v_mfma_f32_32x32x16_bf16 v[112:127], v[236:239], v[156:159], 0
	ds_read_b128 v[236:239], v199 offset:57344
	v_add_f32_e32 v0, v216, v0
	v_add_f32_e32 v0, v218, v0
	v_permlane32_swap_b32_e32 v18, v20
	s_waitcnt lgkmcnt(6)
	v_mfma_f32_32x32x16_bf16 v[96:111], v[240:243], v[156:159], 0
	ds_read_b128 v[240:243], v206 offset:12288
	v_add_f32_e32 v0, v214, v0
	v_add_f32_e32 v0, v217, v0
	v_permlane32_swap_b32_e32 v19, v21
	s_waitcnt lgkmcnt(6)
	v_mfma_f32_32x32x16_bf16 v[112:127], v[246:249], v[152:155], v[112:127]
	ds_read_b128 v[246:249], v198 offset:57344
	v_add_f32_e32 v0, v212, v0
	v_add_f32_e32 v0, v215, v0
	s_waitcnt lgkmcnt(6)
	v_mfma_f32_32x32x16_bf16 v[96:111], v[250:253], v[152:155], v[96:111]
	ds_read_b128 v[250:253], v204 offset:12288
	v_permlane32_swap_b32_e32 v22, v24
	v_add_f32_e32 v0, v211, v0
	s_waitcnt lgkmcnt(3)
	v_mfma_f32_32x32x16_bf16 v[112:127], v[236:239], v[148:151], v[112:127]
	ds_read_b128 v[236:239], v196 offset:57472
	v_add_f32_e32 v0, v213, v0
	v_permlane32_swap_b32_e32 v23, v25
	s_waitcnt lgkmcnt(3)
	v_mfma_f32_32x32x16_bf16 v[96:111], v[240:243], v[148:151], v[96:111]
	ds_read_b128 v[240:243], v207 offset:12416
	v_exp_f32_e32 v182, v182
	v_exp_f32_e32 v183, v183
	s_waitcnt lgkmcnt(3)
	v_mfma_f32_32x32x16_bf16 v[112:127], v[246:249], v[144:147], v[112:127]
	ds_read_b128 v[246:249], v197 offset:57472
	v_exp_f32_e32 v180, v180
	v_exp_f32_e32 v181, v181
	s_waitcnt lgkmcnt(3)
	v_mfma_f32_32x32x16_bf16 v[96:111], v[250:253], v[144:147], v[96:111]
	ds_read_b128 v[250:253], v205 offset:12416
	v_add_f32_e32 v0, v182, v0
	v_exp_f32_e32 v170, v170
	s_waitcnt lgkmcnt(3)
	v_mfma_f32_32x32x16_bf16 v[112:127], v[236:239], v[140:143], v[112:127]
	ds_read_b128 v[236:239], v199 offset:57472
	v_add_f32_e32 v0, v183, v0
	v_exp_f32_e32 v171, v171
	s_waitcnt lgkmcnt(3)
	v_mfma_f32_32x32x16_bf16 v[96:111], v[240:243], v[140:143], v[96:111]
	ds_read_b128 v[240:243], v206 offset:12416
	v_add_f32_e32 v0, v180, v0
	v_exp_f32_e32 v168, v168
	s_waitcnt lgkmcnt(3)
	v_mfma_f32_32x32x16_bf16 v[112:127], v[246:249], v[136:139], v[112:127]
	ds_read_b128 v[246:249], v198 offset:57472
	v_add_f32_e32 v0, v181, v0
	v_exp_f32_e32 v169, v169
	s_waitcnt lgkmcnt(3)
	v_mfma_f32_32x32x16_bf16 v[96:111], v[250:253], v[136:139], v[96:111]
	ds_read_b128 v[250:253], v204 offset:12416
	v_cvt_pk_bf16_f32 v26, v182, v183
	v_cvt_pk_bf16_f32 v27, v180, v181
	s_waitcnt lgkmcnt(3)
	v_mfma_f32_32x32x16_bf16 v[112:127], v[236:239], v[132:135], v[112:127]
	ds_read_b128 v[236:239], v196 offset:57600
	v_add_f32_e32 v0, v170, v0
	v_exp_f32_e32 v166, v166
	s_waitcnt lgkmcnt(3)
	v_mfma_f32_32x32x16_bf16 v[96:111], v[240:243], v[132:135], v[96:111]
	ds_read_b128 v[240:243], v207 offset:12544
	v_add_f32_e32 v0, v171, v0
	v_exp_f32_e32 v167, v167
	s_waitcnt lgkmcnt(3)
	v_mfma_f32_32x32x16_bf16 v[112:127], v[246:249], v[128:131], v[112:127]
	ds_read_b128 v[246:249], v197 offset:57600
	v_add_f32_e32 v0, v168, v0
	v_exp_f32_e32 v164, v164
	s_waitcnt lgkmcnt(3)
	v_mfma_f32_32x32x16_bf16 v[96:111], v[250:253], v[128:131], v[96:111]
	ds_read_b128 v[250:253], v205 offset:12544
	v_add_f32_e32 v0, v169, v0
	v_exp_f32_e32 v165, v165
	s_waitcnt lgkmcnt(3)
	v_mfma_f32_32x32x16_bf16 v[112:127], v[236:239], v[6:9], v[112:127]
	ds_read_b128 v[236:239], v199 offset:57600
	v_cvt_pk_bf16_f32 v28, v170, v171
	v_cvt_pk_bf16_f32 v29, v168, v169
	s_waitcnt lgkmcnt(3)
	v_mfma_f32_32x32x16_bf16 v[96:111], v[240:243], v[6:9], v[96:111]
	ds_read_b128 v[240:243], v206 offset:12544
	ds_read_b128 v[6:9], v195 offset:3072
	v_add_f32_e32 v0, v166, v0
	v_exp_f32_e32 v162, v162
	s_waitcnt lgkmcnt(4)
	v_mfma_f32_32x32x16_bf16 v[112:127], v[246:249], v[10:13], v[112:127]
	ds_read_b128 v[246:249], v198 offset:57600
	v_permlane32_swap_b32_e32 v26, v28
	v_permlane32_swap_b32_e32 v27, v29
	s_waitcnt lgkmcnt(4)
	v_mfma_f32_32x32x16_bf16 v[96:111], v[250:253], v[10:13], v[96:111]
	ds_read_b128 v[250:253], v204 offset:12544
	v_add_f32_e32 v0, v167, v0
	v_exp_f32_e32 v163, v163
	s_waitcnt lgkmcnt(4)
	v_mfma_f32_32x32x16_bf16 v[112:127], v[236:239], v[2:5], v[112:127]
	v_add_f32_e32 v0, v164, v0
	v_exp_f32_e32 v160, v160
	s_waitcnt lgkmcnt(3)
	v_mfma_f32_32x32x16_bf16 v[96:111], v[240:243], v[2:5], v[96:111]
	v_add_f32_e32 v0, v165, v0
	v_exp_f32_e32 v161, v161
	s_waitcnt lgkmcnt(1)
	v_mfma_f32_32x32x16_bf16 v[112:127], v[246:249], v[6:9], v[112:127]
	v_cvt_pk_bf16_f32 v168, v166, v167
	v_cvt_pk_bf16_f32 v169, v164, v165
	s_waitcnt lgkmcnt(0)
	v_mfma_f32_32x32x16_bf16 v[96:111], v[250:253], v[6:9], v[96:111]
	v_add_f32_e32 v0, v162, v0
	v_add_f32_e32 v0, v163, v0
	v_add_f32_e32 v0, v160, v0
	v_add_f32_e32 v0, v161, v0
	v_cvt_pk_bf16_f32 v170, v162, v163
	v_cvt_pk_bf16_f32 v171, v160, v161
	v_mov_b32_e32 v14, v0
	s_nop 1
	v_permlane32_swap_b32_e32 v168, v170
	v_permlane32_swap_b32_e32 v169, v171
	v_permlane32_swap_b32_e32 v0, v14
	s_branch .Lattn_h1_join

.Lattn_h1_join:
	s_mov_b32 s10, 0xffe80000
	v_add_co_u32_e32 v6, vcc, s10, v178
	s_mov_b32 s10, 0xfff00000
	s_nop 0
	v_addc_co_u32_e32 v7, vcc, -1, v179, vcc
	v_add_co_u32_e32 v30, vcc, s10, v178
	s_nop 1
	v_addc_co_u32_e32 v31, vcc, -1, v179, vcc
	global_load_dwordx4 v[2:5], v[6:7], off
	s_nop 0
	global_load_dwordx4 v[6:9], v[6:7], off offset:-256
	s_nop 0
	global_load_dwordx4 v[10:13], v[30:31], off
	global_load_dwordx4 v[160:163], v[30:31], off offset:-256
	v_add_co_u32_e32 v30, vcc, 0xffffe000, v176
	s_nop 1
	v_addc_co_u32_e32 v31, vcc, -1, v177, vcc
	global_load_dwordx4 v[164:167], v[30:31], off
	s_add_i32 s10, s54, 0xffffff81
	s_cmp_gt_i32 s10, s5
	s_cbranch_scc1 .LBB0_399
	ds_read_b64_tr_b16 v[180:181], v190 offset:0
	ds_read_b64_tr_b16 v[182:183], v190 offset:0x800
	ds_read_b64_tr_b16 v[212:213], v190 offset:0x1000
	ds_read_b64_tr_b16 v[214:215], v190 offset:0x1800
	ds_read_b64_tr_b16 v[216:217], v190 offset:0x2000
	ds_read_b64_tr_b16 v[218:219], v190 offset:0x2800
	ds_read_b64_tr_b16 v[220:221], v190 offset:0x3000
	ds_read_b64_tr_b16 v[222:223], v190 offset:0x3800
	s_waitcnt lgkmcnt(0)
	s_nop 0
	v_mfma_f32_32x32x16_bf16 v[80:95], v[18:21], v[180:183], v[80:95]
	ds_read_b64_tr_b16 v[180:181], v190 offset:0x200
	ds_read_b64_tr_b16 v[182:183], v190 offset:0xa00
	v_mfma_f32_32x32x16_bf16 v[80:95], v[22:25], v[212:215], v[80:95]
	ds_read_b64_tr_b16 v[212:213], v190 offset:0x1200
	ds_read_b64_tr_b16 v[214:215], v190 offset:0x1a00
	v_mfma_f32_32x32x16_bf16 v[80:95], v[26:29], v[216:219], v[80:95]
	ds_read_b64_tr_b16 v[216:217], v190 offset:0x2200
	ds_read_b64_tr_b16 v[218:219], v190 offset:0x2a00
	v_mfma_f32_32x32x16_bf16 v[80:95], v[168:171], v[220:223], v[80:95]
	ds_read_b64_tr_b16 v[220:221], v190 offset:0x3200
	ds_read_b64_tr_b16 v[222:223], v190 offset:0x3a00
	s_waitcnt lgkmcnt(0)
	v_mfma_f32_32x32x16_bf16 v[64:79], v[18:21], v[180:183], v[64:79]
	ds_read_b64_tr_b16 v[180:181], v190 offset:0x400
	ds_read_b64_tr_b16 v[182:183], v190 offset:0xc00
	v_mfma_f32_32x32x16_bf16 v[64:79], v[22:25], v[212:215], v[64:79]
	ds_read_b64_tr_b16 v[212:213], v190 offset:0x1400
	ds_read_b64_tr_b16 v[214:215], v190 offset:0x1c00
	v_mfma_f32_32x32x16_bf16 v[64:79], v[26:29], v[216:219], v[64:79]
	ds_read_b64_tr_b16 v[216:217], v190 offset:0x2400
	ds_read_b64_tr_b16 v[218:219], v190 offset:0x2c00
	v_mfma_f32_32x32x16_bf16 v[64:79], v[168:171], v[220:223], v[64:79]
	ds_read_b64_tr_b16 v[220:221], v190 offset:0x3400
	ds_read_b64_tr_b16 v[222:223], v190 offset:0x3c00
	s_waitcnt lgkmcnt(0)
	v_mfma_f32_32x32x16_bf16 v[48:63], v[18:21], v[180:183], v[48:63]
	ds_read_b64_tr_b16 v[180:181], v190 offset:0x600
	ds_read_b64_tr_b16 v[182:183], v190 offset:0xe00
	v_mfma_f32_32x32x16_bf16 v[48:63], v[22:25], v[212:215], v[48:63]
	ds_read_b64_tr_b16 v[212:213], v190 offset:0x1600
	ds_read_b64_tr_b16 v[214:215], v190 offset:0x1e00
	v_mfma_f32_32x32x16_bf16 v[48:63], v[26:29], v[216:219], v[48:63]
	ds_read_b64_tr_b16 v[216:217], v190 offset:0x2600
	ds_read_b64_tr_b16 v[218:219], v190 offset:0x2e00
	v_mfma_f32_32x32x16_bf16 v[48:63], v[168:171], v[220:223], v[48:63]
	ds_read_b64_tr_b16 v[220:221], v190 offset:0x3600
	ds_read_b64_tr_b16 v[222:223], v190 offset:0x3e00
	s_waitcnt lgkmcnt(0)
	v_mfma_f32_32x32x16_bf16 v[32:47], v[18:21], v[180:183], v[32:47]
	v_mfma_f32_32x32x16_bf16 v[32:47], v[22:25], v[212:215], v[32:47]
	v_mfma_f32_32x32x16_bf16 v[32:47], v[26:29], v[216:219], v[32:47]
	v_mfma_f32_32x32x16_bf16 v[32:47], v[168:171], v[220:223], v[32:47]

.LBB0_405:
	v_cndmask_b32_e64 v180, v17, v208, s[10:11]
	v_mul_f32_e32 v219, 0xbdd53b94, v180
	v_fmamk_f32 v17, v112, 0x3dd53b94, v219
	v_fmamk_f32 v18, v113, 0x3dd53b94, v219
	v_fmamk_f32 v19, v114, 0x3dd53b94, v219
	v_fmamk_f32 v20, v115, 0x3dd53b94, v219
	v_fmamk_f32 v21, v116, 0x3dd53b94, v219
	v_fmamk_f32 v22, v117, 0x3dd53b94, v219
	v_fmamk_f32 v23, v118, 0x3dd53b94, v219
	v_fmamk_f32 v24, v119, 0x3dd53b94, v219
	v_fmamk_f32 v25, v120, 0x3dd53b94, v219
	v_fmamk_f32 v26, v121, 0x3dd53b94, v219
	v_fmamk_f32 v27, v122, 0x3dd53b94, v219
	v_fmamk_f32 v28, v123, 0x3dd53b94, v219
	v_fmamk_f32 v29, v124, 0x3dd53b94, v219
	v_fmamk_f32 v30, v125, 0x3dd53b94, v219
	v_fmamk_f32 v31, v126, 0x3dd53b94, v219
	v_fmamk_f32 v112, v127, 0x3dd53b94, v219
	v_exp_f32_e32 v216, v17
	v_exp_f32_e32 v218, v18
	v_exp_f32_e32 v214, v19
	v_exp_f32_e32 v217, v20
	v_exp_f32_e32 v212, v21
	v_exp_f32_e32 v215, v22
	v_exp_f32_e32 v211, v23
	v_exp_f32_e32 v213, v24
	v_exp_f32_e32 v182, v25
	v_exp_f32_e32 v208, v26
	v_exp_f32_e32 v171, v27
	v_exp_f32_e32 v183, v28
	v_exp_f32_e32 v169, v29
	v_exp_f32_e32 v181, v30
	v_exp_f32_e32 v168, v31
	v_exp_f32_e32 v170, v112
	v_fmamk_f32 v220, v96, 0x3dd53b94, v219
	v_fmamk_f32 v221, v97, 0x3dd53b94, v219
	v_fmamk_f32 v222, v98, 0x3dd53b94, v219
	v_fmamk_f32 v223, v99, 0x3dd53b94, v219
	v_fmamk_f32 v224, v100, 0x3dd53b94, v219
	v_fmamk_f32 v225, v101, 0x3dd53b94, v219
	v_fmamk_f32 v226, v102, 0x3dd53b94, v219
	v_fmamk_f32 v227, v103, 0x3dd53b94, v219
	v_fmamk_f32 v228, v104, 0x3dd53b94, v219
	v_fmamk_f32 v229, v105, 0x3dd53b94, v219
	v_fmamk_f32 v230, v106, 0x3dd53b94, v219
	v_fmamk_f32 v231, v107, 0x3dd53b94, v219
	v_fmamk_f32 v232, v108, 0x3dd53b94, v219
	v_fmamk_f32 v233, v109, 0x3dd53b94, v219
	v_fmamk_f32 v234, v110, 0x3dd53b94, v219
	v_fmac_f32_e32 v219, 0x3dd53b94, v111
	s_add_i32 s10, s54, 1
	s_waitcnt lgkmcnt(0)
	s_barrier
	s_cmp_gt_i32 s10, s5
	s_cbranch_scc1 .LBB0_407
	ds_read_b128 v[236:239], v196 offset:32768
	ds_read_b128 v[240:243], v196 offset:45056
	ds_read_b128 v[246:249], v197 offset:32768
	ds_read_b128 v[250:253], v197 offset:45056
	ds_read_b128 v[6:9], v195
	ds_read_b128 v[10:13], v195 offset:1024
	ds_read_b128 v[2:5], v195 offset:2048
	v_cvt_pk_bf16_f32 v18, v216, v218
	v_cvt_pk_bf16_f32 v19, v214, v217
	v_cvt_pk_bf16_f32 v20, v212, v215
	v_cvt_pk_bf16_f32 v21, v211, v213
	v_cvt_pk_bf16_f32 v22, v182, v208
	v_cvt_pk_bf16_f32 v23, v171, v183
	v_cvt_pk_bf16_f32 v24, v169, v181
	v_cvt_pk_bf16_f32 v25, v168, v170
	v_add_f32_e32 v17, 0, v216
	v_add_f32_e32 v17, v218, v17
	v_add_f32_e32 v17, v214, v17
	v_add_f32_e32 v17, v217, v17
	v_add_f32_e32 v17, v212, v17
	v_add_f32_e32 v17, v215, v17
	v_add_f32_e32 v17, v211, v17
	v_add_f32_e32 v17, v213, v17
	s_waitcnt lgkmcnt(6)
	v_mfma_f32_32x32x16_bf16 v[112:127], v[236:239], v[156:159], 0
	ds_read_b128 v[236:239], v199 offset:32768
	v_add_f32_e32 v17, v182, v17
	v_add_f32_e32 v17, v208, v17
	v_permlane32_swap_b32_e32 v18, v20
	s_waitcnt lgkmcnt(6)
	v_mfma_f32_32x32x16_bf16 v[96:111], v[240:243], v[156:159], 0
	ds_read_b128 v[240:243], v199 offset:45056
	v_add_f32_e32 v17, v171, v17
	v_add_f32_e32 v17, v183, v17
	v_permlane32_swap_b32_e32 v19, v21
	s_waitcnt lgkmcnt(6)
	v_mfma_f32_32x32x16_bf16 v[112:127], v[246:249], v[152:155], v[112:127]
	ds_read_b128 v[246:249], v198 offset:32768
	v_add_f32_e32 v17, v169, v17
	v_add_f32_e32 v17, v181, v17
	s_waitcnt lgkmcnt(6)
	v_mfma_f32_32x32x16_bf16 v[96:111], v[250:253], v[152:155], v[96:111]
	ds_read_b128 v[250:253], v198 offset:45056
	v_permlane32_swap_b32_e32 v22, v24
	v_add_f32_e32 v17, v168, v17
	s_waitcnt lgkmcnt(3)
	v_mfma_f32_32x32x16_bf16 v[112:127], v[236:239], v[148:151], v[112:127]
	ds_read_b128 v[236:239], v196 offset:32896
	v_add_f32_e32 v17, v170, v17
	v_permlane32_swap_b32_e32 v23, v25
	s_waitcnt lgkmcnt(3)
	v_mfma_f32_32x32x16_bf16 v[96:111], v[240:243], v[148:151], v[96:111]
	ds_read_b128 v[240:243], v196 offset:45184
	v_exp_f32_e32 v220, v220
	v_exp_f32_e32 v221, v221
	s_waitcnt lgkmcnt(3)
	v_mfma_f32_32x32x16_bf16 v[112:127], v[246:249], v[144:147], v[112:127]
	ds_read_b128 v[246:249], v197 offset:32896
	v_exp_f32_e32 v222, v222
	v_exp_f32_e32 v223, v223
	s_waitcnt lgkmcnt(3)
	v_mfma_f32_32x32x16_bf16 v[96:111], v[250:253], v[144:147], v[96:111]
	ds_read_b128 v[250:253], v197 offset:45184
	v_add_f32_e32 v17, v220, v17
	v_exp_f32_e32 v224, v224
	s_waitcnt lgkmcnt(3)
	v_mfma_f32_32x32x16_bf16 v[112:127], v[236:239], v[140:143], v[112:127]
	ds_read_b128 v[236:239], v199 offset:32896
	v_add_f32_e32 v17, v221, v17
	v_exp_f32_e32 v225, v225
	s_waitcnt lgkmcnt(3)
	v_mfma_f32_32x32x16_bf16 v[96:111], v[240:243], v[140:143], v[96:111]
	ds_read_b128 v[240:243], v199 offset:45184
	v_add_f32_e32 v17, v222, v17
	v_exp_f32_e32 v226, v226
	s_waitcnt lgkmcnt(3)
	v_mfma_f32_32x32x16_bf16 v[112:127], v[246:249], v[136:139], v[112:127]
	ds_read_b128 v[246:249], v198 offset:32896
	v_add_f32_e32 v17, v223, v17
	v_exp_f32_e32 v227, v227
	s_waitcnt lgkmcnt(3)
	v_mfma_f32_32x32x16_bf16 v[96:111], v[250:253], v[136:139], v[96:111]
	ds_read_b128 v[250:253], v198 offset:45184
	v_cvt_pk_bf16_f32 v26, v220, v221
	v_cvt_pk_bf16_f32 v27, v222, v223
	s_waitcnt lgkmcnt(3)
	v_mfma_f32_32x32x16_bf16 v[112:127], v[236:239], v[132:135], v[112:127]
	ds_read_b128 v[236:239], v196 offset:33024
	v_add_f32_e32 v17, v224, v17
	v_exp_f32_e32 v228, v228
	s_waitcnt lgkmcnt(3)
	v_mfma_f32_32x32x16_bf16 v[96:111], v[240:243], v[132:135], v[96:111]
	ds_read_b128 v[240:243], v196 offset:45312
	v_add_f32_e32 v17, v225, v17
	v_exp_f32_e32 v229, v229
	s_waitcnt lgkmcnt(3)
	v_mfma_f32_32x32x16_bf16 v[112:127], v[246:249], v[128:131], v[112:127]
	ds_read_b128 v[246:249], v197 offset:33024
	v_add_f32_e32 v17, v226, v17
	v_exp_f32_e32 v230, v230
	s_waitcnt lgkmcnt(3)
	v_mfma_f32_32x32x16_bf16 v[96:111], v[250:253], v[128:131], v[96:111]
	ds_read_b128 v[250:253], v197 offset:45312
	v_add_f32_e32 v17, v227, v17
	v_exp_f32_e32 v231, v231
	s_waitcnt lgkmcnt(3)
	v_mfma_f32_32x32x16_bf16 v[112:127], v[236:239], v[6:9], v[112:127]
	ds_read_b128 v[236:239], v199 offset:33024
	v_cvt_pk_bf16_f32 v28, v224, v225
	v_cvt_pk_bf16_f32 v29, v226, v227
	s_waitcnt lgkmcnt(3)
	v_mfma_f32_32x32x16_bf16 v[96:111], v[240:243], v[6:9], v[96:111]
	ds_read_b128 v[240:243], v199 offset:45312
	ds_read_b128 v[6:9], v195 offset:3072
	v_add_f32_e32 v17, v228, v17
	v_exp_f32_e32 v232, v232
	s_waitcnt lgkmcnt(4)
	v_mfma_f32_32x32x16_bf16 v[112:127], v[246:249], v[10:13], v[112:127]
	ds_read_b128 v[246:249], v198 offset:33024
	v_permlane32_swap_b32_e32 v26, v28
	v_permlane32_swap_b32_e32 v27, v29
	s_waitcnt lgkmcnt(4)
	v_mfma_f32_32x32x16_bf16 v[96:111], v[250:253], v[10:13], v[96:111]
	ds_read_b128 v[250:253], v198 offset:45312
	v_add_f32_e32 v17, v229, v17
	v_exp_f32_e32 v233, v233
	s_waitcnt lgkmcnt(4)
	v_mfma_f32_32x32x16_bf16 v[112:127], v[236:239], v[2:5], v[112:127]
	v_add_f32_e32 v17, v230, v17
	v_exp_f32_e32 v234, v234
	s_waitcnt lgkmcnt(3)
	v_mfma_f32_32x32x16_bf16 v[96:111], v[240:243], v[2:5], v[96:111]
	v_add_f32_e32 v17, v231, v17
	v_exp_f32_e32 v219, v219
	s_waitcnt lgkmcnt(1)
	v_mfma_f32_32x32x16_bf16 v[112:127], v[246:249], v[6:9], v[112:127]
	v_cvt_pk_bf16_f32 v168, v228, v229
	v_cvt_pk_bf16_f32 v169, v230, v231
	s_waitcnt lgkmcnt(0)
	v_mfma_f32_32x32x16_bf16 v[96:111], v[250:253], v[6:9], v[96:111]
	v_add_f32_e32 v17, v232, v17
	v_add_f32_e32 v17, v233, v17
	v_add_f32_e32 v17, v234, v17
	v_add_f32_e32 v17, v219, v17
	v_cvt_pk_bf16_f32 v170, v232, v233
	v_cvt_pk_bf16_f32 v171, v234, v219
	v_mov_b32_e32 v30, v17
	s_nop 1
	v_permlane32_swap_b32_e32 v168, v170
	v_permlane32_swap_b32_e32 v169, v171
	v_permlane32_swap_b32_e32 v17, v30
	s_branch .Lattn_h2_join

.Lattn_h2_join:
	s_add_i32 s7, s7, 2
	s_cmp_le_i32 s7, s6
	s_cselect_b64 s[78:79], -1, 0
	s_cmp_gt_i32 s7, s6
	s_cbranch_scc0 .LBB0_417
	s_andn2_b64 vcc, exec, s[76:77]
	s_cbranch_vccz .LBB0_418

.LBB0_514:
	ds_read_b128 v[128:131], v171
	ds_read_b128 v[132:135], v171 offset:1024
	ds_read_b128 v[136:139], v171 offset:2048
	ds_read_b128 v[140:143], v171 offset:3072
	s_add_u32 s40, s38, 0xfff00080
	s_addc_u32 s41, s39, -1
	s_cmp_eq_u32 s61, 60
	s_cselect_b32 s43, s6, s41
	s_cselect_b32 s42, s7, s40
	s_cselect_b32 s41, s25, s55
	s_cselect_b32 s40, s27, s35
	v_lshl_add_u64 v[202:203], s[38:39], 0, v[152:153]
	s_add_i32 m0, s37, 0xc000
	ds_read_b128 v[160:163], v173
	ds_read_b128 v[164:167], v173 offset:1024
	ds_read_b128 v[176:179], v173 offset:2048
	ds_read_b128 v[180:183], v173 offset:3072
	ds_read_b128 v[186:189], v173 offset:4096
	ds_read_b128 v[190:193], v173 offset:5120
	ds_read_b128 v[194:197], v173 offset:6144
	ds_read_b128 v[198:201], v173 offset:7168
	global_load_lds_dwordx4 v[202:203], off
	v_lshl_add_u64 v[202:203], s[38:39], 0, v[154:155]
	s_add_i32 m0, s37, 0xe000
	s_nop 0
	global_load_lds_dwordx4 v[202:203], off
	s_waitcnt lgkmcnt(8)
	s_barrier
	s_waitcnt lgkmcnt(0)
	s_setprio 1
	s_waitcnt lgkmcnt(0)
	v_mfma_f32_16x16x32_bf16 v[124:127], v[128:131], v[160:163], v[124:127]
	v_mfma_f32_16x16x32_bf16 v[124:127], v[132:135], v[164:167], v[124:127]
	v_mfma_f32_16x16x32_bf16 v[120:123], v[136:139], v[160:163], v[120:123]
	v_mfma_f32_16x16x32_bf16 v[120:123], v[140:143], v[164:167], v[120:123]
	v_mfma_f32_16x16x32_bf16 v[108:111], v[128:131], v[176:179], v[108:111]
	v_mfma_f32_16x16x32_bf16 v[108:111], v[132:135], v[180:183], v[108:111]
	v_mfma_f32_16x16x32_bf16 v[104:107], v[136:139], v[176:179], v[104:107]
	v_mfma_f32_16x16x32_bf16 v[104:107], v[140:143], v[180:183], v[104:107]
	v_mfma_f32_16x16x32_bf16 v[92:95], v[128:131], v[186:189], v[92:95]
	v_mfma_f32_16x16x32_bf16 v[92:95], v[132:135], v[190:193], v[92:95]
	v_mfma_f32_16x16x32_bf16 v[88:91], v[136:139], v[186:189], v[88:91]
	v_mfma_f32_16x16x32_bf16 v[88:91], v[140:143], v[190:193], v[88:91]
	v_mfma_f32_16x16x32_bf16 v[76:79], v[128:131], v[194:197], v[76:79]
	v_mfma_f32_16x16x32_bf16 v[76:79], v[132:135], v[198:201], v[76:79]
	v_mfma_f32_16x16x32_bf16 v[72:75], v[136:139], v[194:197], v[72:75]
	v_mfma_f32_16x16x32_bf16 v[72:75], v[140:143], v[198:201], v[72:75]
	s_setprio 0
	s_barrier
	s_add_i32 s62, s53, s5
	v_lshl_add_u64 v[218:219], s[40:41], 0, v[146:147]
	s_mov_b32 m0, s62
	ds_read_b128 v[202:205], v174
	ds_read_b128 v[206:209], v174 offset:1024
	ds_read_b128 v[210:213], v174 offset:2048
	ds_read_b128 v[214:217], v174 offset:3072
	global_load_lds_dwordx4 v[218:219], off
	v_lshl_add_u64 v[220:221], s[40:41], 0, v[150:151]
	s_add_i32 m0, s62, 0x2000
	s_nop 0
	global_load_lds_dwordx4 v[220:221], off
	s_barrier
	s_waitcnt lgkmcnt(0)
	s_setprio 1
	s_waitcnt lgkmcnt(0)
	v_mfma_f32_16x16x32_bf16 v[116:119], v[202:205], v[160:163], v[116:119]
	v_mfma_f32_16x16x32_bf16 v[116:119], v[206:209], v[164:167], v[116:119]
	v_mfma_f32_16x16x32_bf16 v[112:115], v[210:213], v[160:163], v[112:115]
	v_mfma_f32_16x16x32_bf16 v[112:115], v[214:217], v[164:167], v[112:115]
	v_mfma_f32_16x16x32_bf16 v[100:103], v[202:205], v[176:179], v[100:103]
	v_mfma_f32_16x16x32_bf16 v[100:103], v[206:209], v[180:183], v[100:103]
	v_mfma_f32_16x16x32_bf16 v[96:99], v[210:213], v[176:179], v[96:99]
	v_mfma_f32_16x16x32_bf16 v[96:99], v[214:217], v[180:183], v[96:99]
	v_mfma_f32_16x16x32_bf16 v[84:87], v[202:205], v[186:189], v[84:87]
	v_mfma_f32_16x16x32_bf16 v[84:87], v[206:209], v[190:193], v[84:87]
	v_mfma_f32_16x16x32_bf16 v[80:83], v[210:213], v[186:189], v[80:83]
	v_mfma_f32_16x16x32_bf16 v[80:83], v[214:217], v[190:193], v[80:83]
	v_mfma_f32_16x16x32_bf16 v[68:71], v[202:205], v[194:197], v[68:71]
	v_mfma_f32_16x16x32_bf16 v[68:71], v[206:209], v[198:201], v[68:71]
	v_mfma_f32_16x16x32_bf16 v[64:67], v[210:213], v[194:197], v[64:67]
	v_mfma_f32_16x16x32_bf16 v[64:67], v[214:217], v[198:201], v[64:67]
	s_setprio 0
	s_mov_b32 m0, s37
	v_lshl_add_u64 v[222:223], s[42:43], 0, v[144:145]
	s_barrier
	ds_read_b128 v[160:163], v173 offset:16384
	ds_read_b128 v[164:167], v173 offset:17408
	ds_read_b128 v[176:179], v173 offset:18432
	ds_read_b128 v[180:183], v173 offset:19456
	ds_read_b128 v[186:189], v173 offset:20480
	ds_read_b128 v[190:193], v173 offset:21504
	ds_read_b128 v[194:197], v173 offset:22528
	ds_read_b128 v[198:201], v173 offset:23552
	global_load_lds_dwordx4 v[222:223], off
	v_lshl_add_u64 v[224:225], s[42:43], 0, v[148:149]
	s_mov_b32 m0, s44
	s_nop 0
	global_load_lds_dwordx4 v[224:225], off
	s_barrier
	s_waitcnt lgkmcnt(0)
	s_setprio 1
	s_waitcnt lgkmcnt(0)
	v_mfma_f32_16x16x32_bf16 v[60:63], v[128:131], v[160:163], v[60:63]
	v_mfma_f32_16x16x32_bf16 v[60:63], v[132:135], v[164:167], v[60:63]
	v_mfma_f32_16x16x32_bf16 v[56:59], v[136:139], v[160:163], v[56:59]
	v_mfma_f32_16x16x32_bf16 v[56:59], v[140:143], v[164:167], v[56:59]
	v_mfma_f32_16x16x32_bf16 v[44:47], v[128:131], v[176:179], v[44:47]
	v_mfma_f32_16x16x32_bf16 v[44:47], v[132:135], v[180:183], v[44:47]
	v_mfma_f32_16x16x32_bf16 v[40:43], v[136:139], v[176:179], v[40:43]
	v_mfma_f32_16x16x32_bf16 v[40:43], v[140:143], v[180:183], v[40:43]
	v_mfma_f32_16x16x32_bf16 v[28:31], v[128:131], v[186:189], v[28:31]
	v_mfma_f32_16x16x32_bf16 v[28:31], v[132:135], v[190:193], v[28:31]
	v_mfma_f32_16x16x32_bf16 v[24:27], v[136:139], v[186:189], v[24:27]
	v_mfma_f32_16x16x32_bf16 v[24:27], v[140:143], v[190:193], v[24:27]
	v_mfma_f32_16x16x32_bf16 v[12:15], v[128:131], v[194:197], v[12:15]
	v_mfma_f32_16x16x32_bf16 v[12:15], v[132:135], v[198:201], v[12:15]
	v_mfma_f32_16x16x32_bf16 v[8:11], v[136:139], v[194:197], v[8:11]
	v_mfma_f32_16x16x32_bf16 v[8:11], v[140:143], v[198:201], v[8:11]
	s_setprio 0
	s_barrier
	s_add_u32 s62, s40, 0x100000
	s_addc_u32 s63, s41, 0
	s_add_i32 s74, s54, s5
	v_lshl_add_u64 v[128:129], s[62:63], 0, v[146:147]
	s_mov_b32 m0, s74
	s_nop 0
	global_load_lds_dwordx4 v[128:129], off
	v_lshl_add_u64 v[128:129], s[62:63], 0, v[150:151]
	s_add_i32 m0, s74, 0x2000
	s_nop 0
	global_load_lds_dwordx4 v[128:129], off
	s_waitcnt vmcnt(6)
	s_barrier
	s_setprio 1
	v_mfma_f32_16x16x32_bf16 v[52:55], v[202:205], v[160:163], v[52:55]
	v_mfma_f32_16x16x32_bf16 v[52:55], v[206:209], v[164:167], v[52:55]
	v_mfma_f32_16x16x32_bf16 v[48:51], v[210:213], v[160:163], v[48:51]
	v_mfma_f32_16x16x32_bf16 v[48:51], v[214:217], v[164:167], v[48:51]
	v_mfma_f32_16x16x32_bf16 v[36:39], v[202:205], v[176:179], v[36:39]
	v_mfma_f32_16x16x32_bf16 v[36:39], v[206:209], v[180:183], v[36:39]
	v_mfma_f32_16x16x32_bf16 v[32:35], v[210:213], v[176:179], v[32:35]
	v_mfma_f32_16x16x32_bf16 v[32:35], v[214:217], v[180:183], v[32:35]
	v_mfma_f32_16x16x32_bf16 v[20:23], v[202:205], v[186:189], v[20:23]
	v_mfma_f32_16x16x32_bf16 v[20:23], v[206:209], v[190:193], v[20:23]
	v_mfma_f32_16x16x32_bf16 v[16:19], v[210:213], v[186:189], v[16:19]
	v_mfma_f32_16x16x32_bf16 v[16:19], v[214:217], v[190:193], v[16:19]
	v_mfma_f32_16x16x32_bf16 v[4:7], v[202:205], v[194:197], v[4:7]
	v_mfma_f32_16x16x32_bf16 v[4:7], v[206:209], v[198:201], v[4:7]
	v_mfma_f32_16x16x32_bf16 v[0:3], v[210:213], v[194:197], v[0:3]
	v_mfma_f32_16x16x32_bf16 v[0:3], v[214:217], v[198:201], v[0:3]
	s_setprio 0
	s_add_i32 s62, 0, 0x18000
	v_add_u32_e32 v140, s62, v169
	s_barrier
	ds_read_b128 v[128:131], v140
	ds_read_b128 v[132:135], v140 offset:1024
	ds_read_b128 v[136:139], v140 offset:2048
	ds_read_b128 v[140:143], v140 offset:3072
	s_add_u32 s42, s42, 0x100000
	s_addc_u32 s43, s43, 0
	s_mov_b32 m0, s45
	v_lshl_add_u64 v[202:203], s[42:43], 0, v[144:145]
	ds_read_b128 v[160:163], v173 offset:32768
	ds_read_b128 v[164:167], v173 offset:33792
	ds_read_b128 v[176:179], v173 offset:34816
	ds_read_b128 v[180:183], v173 offset:35840
	ds_read_b128 v[186:189], v173 offset:36864
	ds_read_b128 v[190:193], v173 offset:37888
	ds_read_b128 v[194:197], v173 offset:38912
	ds_read_b128 v[198:201], v173 offset:39936
	global_load_lds_dwordx4 v[202:203], off
	v_lshl_add_u64 v[202:203], s[42:43], 0, v[148:149]
	s_mov_b32 m0, s46
	s_nop 0
	global_load_lds_dwordx4 v[202:203], off
	s_waitcnt lgkmcnt(8)
	s_barrier
	s_waitcnt lgkmcnt(0)
	s_setprio 1
	s_waitcnt lgkmcnt(0)
	v_mfma_f32_16x16x32_bf16 v[124:127], v[128:131], v[160:163], v[124:127]
	v_mfma_f32_16x16x32_bf16 v[124:127], v[132:135], v[164:167], v[124:127]
	v_mfma_f32_16x16x32_bf16 v[120:123], v[136:139], v[160:163], v[120:123]
	v_mfma_f32_16x16x32_bf16 v[120:123], v[140:143], v[164:167], v[120:123]
	v_mfma_f32_16x16x32_bf16 v[108:111], v[128:131], v[176:179], v[108:111]
	v_mfma_f32_16x16x32_bf16 v[108:111], v[132:135], v[180:183], v[108:111]
	v_mfma_f32_16x16x32_bf16 v[104:107], v[136:139], v[176:179], v[104:107]
	v_mfma_f32_16x16x32_bf16 v[104:107], v[140:143], v[180:183], v[104:107]
	v_mfma_f32_16x16x32_bf16 v[92:95], v[128:131], v[186:189], v[92:95]
	v_mfma_f32_16x16x32_bf16 v[92:95], v[132:135], v[190:193], v[92:95]
	v_mfma_f32_16x16x32_bf16 v[88:91], v[136:139], v[186:189], v[88:91]
	v_mfma_f32_16x16x32_bf16 v[88:91], v[140:143], v[190:193], v[88:91]
	v_mfma_f32_16x16x32_bf16 v[76:79], v[128:131], v[194:197], v[76:79]
	v_mfma_f32_16x16x32_bf16 v[76:79], v[132:135], v[198:201], v[76:79]
	v_mfma_f32_16x16x32_bf16 v[72:75], v[136:139], v[194:197], v[72:75]
	v_mfma_f32_16x16x32_bf16 v[72:75], v[140:143], v[198:201], v[72:75]
	s_setprio 0
	s_barrier
	s_add_i32 s42, 0, 0x1c000
	s_add_i32 s43, s62, s5
	v_add_u32_e32 v185, s42, v169
	v_lshl_add_u64 v[218:219], v[218:219], 0, s[22:23]
	s_mov_b32 m0, s43
	ds_read_b128 v[202:205], v185
	ds_read_b128 v[206:209], v185 offset:1024
	ds_read_b128 v[210:213], v185 offset:2048
	ds_read_b128 v[214:217], v185 offset:3072
	global_load_lds_dwordx4 v[218:219], off
	v_lshl_add_u64 v[218:219], v[220:221], 0, s[22:23]
	s_add_i32 m0, s43, 0x2000
	s_nop 0
	global_load_lds_dwordx4 v[218:219], off
	s_barrier
	s_waitcnt lgkmcnt(0)
	s_setprio 1
	s_waitcnt lgkmcnt(0)
	v_mfma_f32_16x16x32_bf16 v[116:119], v[202:205], v[160:163], v[116:119]
	v_mfma_f32_16x16x32_bf16 v[116:119], v[206:209], v[164:167], v[116:119]
	v_mfma_f32_16x16x32_bf16 v[112:115], v[210:213], v[160:163], v[112:115]
	v_mfma_f32_16x16x32_bf16 v[112:115], v[214:217], v[164:167], v[112:115]
	v_mfma_f32_16x16x32_bf16 v[100:103], v[202:205], v[176:179], v[100:103]
	v_mfma_f32_16x16x32_bf16 v[100:103], v[206:209], v[180:183], v[100:103]
	v_mfma_f32_16x16x32_bf16 v[96:99], v[210:213], v[176:179], v[96:99]
	v_mfma_f32_16x16x32_bf16 v[96:99], v[214:217], v[180:183], v[96:99]
	v_mfma_f32_16x16x32_bf16 v[84:87], v[202:205], v[186:189], v[84:87]
	v_mfma_f32_16x16x32_bf16 v[84:87], v[206:209], v[190:193], v[84:87]
	v_mfma_f32_16x16x32_bf16 v[80:83], v[210:213], v[186:189], v[80:83]
	v_mfma_f32_16x16x32_bf16 v[80:83], v[214:217], v[190:193], v[80:83]
	v_mfma_f32_16x16x32_bf16 v[68:71], v[202:205], v[194:197], v[68:71]
	v_mfma_f32_16x16x32_bf16 v[68:71], v[206:209], v[198:201], v[68:71]
	v_mfma_f32_16x16x32_bf16 v[64:67], v[210:213], v[194:197], v[64:67]
	v_mfma_f32_16x16x32_bf16 v[64:67], v[214:217], v[198:201], v[64:67]
	s_setprio 0
	s_mov_b32 m0, s48
	v_lshl_add_u64 v[218:219], v[222:223], 0, s[22:23]
	s_barrier
	ds_read_b128 v[160:163], v173 offset:49152
	ds_read_b128 v[164:167], v173 offset:50176
	ds_read_b128 v[176:179], v173 offset:51200
	ds_read_b128 v[180:183], v173 offset:52224
	ds_read_b128 v[186:189], v173 offset:53248
	ds_read_b128 v[190:193], v173 offset:54272
	ds_read_b128 v[194:197], v173 offset:55296
	ds_read_b128 v[198:201], v173 offset:56320
	global_load_lds_dwordx4 v[218:219], off
	v_lshl_add_u64 v[218:219], v[224:225], 0, s[22:23]
	s_mov_b32 m0, s49
	s_nop 0
	global_load_lds_dwordx4 v[218:219], off
	s_barrier
	s_waitcnt lgkmcnt(0)
	s_setprio 1
	s_waitcnt lgkmcnt(0)
	v_mfma_f32_16x16x32_bf16 v[60:63], v[128:131], v[160:163], v[60:63]
	v_mfma_f32_16x16x32_bf16 v[60:63], v[132:135], v[164:167], v[60:63]
	v_mfma_f32_16x16x32_bf16 v[56:59], v[136:139], v[160:163], v[56:59]
	v_mfma_f32_16x16x32_bf16 v[56:59], v[140:143], v[164:167], v[56:59]
	v_mfma_f32_16x16x32_bf16 v[44:47], v[128:131], v[176:179], v[44:47]
	v_mfma_f32_16x16x32_bf16 v[44:47], v[132:135], v[180:183], v[44:47]
	v_mfma_f32_16x16x32_bf16 v[40:43], v[136:139], v[176:179], v[40:43]
	v_mfma_f32_16x16x32_bf16 v[40:43], v[140:143], v[180:183], v[40:43]
	v_mfma_f32_16x16x32_bf16 v[28:31], v[128:131], v[186:189], v[28:31]
	v_mfma_f32_16x16x32_bf16 v[28:31], v[132:135], v[190:193], v[28:31]
	v_mfma_f32_16x16x32_bf16 v[24:27], v[136:139], v[186:189], v[24:27]
	v_mfma_f32_16x16x32_bf16 v[24:27], v[140:143], v[190:193], v[24:27]
	v_mfma_f32_16x16x32_bf16 v[12:15], v[128:131], v[194:197], v[12:15]
	v_mfma_f32_16x16x32_bf16 v[12:15], v[132:135], v[198:201], v[12:15]
	v_mfma_f32_16x16x32_bf16 v[8:11], v[136:139], v[194:197], v[8:11]
	v_mfma_f32_16x16x32_bf16 v[8:11], v[140:143], v[198:201], v[8:11]
	s_setprio 0
	s_barrier
	s_add_u32 s40, s40, 0x100080
	s_addc_u32 s41, s41, 0
	s_add_i32 s42, s42, s5
	v_lshl_add_u64 v[128:129], s[40:41], 0, v[146:147]
	s_mov_b32 m0, s42
	s_nop 0
	global_load_lds_dwordx4 v[128:129], off
	v_lshl_add_u64 v[128:129], s[40:41], 0, v[150:151]
	s_add_i32 m0, s42, 0x2000
	s_nop 0
	global_load_lds_dwordx4 v[128:129], off
	s_waitcnt vmcnt(6)
	s_barrier
	s_setprio 1
	v_mfma_f32_16x16x32_bf16 v[52:55], v[202:205], v[160:163], v[52:55]
	v_mfma_f32_16x16x32_bf16 v[52:55], v[206:209], v[164:167], v[52:55]
	v_mfma_f32_16x16x32_bf16 v[48:51], v[210:213], v[160:163], v[48:51]
	v_mfma_f32_16x16x32_bf16 v[48:51], v[214:217], v[164:167], v[48:51]
	v_mfma_f32_16x16x32_bf16 v[36:39], v[202:205], v[176:179], v[36:39]
	v_mfma_f32_16x16x32_bf16 v[36:39], v[206:209], v[180:183], v[36:39]
	v_mfma_f32_16x16x32_bf16 v[32:35], v[210:213], v[176:179], v[32:35]
	v_mfma_f32_16x16x32_bf16 v[32:35], v[214:217], v[180:183], v[32:35]
	v_mfma_f32_16x16x32_bf16 v[20:23], v[202:205], v[186:189], v[20:23]
	v_mfma_f32_16x16x32_bf16 v[20:23], v[206:209], v[190:193], v[20:23]
	v_mfma_f32_16x16x32_bf16 v[16:19], v[210:213], v[186:189], v[16:19]
	v_mfma_f32_16x16x32_bf16 v[16:19], v[214:217], v[190:193], v[16:19]
	v_mfma_f32_16x16x32_bf16 v[4:7], v[202:205], v[194:197], v[4:7]
	v_mfma_f32_16x16x32_bf16 v[4:7], v[206:209], v[198:201], v[4:7]
	v_mfma_f32_16x16x32_bf16 v[0:3], v[210:213], v[194:197], v[0:3]
	v_mfma_f32_16x16x32_bf16 v[0:3], v[214:217], v[198:201], v[0:3]
	s_setprio 0
	s_add_i32 s61, s61, 2
	s_add_u32 s38, s38, 0x100
	s_addc_u32 s39, s39, 0
	s_add_u32 s35, s35, 0x100
	s_addc_u32 s55, s55, 0
	s_cmp_gt_u32 s61, 61
	s_barrier
	s_cbranch_scc0 .LBB0_514
	v_lshl_add_u32 v162, s34, 8, v168
	v_lshl_or_b32 v160, s36, 8, v170
	v_ashrrev_i32_e32 v163, 31, v162
	v_ashrrev_i32_e32 v161, 31, v160
	v_lshlrev_b64 v[128:129], 14, v[162:163]
	v_lshl_add_u64 v[128:129], s[12:13], 0, v[128:129]
	v_lshlrev_b64 v[130:131], 2, v[160:161]
	v_lshl_add_u64 v[128:129], v[128:129], 0, v[130:131]
	global_load_dwordx4 v[178:181], v[128:129], off
	global_load_dwordx4 v[186:189], v[128:129], off offset:16
	global_load_dwordx4 v[190:193], v[128:129], off offset:512
	global_load_dwordx4 v[194:197], v[128:129], off offset:528
	v_or_b32_e32 v164, 16, v162
	v_ashrrev_i32_e32 v165, 31, v164
	v_lshlrev_b64 v[128:129], 14, v[164:165]
	v_lshl_add_u64 v[128:129], s[12:13], 0, v[128:129]
	v_lshl_add_u64 v[132:133], v[128:129], 0, v[130:131]
	global_load_dwordx4 v[136:139], v[132:133], off offset:16
	global_load_dwordx4 v[140:143], v[132:133], off
	global_load_dwordx4 v[128:131], v[132:133], off offset:528
	s_nop 0
	global_load_dwordx4 v[132:135], v[132:133], off offset:512
	v_and_b32_e32 v166, 64, v175
	v_xor_b32_e32 v176, 16, v175
	v_add_u32_e32 v182, 64, v166
	v_xor_b32_e32 v177, 32, v175
	v_cmp_lt_i32_e32 vcc, v176, v182
	v_lshlrev_b64 v[166:167], 13, v[162:163]
	v_lshl_add_u64 v[166:167], s[56:57], 0, v[166:167]
	v_cndmask_b32_e32 v176, v175, v176, vcc
	v_cmp_lt_i32_e32 vcc, v177, v182
	v_lshlrev_b32_e32 v176, 2, v176
	v_lshl_add_u64 v[166:167], v[160:161], 1, v[166:167]
	v_cndmask_b32_e32 v177, v175, v177, vcc
	v_lshlrev_b32_e32 v177, 2, v177
	s_waitcnt vmcnt(0)
	v_pk_add_f32 v[126:127], v[126:127], v[180:181]
	v_pk_add_f32 v[124:125], v[124:125], v[178:179]
	v_pk_add_f32 v[118:119], v[118:119], v[192:193]
	v_pk_add_f32 v[116:117], v[116:117], v[190:191]
	v_pk_add_f32 v[120:121], v[120:121], v[186:187]
	v_pk_add_f32 v[178:179], v[114:115], v[196:197]
	v_pk_add_f32 v[180:181], v[112:113], v[194:195]
	v_mul_f32_e32 v114, v125, v125
	v_mul_f32_e32 v115, v127, v127
	v_cvt_pk_bf16_f32 v112, v124, v125
	v_cvt_pk_bf16_f32 v113, v126, v127
	v_mul_f32_e32 v125, v117, v117
	v_mul_f32_e32 v127, v119, v119
	v_pk_add_f32 v[122:123], v[122:123], v[188:189]
	v_mul_f32_e32 v182, v121, v121
	v_mul_f32_e32 v185, v181, v181
	v_fmac_f32_e32 v114, v124, v124
	v_fmac_f32_e32 v115, v126, v126
	v_fmac_f32_e32 v125, v116, v116
	v_fmac_f32_e32 v127, v118, v118
	v_mul_f32_e32 v183, v123, v123
	v_mul_f32_e32 v186, v179, v179
	v_fmac_f32_e32 v182, v120, v120
	v_fmac_f32_e32 v185, v180, v180
	v_add_f32_e32 v114, v114, v115
	v_add_f32_e32 v115, v125, v127
	v_fmac_f32_e32 v183, v122, v122
	v_fmac_f32_e32 v186, v178, v178
	v_add_f32_e32 v114, v114, v182
	v_add_f32_e32 v115, v115, v185
	v_add_f32_e32 v114, v183, v114
	v_add_f32_e32 v115, v186, v115
	v_add_f32_e32 v124, v114, v115
	ds_bpermute_b32 v125, v176, v124
	v_cvt_pk_bf16_f32 v114, v120, v121
	v_cvt_pk_bf16_f32 v115, v122, v123
	global_store_dwordx4 v[166:167], v[112:115], off
	s_waitcnt lgkmcnt(0)
	s_nop 0
	v_add_f32_e32 v112, v124, v125
	ds_bpermute_b32 v113, v177, v112
	v_cvt_pk_bf16_f32 v114, v116, v117
	v_cvt_pk_bf16_f32 v115, v118, v119
	v_cvt_pk_bf16_f32 v116, v180, v181
	v_cvt_pk_bf16_f32 v117, v178, v179
	global_store_dwordx4 v[166:167], v[114:117], off offset:256
	s_and_saveexec_b64 s[34:35], s[8:9]
	s_cbranch_execz .LBB0_517
	v_lshl_add_u64 v[114:115], v[162:163], 2, s[20:21]
	s_waitcnt lgkmcnt(0)
	v_add_f32_e32 v112, v112, v113
	global_atomic_add_f32 v[114:115], v112, off

.LBB0_604:
	ds_read_b128 v[16:19], v176
	ds_read_b128 v[20:23], v176 offset:1024
	ds_read_b128 v[32:35], v176 offset:2048
	ds_read_b128 v[36:39], v176 offset:3072
	s_add_u32 s41, s10, 0xfff00080
	s_addc_u32 s46, s11, -1
	s_cmp_eq_u32 s39, 60
	s_cselect_b32 s49, s4, s46
	s_cselect_b32 s48, s5, s41
	s_cselect_b32 s47, s6, s15
	s_cselect_b32 s46, s7, s13
	v_lshl_add_u64 v[160:161], s[10:11], 0, v[152:153]
	s_add_i32 m0, s52, 0xc000
	ds_read_b128 v[164:167], v177
	ds_read_b128 v[168:171], v177 offset:1024
	ds_read_b128 v[190:193], v177 offset:2048
	ds_read_b128 v[194:197], v177 offset:3072
	ds_read_b128 v[198:201], v177 offset:4096
	ds_read_b128 v[202:205], v177 offset:5120
	ds_read_b128 v[206:209], v177 offset:6144
	ds_read_b128 v[210:213], v177 offset:7168
	global_load_lds_dwordx4 v[160:161], off
	v_lshl_add_u64 v[160:161], s[10:11], 0, v[154:155]
	s_add_i32 m0, s52, 0xe000
	s_nop 0
	global_load_lds_dwordx4 v[160:161], off
	s_waitcnt lgkmcnt(8)
	s_barrier
	s_waitcnt lgkmcnt(0)
	s_setprio 1
	s_waitcnt lgkmcnt(0)
	v_mfma_f32_16x16x32_bf16 v[140:143], v[16:19], v[164:167], v[140:143]
	v_mfma_f32_16x16x32_bf16 v[140:143], v[20:23], v[168:171], v[140:143]
	v_mfma_f32_16x16x32_bf16 v[136:139], v[32:35], v[164:167], v[136:139]
	v_mfma_f32_16x16x32_bf16 v[136:139], v[36:39], v[168:171], v[136:139]
	v_mfma_f32_16x16x32_bf16 v[124:127], v[16:19], v[190:193], v[124:127]
	v_mfma_f32_16x16x32_bf16 v[124:127], v[20:23], v[194:197], v[124:127]
	v_mfma_f32_16x16x32_bf16 v[120:123], v[32:35], v[190:193], v[120:123]
	v_mfma_f32_16x16x32_bf16 v[120:123], v[36:39], v[194:197], v[120:123]
	v_mfma_f32_16x16x32_bf16 v[108:111], v[16:19], v[198:201], v[108:111]
	v_mfma_f32_16x16x32_bf16 v[108:111], v[20:23], v[202:205], v[108:111]
	v_mfma_f32_16x16x32_bf16 v[104:107], v[32:35], v[198:201], v[104:107]
	v_mfma_f32_16x16x32_bf16 v[104:107], v[36:39], v[202:205], v[104:107]
	v_mfma_f32_16x16x32_bf16 v[92:95], v[16:19], v[206:209], v[92:95]
	v_mfma_f32_16x16x32_bf16 v[92:95], v[20:23], v[210:213], v[92:95]
	v_mfma_f32_16x16x32_bf16 v[88:91], v[32:35], v[206:209], v[88:91]
	v_mfma_f32_16x16x32_bf16 v[88:91], v[36:39], v[210:213], v[88:91]
	s_setprio 0
	s_barrier
	s_add_i32 s41, s81, s51
	v_lshl_add_u64 v[160:161], s[46:47], 0, v[146:147]
	s_mov_b32 m0, s41
	ds_read_b128 v[214:217], v178
	ds_read_b128 v[218:221], v178 offset:1024
	ds_read_b128 v[222:225], v178 offset:2048
	ds_read_b128 v[226:229], v178 offset:3072
	global_load_lds_dwordx4 v[160:161], off
	v_lshl_add_u64 v[230:231], s[46:47], 0, v[150:151]
	s_add_i32 m0, s41, 0x2000
	s_nop 0
	global_load_lds_dwordx4 v[230:231], off
	s_barrier
	s_waitcnt lgkmcnt(0)
	s_setprio 1
	s_waitcnt lgkmcnt(0)
	v_mfma_f32_16x16x32_bf16 v[132:135], v[214:217], v[164:167], v[132:135]
	v_mfma_f32_16x16x32_bf16 v[132:135], v[218:221], v[168:171], v[132:135]
	v_mfma_f32_16x16x32_bf16 v[128:131], v[222:225], v[164:167], v[128:131]
	v_mfma_f32_16x16x32_bf16 v[128:131], v[226:229], v[168:171], v[128:131]
	v_mfma_f32_16x16x32_bf16 v[116:119], v[214:217], v[190:193], v[116:119]
	v_mfma_f32_16x16x32_bf16 v[116:119], v[218:221], v[194:197], v[116:119]
	v_mfma_f32_16x16x32_bf16 v[112:115], v[222:225], v[190:193], v[112:115]
	v_mfma_f32_16x16x32_bf16 v[112:115], v[226:229], v[194:197], v[112:115]
	v_mfma_f32_16x16x32_bf16 v[100:103], v[214:217], v[198:201], v[100:103]
	v_mfma_f32_16x16x32_bf16 v[100:103], v[218:221], v[202:205], v[100:103]
	v_mfma_f32_16x16x32_bf16 v[96:99], v[222:225], v[198:201], v[96:99]
	v_mfma_f32_16x16x32_bf16 v[96:99], v[226:229], v[202:205], v[96:99]
	v_mfma_f32_16x16x32_bf16 v[84:87], v[214:217], v[206:209], v[84:87]
	v_mfma_f32_16x16x32_bf16 v[84:87], v[218:221], v[210:213], v[84:87]
	v_mfma_f32_16x16x32_bf16 v[80:83], v[222:225], v[206:209], v[80:83]
	v_mfma_f32_16x16x32_bf16 v[80:83], v[226:229], v[210:213], v[80:83]
	s_setprio 0
	s_mov_b32 m0, s52
	v_lshl_add_u64 v[232:233], s[48:49], 0, v[144:145]
	s_barrier
	ds_read_b128 v[164:167], v177 offset:16384
	ds_read_b128 v[168:171], v177 offset:17408
	ds_read_b128 v[190:193], v177 offset:18432
	ds_read_b128 v[194:197], v177 offset:19456
	ds_read_b128 v[198:201], v177 offset:20480
	ds_read_b128 v[202:205], v177 offset:21504
	ds_read_b128 v[206:209], v177 offset:22528
	ds_read_b128 v[210:213], v177 offset:23552
	global_load_lds_dwordx4 v[232:233], off
	v_lshl_add_u64 v[234:235], s[48:49], 0, v[148:149]
	s_mov_b32 m0, s53
	s_nop 0
	global_load_lds_dwordx4 v[234:235], off
	s_barrier
	s_waitcnt lgkmcnt(0)
	s_setprio 1
	s_waitcnt lgkmcnt(0)
	v_mfma_f32_16x16x32_bf16 v[76:79], v[16:19], v[164:167], v[76:79]
	v_mfma_f32_16x16x32_bf16 v[76:79], v[20:23], v[168:171], v[76:79]
	v_mfma_f32_16x16x32_bf16 v[72:75], v[32:35], v[164:167], v[72:75]
	v_mfma_f32_16x16x32_bf16 v[72:75], v[36:39], v[168:171], v[72:75]
	v_mfma_f32_16x16x32_bf16 v[60:63], v[16:19], v[190:193], v[60:63]
	v_mfma_f32_16x16x32_bf16 v[60:63], v[20:23], v[194:197], v[60:63]
	v_mfma_f32_16x16x32_bf16 v[56:59], v[32:35], v[190:193], v[56:59]
	v_mfma_f32_16x16x32_bf16 v[56:59], v[36:39], v[194:197], v[56:59]
	v_mfma_f32_16x16x32_bf16 v[44:47], v[16:19], v[198:201], v[44:47]
	v_mfma_f32_16x16x32_bf16 v[44:47], v[20:23], v[202:205], v[44:47]
	v_mfma_f32_16x16x32_bf16 v[40:43], v[32:35], v[198:201], v[40:43]
	v_mfma_f32_16x16x32_bf16 v[40:43], v[36:39], v[202:205], v[40:43]
	v_mfma_f32_16x16x32_bf16 v[12:15], v[16:19], v[206:209], v[12:15]
	v_mfma_f32_16x16x32_bf16 v[12:15], v[20:23], v[210:213], v[12:15]
	v_mfma_f32_16x16x32_bf16 v[8:11], v[32:35], v[206:209], v[8:11]
	v_mfma_f32_16x16x32_bf16 v[8:11], v[36:39], v[210:213], v[8:11]
	s_setprio 0
	s_barrier
	s_add_u32 s54, s46, 0x100000
	s_addc_u32 s55, s47, 0
	s_add_i32 s41, s82, s51
	v_lshl_add_u64 v[16:17], s[54:55], 0, v[146:147]
	s_mov_b32 m0, s41
	s_nop 0
	global_load_lds_dwordx4 v[16:17], off
	v_lshl_add_u64 v[16:17], s[54:55], 0, v[150:151]
	s_add_i32 m0, s41, 0x2000
	s_nop 0
	global_load_lds_dwordx4 v[16:17], off
	s_waitcnt vmcnt(6)
	s_barrier
	s_setprio 1
	v_mfma_f32_16x16x32_bf16 v[28:31], v[214:217], v[198:201], v[28:31]
	v_mfma_f32_16x16x32_bf16 v[24:27], v[222:225], v[198:201], v[24:27]
	v_mfma_f32_16x16x32_bf16 v[4:7], v[214:217], v[206:209], v[4:7]
	v_mfma_f32_16x16x32_bf16 v[0:3], v[222:225], v[206:209], v[0:3]
	v_mfma_f32_16x16x32_bf16 v[16:19], v[214:217], v[164:167], v[68:71]
	v_mfma_f32_16x16x32_bf16 v[20:23], v[222:225], v[164:167], v[64:67]
	v_mfma_f32_16x16x32_bf16 v[32:35], v[214:217], v[190:193], v[52:55]
	v_mfma_f32_16x16x32_bf16 v[36:39], v[222:225], v[190:193], v[48:51]
	v_mfma_f32_16x16x32_bf16 v[28:31], v[218:221], v[202:205], v[28:31]
	v_mfma_f32_16x16x32_bf16 v[24:27], v[226:229], v[202:205], v[24:27]
	v_mfma_f32_16x16x32_bf16 v[4:7], v[218:221], v[210:213], v[4:7]
	v_mfma_f32_16x16x32_bf16 v[0:3], v[226:229], v[210:213], v[0:3]
	v_mfma_f32_16x16x32_bf16 v[16:19], v[218:221], v[168:171], v[16:19]
	v_mfma_f32_16x16x32_bf16 v[20:23], v[226:229], v[168:171], v[20:23]
	v_mfma_f32_16x16x32_bf16 v[32:35], v[218:221], v[194:197], v[32:35]
	v_mfma_f32_16x16x32_bf16 v[36:39], v[226:229], v[194:197], v[36:39]
	s_setprio 0
	s_add_i32 s41, 0, 0x18000
	v_add_u32_e32 v68, s41, v174
	s_barrier
	ds_read_b128 v[48:51], v68
	ds_read_b128 v[52:55], v68 offset:1024
	ds_read_b128 v[64:67], v68 offset:2048
	ds_read_b128 v[68:71], v68 offset:3072
	s_add_u32 s48, s48, 0x100000
	s_addc_u32 s49, s49, 0
	s_mov_b32 m0, s61
	v_lshl_add_u64 v[214:215], s[48:49], 0, v[144:145]
	ds_read_b128 v[164:167], v177 offset:32768
	ds_read_b128 v[168:171], v177 offset:33792
	ds_read_b128 v[190:193], v177 offset:34816
	ds_read_b128 v[194:197], v177 offset:35840
	ds_read_b128 v[198:201], v177 offset:36864
	ds_read_b128 v[202:205], v177 offset:37888
	ds_read_b128 v[206:209], v177 offset:38912
	ds_read_b128 v[210:213], v177 offset:39936
	global_load_lds_dwordx4 v[214:215], off
	v_lshl_add_u64 v[214:215], s[48:49], 0, v[148:149]
	s_mov_b32 m0, s74
	s_nop 0
	global_load_lds_dwordx4 v[214:215], off
	s_waitcnt lgkmcnt(8)
	s_barrier
	s_waitcnt lgkmcnt(0)
	s_setprio 1
	s_waitcnt lgkmcnt(0)
	v_mfma_f32_16x16x32_bf16 v[140:143], v[48:51], v[164:167], v[140:143]
	v_mfma_f32_16x16x32_bf16 v[140:143], v[52:55], v[168:171], v[140:143]
	v_mfma_f32_16x16x32_bf16 v[136:139], v[64:67], v[164:167], v[136:139]
	v_mfma_f32_16x16x32_bf16 v[136:139], v[68:71], v[168:171], v[136:139]
	v_mfma_f32_16x16x32_bf16 v[124:127], v[48:51], v[190:193], v[124:127]
	v_mfma_f32_16x16x32_bf16 v[124:127], v[52:55], v[194:197], v[124:127]
	v_mfma_f32_16x16x32_bf16 v[120:123], v[64:67], v[190:193], v[120:123]
	v_mfma_f32_16x16x32_bf16 v[120:123], v[68:71], v[194:197], v[120:123]
	v_mfma_f32_16x16x32_bf16 v[108:111], v[48:51], v[198:201], v[108:111]
	v_mfma_f32_16x16x32_bf16 v[108:111], v[52:55], v[202:205], v[108:111]
	v_mfma_f32_16x16x32_bf16 v[104:107], v[64:67], v[198:201], v[104:107]
	v_mfma_f32_16x16x32_bf16 v[104:107], v[68:71], v[202:205], v[104:107]
	v_mfma_f32_16x16x32_bf16 v[92:95], v[48:51], v[206:209], v[92:95]
	v_mfma_f32_16x16x32_bf16 v[92:95], v[52:55], v[210:213], v[92:95]
	v_mfma_f32_16x16x32_bf16 v[88:91], v[64:67], v[206:209], v[88:91]
	v_mfma_f32_16x16x32_bf16 v[88:91], v[68:71], v[210:213], v[88:91]
	s_setprio 0
	s_barrier
	s_add_i32 s48, 0, 0x1c000
	s_add_i32 s41, s41, s51
	v_add_u32_e32 v163, s48, v174
	v_lshl_add_u64 v[160:161], v[160:161], 0, s[22:23]
	s_mov_b32 m0, s41
	ds_read_b128 v[214:217], v163
	ds_read_b128 v[218:221], v163 offset:1024
	ds_read_b128 v[222:225], v163 offset:2048
	ds_read_b128 v[226:229], v163 offset:3072
	global_load_lds_dwordx4 v[160:161], off
	v_lshl_add_u64 v[160:161], v[230:231], 0, s[22:23]
	s_add_i32 m0, s41, 0x2000
	s_nop 0
	global_load_lds_dwordx4 v[160:161], off
	s_barrier
	s_waitcnt lgkmcnt(0)
	s_setprio 1
	s_waitcnt lgkmcnt(0)
	v_mfma_f32_16x16x32_bf16 v[132:135], v[214:217], v[164:167], v[132:135]
	v_mfma_f32_16x16x32_bf16 v[132:135], v[218:221], v[168:171], v[132:135]
	v_mfma_f32_16x16x32_bf16 v[128:131], v[222:225], v[164:167], v[128:131]
	v_mfma_f32_16x16x32_bf16 v[128:131], v[226:229], v[168:171], v[128:131]
	v_mfma_f32_16x16x32_bf16 v[116:119], v[214:217], v[190:193], v[116:119]
	v_mfma_f32_16x16x32_bf16 v[116:119], v[218:221], v[194:197], v[116:119]
	v_mfma_f32_16x16x32_bf16 v[112:115], v[222:225], v[190:193], v[112:115]
	v_mfma_f32_16x16x32_bf16 v[112:115], v[226:229], v[194:197], v[112:115]
	v_mfma_f32_16x16x32_bf16 v[100:103], v[214:217], v[198:201], v[100:103]
	v_mfma_f32_16x16x32_bf16 v[100:103], v[218:221], v[202:205], v[100:103]
	v_mfma_f32_16x16x32_bf16 v[96:99], v[222:225], v[198:201], v[96:99]
	v_mfma_f32_16x16x32_bf16 v[96:99], v[226:229], v[202:205], v[96:99]
	v_mfma_f32_16x16x32_bf16 v[84:87], v[214:217], v[206:209], v[84:87]
	v_mfma_f32_16x16x32_bf16 v[84:87], v[218:221], v[210:213], v[84:87]
	v_mfma_f32_16x16x32_bf16 v[80:83], v[222:225], v[206:209], v[80:83]
	v_mfma_f32_16x16x32_bf16 v[80:83], v[226:229], v[210:213], v[80:83]
	s_setprio 0
	s_mov_b32 m0, s76
	v_lshl_add_u64 v[160:161], v[232:233], 0, s[22:23]
	s_barrier
	ds_read_b128 v[164:167], v177 offset:49152
	ds_read_b128 v[168:171], v177 offset:50176
	ds_read_b128 v[190:193], v177 offset:51200
	ds_read_b128 v[194:197], v177 offset:52224
	ds_read_b128 v[198:201], v177 offset:53248
	ds_read_b128 v[202:205], v177 offset:54272
	ds_read_b128 v[206:209], v177 offset:55296
	ds_read_b128 v[210:213], v177 offset:56320
	global_load_lds_dwordx4 v[160:161], off
	v_lshl_add_u64 v[160:161], v[234:235], 0, s[22:23]
	s_mov_b32 m0, s77
	s_nop 0
	global_load_lds_dwordx4 v[160:161], off
	s_barrier
	s_waitcnt lgkmcnt(0)
	s_setprio 1
	s_waitcnt lgkmcnt(0)
	v_mfma_f32_16x16x32_bf16 v[76:79], v[48:51], v[164:167], v[76:79]
	v_mfma_f32_16x16x32_bf16 v[76:79], v[52:55], v[168:171], v[76:79]
	v_mfma_f32_16x16x32_bf16 v[72:75], v[64:67], v[164:167], v[72:75]
	v_mfma_f32_16x16x32_bf16 v[72:75], v[68:71], v[168:171], v[72:75]
	v_mfma_f32_16x16x32_bf16 v[60:63], v[48:51], v[190:193], v[60:63]
	v_mfma_f32_16x16x32_bf16 v[60:63], v[52:55], v[194:197], v[60:63]
	v_mfma_f32_16x16x32_bf16 v[56:59], v[64:67], v[190:193], v[56:59]
	v_mfma_f32_16x16x32_bf16 v[56:59], v[68:71], v[194:197], v[56:59]
	v_mfma_f32_16x16x32_bf16 v[44:47], v[48:51], v[198:201], v[44:47]
	v_mfma_f32_16x16x32_bf16 v[44:47], v[52:55], v[202:205], v[44:47]
	v_mfma_f32_16x16x32_bf16 v[40:43], v[64:67], v[198:201], v[40:43]
	v_mfma_f32_16x16x32_bf16 v[40:43], v[68:71], v[202:205], v[40:43]
	v_mfma_f32_16x16x32_bf16 v[12:15], v[48:51], v[206:209], v[12:15]
	v_mfma_f32_16x16x32_bf16 v[12:15], v[52:55], v[210:213], v[12:15]
	v_mfma_f32_16x16x32_bf16 v[8:11], v[64:67], v[206:209], v[8:11]
	v_mfma_f32_16x16x32_bf16 v[8:11], v[68:71], v[210:213], v[8:11]
	s_setprio 0
	s_barrier
	s_add_u32 s46, s46, 0x100080
	s_addc_u32 s47, s47, 0
	s_add_i32 s41, s48, s51
	v_lshl_add_u64 v[48:49], s[46:47], 0, v[146:147]
	s_mov_b32 m0, s41
	s_nop 0
	global_load_lds_dwordx4 v[48:49], off
	v_lshl_add_u64 v[48:49], s[46:47], 0, v[150:151]
	s_add_i32 m0, s41, 0x2000
	s_nop 0
	global_load_lds_dwordx4 v[48:49], off
	s_waitcnt vmcnt(6)
	s_barrier
	s_setprio 1
	v_mfma_f32_16x16x32_bf16 v[16:19], v[214:217], v[164:167], v[16:19]
	v_mfma_f32_16x16x32_bf16 v[68:71], v[218:221], v[168:171], v[16:19]
	v_mfma_f32_16x16x32_bf16 v[16:19], v[222:225], v[164:167], v[20:23]
	v_mfma_f32_16x16x32_bf16 v[64:67], v[226:229], v[168:171], v[16:19]
	v_mfma_f32_16x16x32_bf16 v[16:19], v[214:217], v[190:193], v[32:35]
	v_mfma_f32_16x16x32_bf16 v[52:55], v[218:221], v[194:197], v[16:19]
	v_mfma_f32_16x16x32_bf16 v[16:19], v[222:225], v[190:193], v[36:39]
	v_mfma_f32_16x16x32_bf16 v[48:51], v[226:229], v[194:197], v[16:19]
	v_mfma_f32_16x16x32_bf16 v[16:19], v[214:217], v[198:201], v[28:31]
	v_mfma_f32_16x16x32_bf16 v[28:31], v[218:221], v[202:205], v[16:19]
	v_mfma_f32_16x16x32_bf16 v[16:19], v[222:225], v[198:201], v[24:27]
	v_mfma_f32_16x16x32_bf16 v[4:7], v[214:217], v[206:209], v[4:7]
	v_mfma_f32_16x16x32_bf16 v[0:3], v[222:225], v[206:209], v[0:3]
	v_mfma_f32_16x16x32_bf16 v[24:27], v[226:229], v[202:205], v[16:19]
	v_mfma_f32_16x16x32_bf16 v[4:7], v[218:221], v[210:213], v[4:7]
	v_mfma_f32_16x16x32_bf16 v[0:3], v[226:229], v[210:213], v[0:3]
	s_setprio 0
	s_add_i32 s39, s39, 2
	s_add_u32 s10, s10, 0x100
	s_addc_u32 s11, s11, 0
	s_add_u32 s13, s13, 0x100
	s_addc_u32 s15, s15, 0
	s_cmp_gt_u32 s39, 61
	s_barrier
	s_cbranch_scc0 .LBB0_604
	s_ashr_i32 s4, s12, 4
	s_cmp_eq_u32 s4, 1
	v_lshl_or_b32 v160, s12, 8, v175
	v_mov_b32_e32 v36, 0
	s_cselect_b64 s[46:47], -1, 0
	s_cmp_lg_u32 s4, 1
	v_mov_b32_e32 v37, 0
	v_mov_b32_e32 v38, 0
	v_mov_b32_e32 v39, 0
	v_mov_b32_e32 v32, 0
	v_mov_b32_e32 v33, 0
	v_mov_b32_e32 v34, 0
	v_mov_b32_e32 v35, 0
	v_mov_b32_e32 v20, 0
	v_mov_b32_e32 v21, 0
	v_mov_b32_e32 v22, 0
	v_mov_b32_e32 v23, 0
	v_mov_b32_e32 v16, 0
	v_mov_b32_e32 v17, 0
	v_mov_b32_e32 v18, 0
	v_mov_b32_e32 v19, 0
	s_cbranch_scc1 .LBB0_607
	v_mov_b32_e32 v161, v147
	v_lshl_add_u64 v[16:17], v[160:161], 2, s[18:19]
	v_add_co_u32_e32 v20, vcc, 0xffffc000, v16
	v_lshl_add_u64 v[18:19], v[16:17], 0, s[24:25]
	s_nop 0
	v_addc_co_u32_e32 v21, vcc, -1, v17, vcc
	global_load_dwordx4 v[36:39], v[20:21], off
	global_load_dwordx4 v[32:35], v[18:19], off offset:16
	v_lshl_add_u64 v[18:19], v[16:17], 0, s[26:27]
	v_add_co_u32_e32 v16, vcc, 0xffffd000, v16
	s_nop 1
	v_addc_co_u32_e32 v17, vcc, -1, v17, vcc
	global_load_dwordx4 v[20:23], v[16:17], off offset:-3584
	s_nop 0
	global_load_dwordx4 v[16:19], v[18:19], off offset:16

.LBB0_981:
	ds_read_b128 v[128:131], v163
	ds_read_b128 v[132:135], v163 offset:1024
	ds_read_b128 v[152:155], v163 offset:2048
	ds_read_b128 v[156:159], v163 offset:3072
	s_add_u32 s26, s24, 0xffc00080
	s_addc_u32 s27, s25, -1
	s_cmp_eq_u32 s47, 60
	s_cselect_b32 s29, s15, s27
	s_cselect_b32 s28, s21, s26
	s_cselect_b32 s27, s13, s46
	s_cselect_b32 s26, s44, s45
	v_lshl_add_u64 v[182:183], s[24:25], 0, v[144:145]
	s_add_i32 m0, s23, 0xc000
	ds_read_b128 v[168:171], v164
	ds_read_b128 v[174:177], v164 offset:1024
	ds_read_b128 v[178:181], v164 offset:2048
	ds_read_b128 v[186:189], v164 offset:3072
	ds_read_b128 v[190:193], v164 offset:4096
	ds_read_b128 v[194:197], v164 offset:5120
	ds_read_b128 v[198:201], v164 offset:6144
	ds_read_b128 v[202:205], v164 offset:7168
	global_load_lds_dwordx4 v[182:183], off
	v_lshl_add_u64 v[182:183], s[24:25], 0, v[146:147]
	s_add_i32 m0, s23, 0xe000
	s_nop 0
	global_load_lds_dwordx4 v[182:183], off
	s_waitcnt lgkmcnt(8)
	s_barrier
	s_waitcnt lgkmcnt(0)
	s_setprio 1
	s_waitcnt lgkmcnt(0)
	v_mfma_f32_16x16x32_bf16 v[124:127], v[128:131], v[168:171], v[124:127]
	v_mfma_f32_16x16x32_bf16 v[124:127], v[132:135], v[174:177], v[124:127]
	v_mfma_f32_16x16x32_bf16 v[120:123], v[152:155], v[168:171], v[120:123]
	v_mfma_f32_16x16x32_bf16 v[120:123], v[156:159], v[174:177], v[120:123]
	v_mfma_f32_16x16x32_bf16 v[108:111], v[128:131], v[178:181], v[108:111]
	v_mfma_f32_16x16x32_bf16 v[108:111], v[132:135], v[186:189], v[108:111]
	v_mfma_f32_16x16x32_bf16 v[104:107], v[152:155], v[178:181], v[104:107]
	v_mfma_f32_16x16x32_bf16 v[104:107], v[156:159], v[186:189], v[104:107]
	v_mfma_f32_16x16x32_bf16 v[92:95], v[128:131], v[190:193], v[92:95]
	v_mfma_f32_16x16x32_bf16 v[92:95], v[132:135], v[194:197], v[92:95]
	v_mfma_f32_16x16x32_bf16 v[88:91], v[152:155], v[190:193], v[88:91]
	v_mfma_f32_16x16x32_bf16 v[88:91], v[156:159], v[194:197], v[88:91]
	v_mfma_f32_16x16x32_bf16 v[76:79], v[128:131], v[198:201], v[76:79]
	v_mfma_f32_16x16x32_bf16 v[76:79], v[132:135], v[202:205], v[76:79]
	v_mfma_f32_16x16x32_bf16 v[72:75], v[152:155], v[198:201], v[72:75]
	v_mfma_f32_16x16x32_bf16 v[72:75], v[156:159], v[202:205], v[72:75]
	s_setprio 0
	s_barrier
	s_add_i32 s48, s42, s30
	v_lshl_add_u64 v[182:183], s[26:27], 0, v[138:139]
	s_mov_b32 m0, s48
	ds_read_b128 v[206:209], v165
	ds_read_b128 v[210:213], v165 offset:1024
	ds_read_b128 v[214:217], v165 offset:2048
	ds_read_b128 v[218:221], v165 offset:3072
	global_load_lds_dwordx4 v[182:183], off
	v_lshl_add_u64 v[222:223], s[26:27], 0, v[142:143]
	s_add_i32 m0, s48, 0x2000
	s_nop 0
	global_load_lds_dwordx4 v[222:223], off
	s_barrier
	s_waitcnt lgkmcnt(0)
	s_setprio 1
	s_waitcnt lgkmcnt(0)
	v_mfma_f32_16x16x32_bf16 v[116:119], v[206:209], v[168:171], v[116:119]
	v_mfma_f32_16x16x32_bf16 v[116:119], v[210:213], v[174:177], v[116:119]
	v_mfma_f32_16x16x32_bf16 v[112:115], v[214:217], v[168:171], v[112:115]
	v_mfma_f32_16x16x32_bf16 v[112:115], v[218:221], v[174:177], v[112:115]
	v_mfma_f32_16x16x32_bf16 v[100:103], v[206:209], v[178:181], v[100:103]
	v_mfma_f32_16x16x32_bf16 v[100:103], v[210:213], v[186:189], v[100:103]
	v_mfma_f32_16x16x32_bf16 v[96:99], v[214:217], v[178:181], v[96:99]
	v_mfma_f32_16x16x32_bf16 v[96:99], v[218:221], v[186:189], v[96:99]
	v_mfma_f32_16x16x32_bf16 v[84:87], v[206:209], v[190:193], v[84:87]
	v_mfma_f32_16x16x32_bf16 v[84:87], v[210:213], v[194:197], v[84:87]
	v_mfma_f32_16x16x32_bf16 v[80:83], v[214:217], v[190:193], v[80:83]
	v_mfma_f32_16x16x32_bf16 v[80:83], v[218:221], v[194:197], v[80:83]
	v_mfma_f32_16x16x32_bf16 v[68:71], v[206:209], v[198:201], v[68:71]
	v_mfma_f32_16x16x32_bf16 v[68:71], v[210:213], v[202:205], v[68:71]
	v_mfma_f32_16x16x32_bf16 v[64:67], v[214:217], v[198:201], v[64:67]
	v_mfma_f32_16x16x32_bf16 v[64:67], v[218:221], v[202:205], v[64:67]
	s_setprio 0
	s_mov_b32 m0, s23
	v_lshl_add_u64 v[224:225], s[28:29], 0, v[136:137]
	s_barrier
	ds_read_b128 v[168:171], v164 offset:16384
	ds_read_b128 v[174:177], v164 offset:17408
	ds_read_b128 v[178:181], v164 offset:18432
	ds_read_b128 v[186:189], v164 offset:19456
	ds_read_b128 v[190:193], v164 offset:20480
	ds_read_b128 v[194:197], v164 offset:21504
	ds_read_b128 v[198:201], v164 offset:22528
	ds_read_b128 v[202:205], v164 offset:23552
	global_load_lds_dwordx4 v[224:225], off
	v_lshl_add_u64 v[226:227], s[28:29], 0, v[140:141]
	s_mov_b32 m0, s31
	s_nop 0
	global_load_lds_dwordx4 v[226:227], off
	s_barrier
	s_waitcnt lgkmcnt(0)
	s_setprio 1
	s_waitcnt lgkmcnt(0)
	v_mfma_f32_16x16x32_bf16 v[60:63], v[128:131], v[168:171], v[60:63]
	v_mfma_f32_16x16x32_bf16 v[60:63], v[132:135], v[174:177], v[60:63]
	v_mfma_f32_16x16x32_bf16 v[56:59], v[152:155], v[168:171], v[56:59]
	v_mfma_f32_16x16x32_bf16 v[56:59], v[156:159], v[174:177], v[56:59]
	v_mfma_f32_16x16x32_bf16 v[44:47], v[128:131], v[178:181], v[44:47]
	v_mfma_f32_16x16x32_bf16 v[44:47], v[132:135], v[186:189], v[44:47]
	v_mfma_f32_16x16x32_bf16 v[40:43], v[152:155], v[178:181], v[40:43]
	v_mfma_f32_16x16x32_bf16 v[40:43], v[156:159], v[186:189], v[40:43]
	v_mfma_f32_16x16x32_bf16 v[28:31], v[128:131], v[190:193], v[28:31]
	v_mfma_f32_16x16x32_bf16 v[28:31], v[132:135], v[194:197], v[28:31]
	v_mfma_f32_16x16x32_bf16 v[24:27], v[152:155], v[190:193], v[24:27]
	v_mfma_f32_16x16x32_bf16 v[24:27], v[156:159], v[194:197], v[24:27]
	v_mfma_f32_16x16x32_bf16 v[12:15], v[128:131], v[198:201], v[12:15]
	v_mfma_f32_16x16x32_bf16 v[12:15], v[132:135], v[202:205], v[12:15]
	v_mfma_f32_16x16x32_bf16 v[8:11], v[152:155], v[198:201], v[8:11]
	v_mfma_f32_16x16x32_bf16 v[8:11], v[156:159], v[202:205], v[8:11]
	s_setprio 0
	s_barrier
	s_add_u32 s48, s26, 0x100000
	s_addc_u32 s49, s27, 0
	s_add_i32 s50, s43, s30
	v_lshl_add_u64 v[128:129], s[48:49], 0, v[138:139]
	s_mov_b32 m0, s50
	s_nop 0
	global_load_lds_dwordx4 v[128:129], off
	v_lshl_add_u64 v[128:129], s[48:49], 0, v[142:143]
	s_add_i32 m0, s50, 0x2000
	s_nop 0
	global_load_lds_dwordx4 v[128:129], off
	s_waitcnt vmcnt(6)
	s_barrier
	s_setprio 1
	v_mfma_f32_16x16x32_bf16 v[52:55], v[206:209], v[168:171], v[52:55]
	v_mfma_f32_16x16x32_bf16 v[52:55], v[210:213], v[174:177], v[52:55]
	v_mfma_f32_16x16x32_bf16 v[48:51], v[214:217], v[168:171], v[48:51]
	v_mfma_f32_16x16x32_bf16 v[48:51], v[218:221], v[174:177], v[48:51]
	v_mfma_f32_16x16x32_bf16 v[36:39], v[206:209], v[178:181], v[36:39]
	v_mfma_f32_16x16x32_bf16 v[36:39], v[210:213], v[186:189], v[36:39]
	v_mfma_f32_16x16x32_bf16 v[32:35], v[214:217], v[178:181], v[32:35]
	v_mfma_f32_16x16x32_bf16 v[32:35], v[218:221], v[186:189], v[32:35]
	v_mfma_f32_16x16x32_bf16 v[20:23], v[206:209], v[190:193], v[20:23]
	v_mfma_f32_16x16x32_bf16 v[20:23], v[210:213], v[194:197], v[20:23]
	v_mfma_f32_16x16x32_bf16 v[16:19], v[214:217], v[190:193], v[16:19]
	v_mfma_f32_16x16x32_bf16 v[16:19], v[218:221], v[194:197], v[16:19]
	v_mfma_f32_16x16x32_bf16 v[4:7], v[206:209], v[198:201], v[4:7]
	v_mfma_f32_16x16x32_bf16 v[4:7], v[210:213], v[202:205], v[4:7]
	v_mfma_f32_16x16x32_bf16 v[0:3], v[214:217], v[198:201], v[0:3]
	v_mfma_f32_16x16x32_bf16 v[0:3], v[218:221], v[202:205], v[0:3]
	s_setprio 0
	s_add_i32 s48, 0, 0x18000
	v_add_u32_e32 v156, s48, v161
	s_barrier
	ds_read_b128 v[128:131], v156
	ds_read_b128 v[132:135], v156 offset:1024
	ds_read_b128 v[152:155], v156 offset:2048
	ds_read_b128 v[156:159], v156 offset:3072
	s_add_u32 s28, s28, 0x400000
	s_addc_u32 s29, s29, 0
	s_mov_b32 m0, s34
	v_lshl_add_u64 v[206:207], s[28:29], 0, v[136:137]
	ds_read_b128 v[168:171], v164 offset:32768
	ds_read_b128 v[174:177], v164 offset:33792
	ds_read_b128 v[178:181], v164 offset:34816
	ds_read_b128 v[186:189], v164 offset:35840
	ds_read_b128 v[190:193], v164 offset:36864
	ds_read_b128 v[194:197], v164 offset:37888
	ds_read_b128 v[198:201], v164 offset:38912
	ds_read_b128 v[202:205], v164 offset:39936
	global_load_lds_dwordx4 v[206:207], off
	v_lshl_add_u64 v[206:207], s[28:29], 0, v[140:141]
	s_mov_b32 m0, s35
	s_nop 0
	global_load_lds_dwordx4 v[206:207], off
	s_waitcnt lgkmcnt(8)
	s_barrier
	s_waitcnt lgkmcnt(0)
	s_setprio 1
	s_waitcnt lgkmcnt(0)
	v_mfma_f32_16x16x32_bf16 v[124:127], v[128:131], v[168:171], v[124:127]
	v_mfma_f32_16x16x32_bf16 v[124:127], v[132:135], v[174:177], v[124:127]
	v_mfma_f32_16x16x32_bf16 v[120:123], v[152:155], v[168:171], v[120:123]
	v_mfma_f32_16x16x32_bf16 v[120:123], v[156:159], v[174:177], v[120:123]
	v_mfma_f32_16x16x32_bf16 v[108:111], v[128:131], v[178:181], v[108:111]
	v_mfma_f32_16x16x32_bf16 v[108:111], v[132:135], v[186:189], v[108:111]
	v_mfma_f32_16x16x32_bf16 v[104:107], v[152:155], v[178:181], v[104:107]
	v_mfma_f32_16x16x32_bf16 v[104:107], v[156:159], v[186:189], v[104:107]
	v_mfma_f32_16x16x32_bf16 v[92:95], v[128:131], v[190:193], v[92:95]
	v_mfma_f32_16x16x32_bf16 v[92:95], v[132:135], v[194:197], v[92:95]
	v_mfma_f32_16x16x32_bf16 v[88:91], v[152:155], v[190:193], v[88:91]
	v_mfma_f32_16x16x32_bf16 v[88:91], v[156:159], v[194:197], v[88:91]
	v_mfma_f32_16x16x32_bf16 v[76:79], v[128:131], v[198:201], v[76:79]
	v_mfma_f32_16x16x32_bf16 v[76:79], v[132:135], v[202:205], v[76:79]
	v_mfma_f32_16x16x32_bf16 v[72:75], v[152:155], v[198:201], v[72:75]
	v_mfma_f32_16x16x32_bf16 v[72:75], v[156:159], v[202:205], v[72:75]
	s_setprio 0
	s_barrier
	s_add_i32 s28, 0, 0x1c000
	s_add_i32 s29, s48, s30
	v_add_u32_e32 v167, s28, v161
	v_lshl_add_u64 v[182:183], v[182:183], 0, s[10:11]
	s_mov_b32 m0, s29
	ds_read_b128 v[206:209], v167
	ds_read_b128 v[210:213], v167 offset:1024
	ds_read_b128 v[214:217], v167 offset:2048
	ds_read_b128 v[218:221], v167 offset:3072
	global_load_lds_dwordx4 v[182:183], off
	v_lshl_add_u64 v[182:183], v[222:223], 0, s[10:11]
	s_add_i32 m0, s29, 0x2000
	s_nop 0
	global_load_lds_dwordx4 v[182:183], off
	s_barrier
	s_waitcnt lgkmcnt(0)
	s_setprio 1
	s_waitcnt lgkmcnt(0)
	v_mfma_f32_16x16x32_bf16 v[116:119], v[206:209], v[168:171], v[116:119]
	v_mfma_f32_16x16x32_bf16 v[116:119], v[210:213], v[174:177], v[116:119]
	v_mfma_f32_16x16x32_bf16 v[112:115], v[214:217], v[168:171], v[112:115]
	v_mfma_f32_16x16x32_bf16 v[112:115], v[218:221], v[174:177], v[112:115]
	v_mfma_f32_16x16x32_bf16 v[100:103], v[206:209], v[178:181], v[100:103]
	v_mfma_f32_16x16x32_bf16 v[100:103], v[210:213], v[186:189], v[100:103]
	v_mfma_f32_16x16x32_bf16 v[96:99], v[214:217], v[178:181], v[96:99]
	v_mfma_f32_16x16x32_bf16 v[96:99], v[218:221], v[186:189], v[96:99]
	v_mfma_f32_16x16x32_bf16 v[84:87], v[206:209], v[190:193], v[84:87]
	v_mfma_f32_16x16x32_bf16 v[84:87], v[210:213], v[194:197], v[84:87]
	v_mfma_f32_16x16x32_bf16 v[80:83], v[214:217], v[190:193], v[80:83]
	v_mfma_f32_16x16x32_bf16 v[80:83], v[218:221], v[194:197], v[80:83]
	v_mfma_f32_16x16x32_bf16 v[68:71], v[206:209], v[198:201], v[68:71]
	v_mfma_f32_16x16x32_bf16 v[68:71], v[210:213], v[202:205], v[68:71]
	v_mfma_f32_16x16x32_bf16 v[64:67], v[214:217], v[198:201], v[64:67]
	v_mfma_f32_16x16x32_bf16 v[64:67], v[218:221], v[202:205], v[64:67]
	s_setprio 0
	s_mov_b32 m0, s37
	v_lshl_add_u64 v[182:183], v[224:225], 0, s[10:11]
	s_barrier
	ds_read_b128 v[168:171], v164 offset:49152
	ds_read_b128 v[174:177], v164 offset:50176
	ds_read_b128 v[178:181], v164 offset:51200
	ds_read_b128 v[186:189], v164 offset:52224
	ds_read_b128 v[190:193], v164 offset:53248
	ds_read_b128 v[194:197], v164 offset:54272
	ds_read_b128 v[198:201], v164 offset:55296
	ds_read_b128 v[202:205], v164 offset:56320
	global_load_lds_dwordx4 v[182:183], off
	v_lshl_add_u64 v[182:183], v[226:227], 0, s[10:11]
	s_mov_b32 m0, s38
	s_nop 0
	global_load_lds_dwordx4 v[182:183], off
	s_barrier
	s_waitcnt lgkmcnt(0)
	s_setprio 1
	s_waitcnt lgkmcnt(0)
	v_mfma_f32_16x16x32_bf16 v[60:63], v[128:131], v[168:171], v[60:63]
	v_mfma_f32_16x16x32_bf16 v[60:63], v[132:135], v[174:177], v[60:63]
	v_mfma_f32_16x16x32_bf16 v[56:59], v[152:155], v[168:171], v[56:59]
	v_mfma_f32_16x16x32_bf16 v[56:59], v[156:159], v[174:177], v[56:59]
	v_mfma_f32_16x16x32_bf16 v[44:47], v[128:131], v[178:181], v[44:47]
	v_mfma_f32_16x16x32_bf16 v[44:47], v[132:135], v[186:189], v[44:47]
	v_mfma_f32_16x16x32_bf16 v[40:43], v[152:155], v[178:181], v[40:43]
	v_mfma_f32_16x16x32_bf16 v[40:43], v[156:159], v[186:189], v[40:43]
	v_mfma_f32_16x16x32_bf16 v[28:31], v[128:131], v[190:193], v[28:31]
	v_mfma_f32_16x16x32_bf16 v[28:31], v[132:135], v[194:197], v[28:31]
	v_mfma_f32_16x16x32_bf16 v[24:27], v[152:155], v[190:193], v[24:27]
	v_mfma_f32_16x16x32_bf16 v[24:27], v[156:159], v[194:197], v[24:27]
	v_mfma_f32_16x16x32_bf16 v[12:15], v[128:131], v[198:201], v[12:15]
	v_mfma_f32_16x16x32_bf16 v[12:15], v[132:135], v[202:205], v[12:15]
	v_mfma_f32_16x16x32_bf16 v[8:11], v[152:155], v[198:201], v[8:11]
	v_mfma_f32_16x16x32_bf16 v[8:11], v[156:159], v[202:205], v[8:11]
	s_setprio 0
	s_barrier
	s_add_u32 s26, s26, 0x100080
	s_addc_u32 s27, s27, 0
	s_add_i32 s28, s28, s30
	v_lshl_add_u64 v[128:129], s[26:27], 0, v[138:139]
	s_mov_b32 m0, s28
	s_nop 0
	global_load_lds_dwordx4 v[128:129], off
	v_lshl_add_u64 v[128:129], s[26:27], 0, v[142:143]
	s_add_i32 m0, s28, 0x2000
	s_nop 0
	global_load_lds_dwordx4 v[128:129], off
	s_waitcnt vmcnt(6)
	s_barrier
	s_setprio 1
	v_mfma_f32_16x16x32_bf16 v[52:55], v[206:209], v[168:171], v[52:55]
	v_mfma_f32_16x16x32_bf16 v[52:55], v[210:213], v[174:177], v[52:55]
	v_mfma_f32_16x16x32_bf16 v[48:51], v[214:217], v[168:171], v[48:51]
	v_mfma_f32_16x16x32_bf16 v[48:51], v[218:221], v[174:177], v[48:51]
	v_mfma_f32_16x16x32_bf16 v[36:39], v[206:209], v[178:181], v[36:39]
	v_mfma_f32_16x16x32_bf16 v[36:39], v[210:213], v[186:189], v[36:39]
	v_mfma_f32_16x16x32_bf16 v[32:35], v[214:217], v[178:181], v[32:35]
	v_mfma_f32_16x16x32_bf16 v[32:35], v[218:221], v[186:189], v[32:35]
	v_mfma_f32_16x16x32_bf16 v[20:23], v[206:209], v[190:193], v[20:23]
	v_mfma_f32_16x16x32_bf16 v[20:23], v[210:213], v[194:197], v[20:23]
	v_mfma_f32_16x16x32_bf16 v[16:19], v[214:217], v[190:193], v[16:19]
	v_mfma_f32_16x16x32_bf16 v[16:19], v[218:221], v[194:197], v[16:19]
	v_mfma_f32_16x16x32_bf16 v[4:7], v[206:209], v[198:201], v[4:7]
	v_mfma_f32_16x16x32_bf16 v[4:7], v[210:213], v[202:205], v[4:7]
	v_mfma_f32_16x16x32_bf16 v[0:3], v[214:217], v[198:201], v[0:3]
	v_mfma_f32_16x16x32_bf16 v[0:3], v[218:221], v[202:205], v[0:3]
	s_setprio 0
	s_add_i32 s47, s47, 2
	s_add_u32 s24, s24, 0x100
	s_addc_u32 s25, s25, 0
	s_add_u32 s45, s45, 0x100
	s_addc_u32 s46, s46, 0
	s_cmp_gt_u32 s47, 61
	s_barrier
	s_cbranch_scc0 .LBB0_981
	v_lshl_add_u32 v156, s20, 8, v160
	v_lshl_or_b32 v152, s22, 8, v162
	v_ashrrev_i32_e32 v157, 31, v156
	v_ashrrev_i32_e32 v153, 31, v152
	v_lshlrev_b64 v[128:129], 13, v[156:157]
	v_lshl_add_u64 v[128:129], s[56:57], 0, v[128:129]
	v_lshlrev_b64 v[154:155], 1, v[152:153]
	v_lshl_add_u64 v[128:129], v[128:129], 0, v[154:155]
	global_load_dwordx4 v[168:171], v[128:129], off
	global_load_dwordx4 v[174:177], v[128:129], off offset:256
	v_or_b32_e32 v158, 16, v156
	v_ashrrev_i32_e32 v159, 31, v158
	v_lshlrev_b64 v[128:129], 13, v[158:159]
	v_lshl_add_u64 v[128:129], s[56:57], 0, v[128:129]
	v_lshl_add_u64 v[128:129], v[128:129], 0, v[154:155]
	global_load_dwordx4 v[132:135], v[128:129], off
	s_nop 0
	global_load_dwordx4 v[128:131], v[128:129], off offset:256
	v_and_b32_e32 v173, 64, v166
	v_xor_b32_e32 v167, 16, v166
	v_add_u32_e32 v173, 64, v173
	v_xor_b32_e32 v180, 32, v166
	v_cmp_lt_i32_e32 vcc, v167, v173
	v_lshlrev_b64 v[178:179], 15, v[156:157]
	v_lshl_add_u64 v[178:179], s[68:69], 0, v[178:179]
	v_cndmask_b32_e32 v167, v166, v167, vcc
	v_cmp_lt_i32_e32 vcc, v180, v173
	v_lshlrev_b32_e32 v167, 2, v167
	v_lshl_add_u64 v[178:179], v[178:179], 0, v[154:155]
	v_cndmask_b32_e32 v173, v166, v180, vcc
	s_waitcnt vmcnt(0)
	v_lshlrev_b32_e32 v180, 16, v168
	v_and_b32_e32 v181, 0xffff0000, v168
	v_lshlrev_b32_e32 v168, 16, v169
	v_and_b32_e32 v169, 0xffff0000, v169
	v_lshlrev_b32_e32 v186, 16, v174
	v_and_b32_e32 v187, 0xffff0000, v174
	v_lshlrev_b32_e32 v174, 16, v175
	v_and_b32_e32 v175, 0xffff0000, v175
	v_lshlrev_b32_e32 v182, 16, v170
	v_and_b32_e32 v183, 0xffff0000, v170
	v_lshlrev_b32_e32 v170, 16, v171
	v_and_b32_e32 v171, 0xffff0000, v171
	v_lshlrev_b32_e32 v188, 16, v176
	v_and_b32_e32 v189, 0xffff0000, v176
	v_lshlrev_b32_e32 v176, 16, v177
	v_and_b32_e32 v177, 0xffff0000, v177
	v_pk_add_f32 v[126:127], v[126:127], v[168:169]
	v_pk_add_f32 v[124:125], v[124:125], v[180:181]
	v_pk_add_f32 v[118:119], v[118:119], v[174:175]
	v_pk_add_f32 v[116:117], v[116:117], v[186:187]
	v_pk_add_f32 v[122:123], v[122:123], v[170:171]
	v_pk_add_f32 v[120:121], v[120:121], v[182:183]
	v_pk_add_f32 v[168:169], v[114:115], v[176:177]
	v_pk_add_f32 v[170:171], v[112:113], v[188:189]
	v_mul_f32_e32 v114, v125, v125
	v_mul_f32_e32 v115, v127, v127
	v_cvt_pk_bf16_f32 v112, v124, v125
	v_cvt_pk_bf16_f32 v113, v126, v127
	v_mul_f32_e32 v125, v117, v117
	v_mul_f32_e32 v127, v119, v119
	v_mul_f32_e32 v174, v121, v121
	v_mul_f32_e32 v176, v171, v171
	v_fmac_f32_e32 v114, v124, v124
	v_fmac_f32_e32 v115, v126, v126
	v_fmac_f32_e32 v125, v116, v116
	v_fmac_f32_e32 v127, v118, v118
	v_mul_f32_e32 v175, v123, v123
	v_mul_f32_e32 v177, v169, v169
	v_fmac_f32_e32 v174, v120, v120
	v_fmac_f32_e32 v176, v170, v170
	v_add_f32_e32 v114, v114, v115
	v_add_f32_e32 v115, v125, v127
	v_fmac_f32_e32 v175, v122, v122
	v_fmac_f32_e32 v177, v168, v168
	v_add_f32_e32 v114, v174, v114
	v_add_f32_e32 v115, v176, v115
	v_add_f32_e32 v114, v175, v114
	v_add_f32_e32 v115, v177, v115
	v_add_f32_e32 v124, v114, v115
	ds_bpermute_b32 v125, v167, v124
	v_cvt_pk_bf16_f32 v114, v120, v121
	v_cvt_pk_bf16_f32 v115, v122, v123
	global_store_dwordx4 v[178:179], v[112:115], off
	v_lshlrev_b32_e32 v122, 2, v173
	s_waitcnt lgkmcnt(0)
	v_add_f32_e32 v112, v124, v125
	ds_bpermute_b32 v113, v122, v112
	v_cvt_pk_bf16_f32 v114, v116, v117
	v_cvt_pk_bf16_f32 v115, v118, v119
	v_cvt_pk_bf16_f32 v116, v170, v171
	v_cvt_pk_bf16_f32 v117, v168, v169
	global_store_dwordx4 v[178:179], v[114:117], off offset:256
	s_and_saveexec_b64 s[20:21], s[6:7]
	s_cbranch_execz .LBB0_984
	v_lshl_add_u64 v[114:115], v[156:157], 2, s[72:73]
	s_waitcnt lgkmcnt(0)
	v_add_f32_e32 v112, v112, v113
	global_atomic_add_f32 v[114:115], v112, off

	.amdhsa_kernel _Z13mla_hgrn2_fwd6Params
		.amdhsa_group_segment_fixed_size 0
		.amdhsa_private_segment_fixed_size 0
		.amdhsa_kernarg_size 520
		.amdhsa_user_sgpr_count 2
		.amdhsa_user_sgpr_dispatch_ptr 0
		.amdhsa_user_sgpr_queue_ptr 0
		.amdhsa_user_sgpr_kernarg_segment_ptr 1
		.amdhsa_user_sgpr_dispatch_id 0
		.amdhsa_user_sgpr_kernarg_preload_length 0
		.amdhsa_user_sgpr_kernarg_preload_offset 0
		.amdhsa_user_sgpr_private_segment_size 0
		.amdhsa_uses_dynamic_stack 0
		.amdhsa_enable_private_segment 0
		.amdhsa_system_sgpr_workgroup_id_x 1
		.amdhsa_system_sgpr_workgroup_id_y 0
		.amdhsa_system_sgpr_workgroup_id_z 0
		.amdhsa_system_sgpr_workgroup_info 0
		.amdhsa_system_vgpr_workitem_id 2
		.amdhsa_next_free_vgpr 254
		.amdhsa_next_free_sgpr 98
		.amdhsa_accum_offset 256
		.amdhsa_reserve_vcc 1
		.amdhsa_float_round_mode_32 0
		.amdhsa_float_round_mode_16_64 0
		.amdhsa_float_denorm_mode_32 3
		.amdhsa_float_denorm_mode_16_64 3
		.amdhsa_dx10_clamp 1
		.amdhsa_ieee_mode 1
		.amdhsa_fp16_overflow 0
		.amdhsa_tg_split 0
		.amdhsa_exception_fp_ieee_invalid_op 0
		.amdhsa_exception_fp_denorm_src 0
		.amdhsa_exception_fp_ieee_div_zero 0
		.amdhsa_exception_fp_ieee_overflow 0
		.amdhsa_exception_fp_ieee_underflow 0
		.amdhsa_exception_fp_ieee_inexact 0
		.amdhsa_exception_int_div_zero 0
	.end_amdhsa_kernel

.Lfunc_end0:
	.size	_Z13mla_hgrn2_fwd6Params, .Lfunc_end0-_Z13mla_hgrn2_fwd6Params
	.set _Z13mla_hgrn2_fwd6Params.num_vgpr, 254
	.set _Z13mla_hgrn2_fwd6Params.num_agpr, 0
	.set _Z13mla_hgrn2_fwd6Params.numbered_sgpr, 98
	.set _Z13mla_hgrn2_fwd6Params.num_named_barrier, 0
	.set _Z13mla_hgrn2_fwd6Params.private_seg_size, 0
	.set _Z13mla_hgrn2_fwd6Params.uses_vcc, 1
	.set _Z13mla_hgrn2_fwd6Params.uses_flat_scratch, 0
	.set _Z13mla_hgrn2_fwd6Params.has_dyn_sized_stack, 0
	.set _Z13mla_hgrn2_fwd6Params.has_recursion, 0
	.set _Z13mla_hgrn2_fwd6Params.has_indirect_call, 0

amdhsa.kernels:
  - .agpr_count:     0
    .args:
      - .offset:         0
        .size:           264
        .value_kind:     by_value
      - .offset:         264
        .size:           4
        .value_kind:     hidden_block_count_x
      - .offset:         268
        .size:           4
        .value_kind:     hidden_block_count_y
      - .offset:         272
        .size:           4
        .value_kind:     hidden_block_count_z
      - .offset:         276
        .size:           2
        .value_kind:     hidden_group_size_x
      - .offset:         278
        .size:           2
        .value_kind:     hidden_group_size_y
      - .offset:         280
        .size:           2
        .value_kind:     hidden_group_size_z
      - .offset:         282
        .size:           2
        .value_kind:     hidden_remainder_x
      - .offset:         284
        .size:           2
        .value_kind:     hidden_remainder_y
      - .offset:         286
        .size:           2
        .value_kind:     hidden_remainder_z
      - .offset:         304
        .size:           8
        .value_kind:     hidden_global_offset_x
      - .offset:         312
        .size:           8
        .value_kind:     hidden_global_offset_y
      - .offset:         320
        .size:           8
        .value_kind:     hidden_global_offset_z
      - .offset:         328
        .size:           2
        .value_kind:     hidden_grid_dims
      - .offset:         352
        .size:           8
        .value_kind:     hidden_multigrid_sync_arg
      - .offset:         384
        .size:           4
        .value_kind:     hidden_dynamic_lds_size
    .group_segment_fixed_size: 0
    .kernarg_segment_align: 8
    .kernarg_segment_size: 520
    .language:       OpenCL C
    .language_version:
      - 2
      - 0
    .max_flat_workgroup_size: 512
    .name:           _Z13mla_hgrn2_fwd6Params
    .private_segment_fixed_size: 0
    .sgpr_count:     104
    .sgpr_spill_count: 10
    .symbol:         _Z13mla_hgrn2_fwd6Params.kd
    .uniform_work_group_size: 1
    .uses_dynamic_stack: false
    .vgpr_count:     254
    .vgpr_spill_count: 0
    .wavefront_size: 64
